# GEMM MMA segments: removed the redundant s_waitcnt lgkmcnt(0) after the barrier (LDS reads were already drained before it)
# speedup vs baseline: 1.0046x; 1.0006x over previous
; #define PG8_STAGE(bufoff, gbase, voff) do { _Pragma("unroll") for (int _i = 0; _i < 2; ++_i) \
;         __builtin_amdgcn_global_load_lds((const unsigned*)((const char*)(gbase) + (voff)[_i]), (PG8_LAS unsigned*)(lds + (bufoff) + ldsw + _i * 8192), 16, 0, 0); } while (0)
; #define PG8_LDA(dst, b, h) do { _Pragma("unroll") for (int m = 0; m < 4; ++m) _Pragma("unroll") for (int k = 0; k < 2; ++k) dst[m][k] = *(const PG8_LAS bf16x8*)(lds + PG8_SA(b, h) + aoff + m * 2048 + k * 1024); } while (0)
; #define PG8_LDB(dst, b, h) do { _Pragma("unroll") for (int n = 0; n < 2; ++n) _Pragma("unroll") for (int k = 0; k < 2; ++k) dst[n][k] = *(const PG8_LAS bf16x8*)(lds + PG8_SB(b, h) + boff + n * 2048 + k * 1024); } while (0)
; #define PG8_WAIT_V(n) asm volatile("s_waitcnt vmcnt(" #n ")" ::: "memory")
; #define PG8_WAIT_L(n) asm volatile("s_waitcnt lgkmcnt(" #n ")" ::: "memory")
; #define PG8_BAR __builtin_amdgcn_s_barrier()
; #define PG8_SCHED __builtin_amdgcn_sched_barrier(0)
; template <class Epi, bool ALIGN_EPI = true>
; __device__ __forceinline__ void gemm_phase(PG8_LAS unsigned char* lds, const Gemm g, const StaticOrder& S, const Epi& E) {
;     ...
;         for (int t = 0; t < nt; t += 2) {
;             const bool last = (t == nt - 2);
;             const char* a1 = cA + (size_t)(t + 1) * kstep;
;             const char* a2 = last ? nA : cA + (size_t)(t + 2) * kstep; const char* b2 = last ? nB : cB + (size_t)(t + 2) * kstep;
;             const char* a3 = a2 + kstep; const char* b3 = b2 + kstep;
;             PG8_LDB(B0, 0, 0); PG8_LDB(B1, 0, 1); PG8_SCHED; PG8_LDA(At, 0, 0); PG8_STAGE(PG8_SA(1, 1), a1 + hstepA, voffA);
;             PG8_WAIT_V(8); PG8_WAIT_L(0); PG8_BAR; PG8_MMA(0, 0, At, B0); PG8_MMA(0, 1, At, B1); PG8_BAR; PG8_SCHED;
;             PG8_LDA(At, 0, 1); PG8_STAGE(PG8_SB(0, 0), b2, voffB); PG8_STAGE(PG8_SB(0, 1), b2 + hstepB, voffB); PG8_STAGE(PG8_SA(0, 0), a2, voffA);
;             PG8_WAIT_V(8); PG8_WAIT_L(0); PG8_BAR; PG8_MMA(1, 0, At, B0); PG8_MMA(1, 1, At, B1); PG8_BAR; PG8_SCHED;
.LBB0_439:
	s_add_u32 s28, s8, 0xfffc0080
	s_addc_u32 s29, s9, -1
	s_add_i32 s53, 0, 0x10000
	s_cmp_eq_u32 s52, 12
	s_cselect_b32 s31, s3, s29
	s_cselect_b32 s30, s7, s28
	v_add_u32_e32 v32, s53, v164
	s_cselect_b32 s29, s21, s51
	s_cselect_b32 s28, s23, s50
	s_add_i32 s56, 0, 0x14000
	ds_read_b128 v[142:145], v32
	ds_read_b128 v[148:151], v32 offset:1024
	ds_read_b128 v[158:161], v32 offset:2048
	ds_read_b128 v[168:171], v32 offset:3072
	v_add_u32_e32 v32, s56, v164
	ds_read_b128 v[172:175], v32
	ds_read_b128 v[176:179], v32 offset:1024
	ds_read_b128 v[180:183], v32 offset:2048
	ds_read_b128 v[184:187], v32 offset:3072
	v_lshl_add_u64 v[146:147], s[8:9], 0, v[138:139]
	s_add_i32 m0, s41, 0xc000
	ds_read_b128 v[188:191], v166
	ds_read_b128 v[192:195], v166 offset:1024
	ds_read_b128 v[196:199], v166 offset:2048
	ds_read_b128 v[208:211], v166 offset:3072
	ds_read_b128 v[216:219], v166 offset:4096
	ds_read_b128 v[220:223], v166 offset:5120
	ds_read_b128 v[224:227], v166 offset:6144
	ds_read_b128 v[228:231], v166 offset:7168
	global_load_lds_dwordx4 v[146:147], off
	v_lshl_add_u64 v[146:147], s[8:9], 0, v[140:141]
	s_add_i32 m0, s41, 0xe000
	s_nop 0
	global_load_lds_dwordx4 v[146:147], off
	s_waitcnt vmcnt(8)
	s_waitcnt lgkmcnt(0)
	s_barrier
	s_setprio 1
	v_mfma_f32_16x16x32_bf16 v[126:129], v[142:145], v[188:191], 0
	v_mfma_f32_16x16x32_bf16 v[122:125], v[158:161], v[188:191], 0
	v_mfma_f32_16x16x32_bf16 v[110:113], v[142:145], v[196:199], 0
	v_mfma_f32_16x16x32_bf16 v[106:109], v[158:161], v[196:199], 0
	v_mfma_f32_16x16x32_bf16 v[94:97], v[142:145], v[216:219], 0
	v_mfma_f32_16x16x32_bf16 v[90:93], v[158:161], v[216:219], 0
	v_mfma_f32_16x16x32_bf16 v[78:81], v[142:145], v[224:227], 0
	v_mfma_f32_16x16x32_bf16 v[74:77], v[158:161], v[224:227], 0
	v_mfma_f32_16x16x32_bf16 v[126:129], v[148:151], v[192:195], v[126:129]
	v_mfma_f32_16x16x32_bf16 v[122:125], v[168:171], v[192:195], v[122:125]
	v_mfma_f32_16x16x32_bf16 v[110:113], v[148:151], v[208:211], v[110:113]
	v_mfma_f32_16x16x32_bf16 v[106:109], v[168:171], v[208:211], v[106:109]
	v_mfma_f32_16x16x32_bf16 v[94:97], v[148:151], v[220:223], v[94:97]
	v_mfma_f32_16x16x32_bf16 v[90:93], v[168:171], v[220:223], v[90:93]
	v_mfma_f32_16x16x32_bf16 v[78:81], v[148:151], v[228:231], v[78:81]
	v_mfma_f32_16x16x32_bf16 v[74:77], v[168:171], v[228:231], v[74:77]
	v_mfma_f32_16x16x32_bf16 v[118:121], v[172:175], v[188:191], 0
	v_mfma_f32_16x16x32_bf16 v[114:117], v[180:183], v[188:191], 0
	v_mfma_f32_16x16x32_bf16 v[102:105], v[172:175], v[196:199], 0
	v_mfma_f32_16x16x32_bf16 v[98:101], v[180:183], v[196:199], 0
	v_mfma_f32_16x16x32_bf16 v[86:89], v[172:175], v[216:219], 0
	v_mfma_f32_16x16x32_bf16 v[82:85], v[180:183], v[216:219], 0
	v_mfma_f32_16x16x32_bf16 v[70:73], v[172:175], v[224:227], 0
	v_mfma_f32_16x16x32_bf16 v[66:69], v[180:183], v[224:227], 0
	v_mfma_f32_16x16x32_bf16 v[118:121], v[176:179], v[192:195], v[118:121]
	v_mfma_f32_16x16x32_bf16 v[114:117], v[184:187], v[192:195], v[114:117]
	v_mfma_f32_16x16x32_bf16 v[102:105], v[176:179], v[208:211], v[102:105]
	v_mfma_f32_16x16x32_bf16 v[98:101], v[184:187], v[208:211], v[98:101]
	v_mfma_f32_16x16x32_bf16 v[86:89], v[176:179], v[220:223], v[86:89]
	v_mfma_f32_16x16x32_bf16 v[82:85], v[184:187], v[220:223], v[82:85]
	v_mfma_f32_16x16x32_bf16 v[70:73], v[176:179], v[228:231], v[70:73]
	v_mfma_f32_16x16x32_bf16 v[66:69], v[184:187], v[228:231], v[66:69]
	s_setprio 0
	s_barrier
	s_add_i32 s53, s53, s40
	v_lshl_add_u64 v[146:147], s[28:29], 0, v[132:133]
	s_mov_b32 m0, s53
	ds_read_b128 v[188:191], v166 offset:16384
	ds_read_b128 v[192:195], v166 offset:17408
	ds_read_b128 v[196:199], v166 offset:18432
	ds_read_b128 v[208:211], v166 offset:19456
	ds_read_b128 v[216:219], v166 offset:20480
	ds_read_b128 v[220:223], v166 offset:21504
	ds_read_b128 v[224:227], v166 offset:22528
	ds_read_b128 v[228:231], v166 offset:23552
	global_load_lds_dwordx4 v[146:147], off
	s_add_i32 m0, s53, 0x2000
	s_add_u32 s58, s28, 0x40000
	v_lshl_add_u64 v[200:201], s[28:29], 0, v[136:137]
	s_addc_u32 s59, s29, 0
	s_add_i32 s53, s56, s40
	global_load_lds_dwordx4 v[200:201], off
	v_lshl_add_u64 v[204:205], s[58:59], 0, v[132:133]
	s_mov_b32 m0, s53
	v_lshl_add_u64 v[206:207], s[30:31], 0, v[134:135]
	global_load_lds_dwordx4 v[204:205], off
	v_lshl_add_u64 v[204:205], s[58:59], 0, v[136:137]
	s_add_i32 m0, s53, 0x2000
	s_nop 0
	global_load_lds_dwordx4 v[204:205], off
	v_lshl_add_u64 v[204:205], s[30:31], 0, v[130:131]
	s_mov_b32 m0, s41
	s_nop 0
	global_load_lds_dwordx4 v[204:205], off
	s_mov_b32 m0, s42
	s_nop 0
	global_load_lds_dwordx4 v[206:207], off
	s_waitcnt vmcnt(8)
	s_waitcnt lgkmcnt(0)
	s_barrier
	s_setprio 1
	v_mfma_f32_16x16x32_bf16 v[62:65], v[142:145], v[188:191], 0
	v_mfma_f32_16x16x32_bf16 v[58:61], v[158:161], v[188:191], 0
	v_mfma_f32_16x16x32_bf16 v[46:49], v[142:145], v[196:199], 0
	v_mfma_f32_16x16x32_bf16 v[42:45], v[158:161], v[196:199], 0
	v_mfma_f32_16x16x32_bf16 v[28:31], v[142:145], v[216:219], 0
	v_mfma_f32_16x16x32_bf16 v[24:27], v[158:161], v[216:219], 0
	v_mfma_f32_16x16x32_bf16 v[12:15], v[142:145], v[224:227], 0
	v_mfma_f32_16x16x32_bf16 v[8:11], v[158:161], v[224:227], 0
	v_mfma_f32_16x16x32_bf16 v[62:65], v[148:151], v[192:195], v[62:65]
	v_mfma_f32_16x16x32_bf16 v[58:61], v[168:171], v[192:195], v[58:61]
	v_mfma_f32_16x16x32_bf16 v[46:49], v[148:151], v[208:211], v[46:49]
	v_mfma_f32_16x16x32_bf16 v[42:45], v[168:171], v[208:211], v[42:45]
	v_mfma_f32_16x16x32_bf16 v[28:31], v[148:151], v[220:223], v[28:31]
	v_mfma_f32_16x16x32_bf16 v[24:27], v[168:171], v[220:223], v[24:27]
	v_mfma_f32_16x16x32_bf16 v[12:15], v[148:151], v[228:231], v[12:15]
	v_mfma_f32_16x16x32_bf16 v[8:11], v[168:171], v[228:231], v[8:11]
	v_mfma_f32_16x16x32_bf16 v[54:57], v[172:175], v[188:191], 0
	v_mfma_f32_16x16x32_bf16 v[50:53], v[180:183], v[188:191], 0
	v_mfma_f32_16x16x32_bf16 v[38:41], v[172:175], v[196:199], 0
	v_mfma_f32_16x16x32_bf16 v[34:37], v[180:183], v[196:199], 0
	v_mfma_f32_16x16x32_bf16 v[20:23], v[172:175], v[216:219], 0
	v_mfma_f32_16x16x32_bf16 v[16:19], v[180:183], v[216:219], 0
	v_mfma_f32_16x16x32_bf16 v[4:7], v[172:175], v[224:227], 0
	v_mfma_f32_16x16x32_bf16 v[0:3], v[180:183], v[224:227], 0
	v_mfma_f32_16x16x32_bf16 v[54:57], v[176:179], v[192:195], v[54:57]
	v_mfma_f32_16x16x32_bf16 v[50:53], v[184:187], v[192:195], v[50:53]
	v_mfma_f32_16x16x32_bf16 v[38:41], v[176:179], v[208:211], v[38:41]
	v_mfma_f32_16x16x32_bf16 v[34:37], v[184:187], v[208:211], v[34:37]
	v_mfma_f32_16x16x32_bf16 v[20:23], v[176:179], v[220:223], v[20:23]
	v_mfma_f32_16x16x32_bf16 v[16:19], v[184:187], v[220:223], v[16:19]
	v_mfma_f32_16x16x32_bf16 v[4:7], v[176:179], v[228:231], v[4:7]
	v_mfma_f32_16x16x32_bf16 v[0:3], v[184:187], v[228:231], v[0:3]
	s_setprio 0
	s_barrier
	s_branch .Lp3_439
; #define PG8_STAGE(bufoff, gbase, voff) do { _Pragma("unroll") for (int _i = 0; _i < 2; ++_i) \
;         __builtin_amdgcn_global_load_lds((const unsigned*)((const char*)(gbase) + (voff)[_i]), (PG8_LAS unsigned*)(lds + (bufoff) + ldsw + _i * 8192), 16, 0, 0); } while (0)
; #define PG8_LDA(dst, b, h) do { _Pragma("unroll") for (int m = 0; m < 4; ++m) _Pragma("unroll") for (int k = 0; k < 2; ++k) dst[m][k] = *(const PG8_LAS bf16x8*)(lds + PG8_SA(b, h) + aoff + m * 2048 + k * 1024); } while (0)
; #define PG8_LDB(dst, b, h) do { _Pragma("unroll") for (int n = 0; n < 2; ++n) _Pragma("unroll") for (int k = 0; k < 2; ++k) dst[n][k] = *(const PG8_LAS bf16x8*)(lds + PG8_SB(b, h) + boff + n * 2048 + k * 1024); } while (0)
; #define PG8_WAIT_V(n) asm volatile("s_waitcnt vmcnt(" #n ")" ::: "memory")
; #define PG8_WAIT_L(n) asm volatile("s_waitcnt lgkmcnt(" #n ")" ::: "memory")
; #define PG8_BAR __builtin_amdgcn_s_barrier()
; #define PG8_SCHED __builtin_amdgcn_sched_barrier(0)
; template <class Epi, bool ALIGN_EPI = true>
; __device__ __forceinline__ void gemm_phase(PG8_LAS unsigned char* lds, const Gemm g, const StaticOrder& S, const Epi& E) {
;     ...
;         for (int t = 0; t < nt; t += 2) {
;             const bool last = (t == nt - 2);
;             const char* a1 = cA + (size_t)(t + 1) * kstep;
;             const char* a2 = last ? nA : cA + (size_t)(t + 2) * kstep; const char* b2 = last ? nB : cB + (size_t)(t + 2) * kstep;
;             const char* a3 = a2 + kstep; const char* b3 = b2 + kstep;
;             PG8_LDB(B0, 0, 0); PG8_LDB(B1, 0, 1); PG8_SCHED; PG8_LDA(At, 0, 0); PG8_STAGE(PG8_SA(1, 1), a1 + hstepA, voffA);
;             PG8_WAIT_V(8); PG8_WAIT_L(0); PG8_BAR; PG8_MMA(0, 0, At, B0); PG8_MMA(0, 1, At, B1); PG8_BAR; PG8_SCHED;
;             PG8_LDA(At, 0, 1); PG8_STAGE(PG8_SB(0, 0), b2, voffB); PG8_STAGE(PG8_SB(0, 1), b2 + hstepB, voffB); PG8_STAGE(PG8_SA(0, 0), a2, voffA);
;             PG8_WAIT_V(8); PG8_WAIT_L(0); PG8_BAR; PG8_MMA(1, 0, At, B0); PG8_MMA(1, 1, At, B1); PG8_BAR; PG8_SCHED;
.Lrot_439:
	ds_read_b128 v[142:145], v32
	ds_read_b128 v[148:151], v32 offset:1024
	ds_read_b128 v[158:161], v32 offset:2048
	ds_read_b128 v[168:171], v32 offset:3072
	v_add_u32_e32 v32, s56, v164
	ds_read_b128 v[172:175], v32
	ds_read_b128 v[176:179], v32 offset:1024
	ds_read_b128 v[180:183], v32 offset:2048
	ds_read_b128 v[184:187], v32 offset:3072
	v_lshl_add_u64 v[146:147], s[8:9], 0, v[138:139]
	s_add_i32 m0, s41, 0xc000
	ds_read_b128 v[188:191], v166
	ds_read_b128 v[192:195], v166 offset:1024
	ds_read_b128 v[196:199], v166 offset:2048
	ds_read_b128 v[208:211], v166 offset:3072
	ds_read_b128 v[216:219], v166 offset:4096
	ds_read_b128 v[220:223], v166 offset:5120
	ds_read_b128 v[224:227], v166 offset:6144
	ds_read_b128 v[228:231], v166 offset:7168
	global_load_lds_dwordx4 v[146:147], off
	v_lshl_add_u64 v[146:147], s[8:9], 0, v[140:141]
	s_add_i32 m0, s41, 0xe000
	s_nop 0
	global_load_lds_dwordx4 v[146:147], off
	s_waitcnt vmcnt(8)
	s_waitcnt lgkmcnt(0)
	s_barrier
	s_setprio 1
	v_mfma_f32_16x16x32_bf16 v[126:129], v[142:145], v[188:191], v[126:129]
	v_mfma_f32_16x16x32_bf16 v[122:125], v[158:161], v[188:191], v[122:125]
	v_mfma_f32_16x16x32_bf16 v[110:113], v[142:145], v[196:199], v[110:113]
	v_mfma_f32_16x16x32_bf16 v[106:109], v[158:161], v[196:199], v[106:109]
	v_mfma_f32_16x16x32_bf16 v[94:97], v[142:145], v[216:219], v[94:97]
	v_mfma_f32_16x16x32_bf16 v[90:93], v[158:161], v[216:219], v[90:93]
	v_mfma_f32_16x16x32_bf16 v[78:81], v[142:145], v[224:227], v[78:81]
	v_mfma_f32_16x16x32_bf16 v[74:77], v[158:161], v[224:227], v[74:77]
	v_mfma_f32_16x16x32_bf16 v[126:129], v[148:151], v[192:195], v[126:129]
	v_mfma_f32_16x16x32_bf16 v[122:125], v[168:171], v[192:195], v[122:125]
	v_mfma_f32_16x16x32_bf16 v[110:113], v[148:151], v[208:211], v[110:113]
	v_mfma_f32_16x16x32_bf16 v[106:109], v[168:171], v[208:211], v[106:109]
	v_mfma_f32_16x16x32_bf16 v[94:97], v[148:151], v[220:223], v[94:97]
	v_mfma_f32_16x16x32_bf16 v[90:93], v[168:171], v[220:223], v[90:93]
	v_mfma_f32_16x16x32_bf16 v[78:81], v[148:151], v[228:231], v[78:81]
	v_mfma_f32_16x16x32_bf16 v[74:77], v[168:171], v[228:231], v[74:77]
	v_mfma_f32_16x16x32_bf16 v[118:121], v[172:175], v[188:191], v[118:121]
	v_mfma_f32_16x16x32_bf16 v[114:117], v[180:183], v[188:191], v[114:117]
	v_mfma_f32_16x16x32_bf16 v[102:105], v[172:175], v[196:199], v[102:105]
	v_mfma_f32_16x16x32_bf16 v[98:101], v[180:183], v[196:199], v[98:101]
	v_mfma_f32_16x16x32_bf16 v[86:89], v[172:175], v[216:219], v[86:89]
	v_mfma_f32_16x16x32_bf16 v[82:85], v[180:183], v[216:219], v[82:85]
	v_mfma_f32_16x16x32_bf16 v[70:73], v[172:175], v[224:227], v[70:73]
	v_mfma_f32_16x16x32_bf16 v[66:69], v[180:183], v[224:227], v[66:69]
	v_mfma_f32_16x16x32_bf16 v[118:121], v[176:179], v[192:195], v[118:121]
	v_mfma_f32_16x16x32_bf16 v[114:117], v[184:187], v[192:195], v[114:117]
	v_mfma_f32_16x16x32_bf16 v[102:105], v[176:179], v[208:211], v[102:105]
	v_mfma_f32_16x16x32_bf16 v[98:101], v[184:187], v[208:211], v[98:101]
	v_mfma_f32_16x16x32_bf16 v[86:89], v[176:179], v[220:223], v[86:89]
	v_mfma_f32_16x16x32_bf16 v[82:85], v[184:187], v[220:223], v[82:85]
	v_mfma_f32_16x16x32_bf16 v[70:73], v[176:179], v[228:231], v[70:73]
	v_mfma_f32_16x16x32_bf16 v[66:69], v[184:187], v[228:231], v[66:69]
	s_setprio 0
	s_barrier
	s_add_i32 s53, s53, s40
	v_lshl_add_u64 v[146:147], s[28:29], 0, v[132:133]
	s_mov_b32 m0, s53
	ds_read_b128 v[188:191], v166 offset:16384
	ds_read_b128 v[192:195], v166 offset:17408
	ds_read_b128 v[196:199], v166 offset:18432
	ds_read_b128 v[208:211], v166 offset:19456
	ds_read_b128 v[216:219], v166 offset:20480
	ds_read_b128 v[220:223], v166 offset:21504
	ds_read_b128 v[224:227], v166 offset:22528
	ds_read_b128 v[228:231], v166 offset:23552
	global_load_lds_dwordx4 v[146:147], off
	s_add_i32 m0, s53, 0x2000
	s_add_u32 s58, s28, 0x40000
	v_lshl_add_u64 v[200:201], s[28:29], 0, v[136:137]
	s_addc_u32 s59, s29, 0
	s_add_i32 s53, s56, s40
	global_load_lds_dwordx4 v[200:201], off
	v_lshl_add_u64 v[204:205], s[58:59], 0, v[132:133]
	s_mov_b32 m0, s53
	v_lshl_add_u64 v[206:207], s[30:31], 0, v[134:135]
	global_load_lds_dwordx4 v[204:205], off
	v_lshl_add_u64 v[204:205], s[58:59], 0, v[136:137]
	s_add_i32 m0, s53, 0x2000
	s_nop 0
	global_load_lds_dwordx4 v[204:205], off
	v_lshl_add_u64 v[204:205], s[30:31], 0, v[130:131]
	s_mov_b32 m0, s41
	s_nop 0
	global_load_lds_dwordx4 v[204:205], off
	s_mov_b32 m0, s42
	s_nop 0
	global_load_lds_dwordx4 v[206:207], off
	s_waitcnt vmcnt(8)
	s_waitcnt lgkmcnt(0)
	s_barrier
	s_setprio 1
	v_mfma_f32_16x16x32_bf16 v[62:65], v[142:145], v[188:191], v[62:65]
	v_mfma_f32_16x16x32_bf16 v[58:61], v[158:161], v[188:191], v[58:61]
	v_mfma_f32_16x16x32_bf16 v[46:49], v[142:145], v[196:199], v[46:49]
	v_mfma_f32_16x16x32_bf16 v[42:45], v[158:161], v[196:199], v[42:45]
	v_mfma_f32_16x16x32_bf16 v[28:31], v[142:145], v[216:219], v[28:31]
	v_mfma_f32_16x16x32_bf16 v[24:27], v[158:161], v[216:219], v[24:27]
	v_mfma_f32_16x16x32_bf16 v[12:15], v[142:145], v[224:227], v[12:15]
	v_mfma_f32_16x16x32_bf16 v[8:11], v[158:161], v[224:227], v[8:11]
	v_mfma_f32_16x16x32_bf16 v[62:65], v[148:151], v[192:195], v[62:65]
	v_mfma_f32_16x16x32_bf16 v[58:61], v[168:171], v[192:195], v[58:61]
	v_mfma_f32_16x16x32_bf16 v[46:49], v[148:151], v[208:211], v[46:49]
	v_mfma_f32_16x16x32_bf16 v[42:45], v[168:171], v[208:211], v[42:45]
	v_mfma_f32_16x16x32_bf16 v[28:31], v[148:151], v[220:223], v[28:31]
	v_mfma_f32_16x16x32_bf16 v[24:27], v[168:171], v[220:223], v[24:27]
	v_mfma_f32_16x16x32_bf16 v[12:15], v[148:151], v[228:231], v[12:15]
	v_mfma_f32_16x16x32_bf16 v[8:11], v[168:171], v[228:231], v[8:11]
	v_mfma_f32_16x16x32_bf16 v[54:57], v[172:175], v[188:191], v[54:57]
	v_mfma_f32_16x16x32_bf16 v[50:53], v[180:183], v[188:191], v[50:53]
	v_mfma_f32_16x16x32_bf16 v[38:41], v[172:175], v[196:199], v[38:41]
	v_mfma_f32_16x16x32_bf16 v[34:37], v[180:183], v[196:199], v[34:37]
	v_mfma_f32_16x16x32_bf16 v[20:23], v[172:175], v[216:219], v[20:23]
	v_mfma_f32_16x16x32_bf16 v[16:19], v[180:183], v[216:219], v[16:19]
	v_mfma_f32_16x16x32_bf16 v[4:7], v[172:175], v[224:227], v[4:7]
	v_mfma_f32_16x16x32_bf16 v[0:3], v[180:183], v[224:227], v[0:3]
	v_mfma_f32_16x16x32_bf16 v[54:57], v[176:179], v[192:195], v[54:57]
	v_mfma_f32_16x16x32_bf16 v[50:53], v[184:187], v[192:195], v[50:53]
	v_mfma_f32_16x16x32_bf16 v[38:41], v[176:179], v[208:211], v[38:41]
	v_mfma_f32_16x16x32_bf16 v[34:37], v[184:187], v[208:211], v[34:37]
	v_mfma_f32_16x16x32_bf16 v[20:23], v[176:179], v[220:223], v[20:23]
	v_mfma_f32_16x16x32_bf16 v[16:19], v[184:187], v[220:223], v[16:19]
	v_mfma_f32_16x16x32_bf16 v[4:7], v[176:179], v[228:231], v[4:7]
	v_mfma_f32_16x16x32_bf16 v[0:3], v[184:187], v[228:231], v[0:3]
	s_setprio 0
	s_barrier
; #define PG8_STAGE(bufoff, gbase, voff) do { _Pragma("unroll") for (int _i = 0; _i < 2; ++_i) \
;         __builtin_amdgcn_global_load_lds((const unsigned*)((const char*)(gbase) + (voff)[_i]), (PG8_LAS unsigned*)(lds + (bufoff) + ldsw + _i * 8192), 16, 0, 0); } while (0)
; #define PG8_LDA(dst, b, h) do { _Pragma("unroll") for (int m = 0; m < 4; ++m) _Pragma("unroll") for (int k = 0; k < 2; ++k) dst[m][k] = *(const PG8_LAS bf16x8*)(lds + PG8_SA(b, h) + aoff + m * 2048 + k * 1024); } while (0)
; #define PG8_LDB(dst, b, h) do { _Pragma("unroll") for (int n = 0; n < 2; ++n) _Pragma("unroll") for (int k = 0; k < 2; ++k) dst[n][k] = *(const PG8_LAS bf16x8*)(lds + PG8_SB(b, h) + boff + n * 2048 + k * 1024); } while (0)
; #define PG8_WAIT_V(n) asm volatile("s_waitcnt vmcnt(" #n ")" ::: "memory")
; #define PG8_WAIT_L(n) asm volatile("s_waitcnt lgkmcnt(" #n ")" ::: "memory")
; #define PG8_BAR __builtin_amdgcn_s_barrier()
; #define PG8_SCHED __builtin_amdgcn_sched_barrier(0)
; template <class Epi, bool ALIGN_EPI = true>
; __device__ __forceinline__ void gemm_phase(PG8_LAS unsigned char* lds, const Gemm g, const StaticOrder& S, const Epi& E) {
;     ...
;             PG8_LDB(B0, 1, 0); PG8_LDB(B1, 1, 1); PG8_SCHED; PG8_LDA(At, 1, 0); PG8_STAGE(PG8_SA(0, 1), a2 + hstepA, voffA);
;             PG8_WAIT_V(8); PG8_WAIT_L(0); PG8_BAR; PG8_MMA(0, 0, At, B0); PG8_MMA(0, 1, At, B1); PG8_BAR; PG8_SCHED;
.Lp3_439:
	s_add_i32 s53, 0, 0x18000
	v_add_u32_e32 v32, s53, v164
	s_add_i32 s56, 0, 0x1c000
	ds_read_b128 v[142:145], v32
	ds_read_b128 v[148:151], v32 offset:1024
	ds_read_b128 v[158:161], v32 offset:2048
	ds_read_b128 v[168:171], v32 offset:3072
	v_add_u32_e32 v32, s56, v164
	ds_read_b128 v[172:175], v32
	ds_read_b128 v[176:179], v32 offset:1024
	ds_read_b128 v[180:183], v32 offset:2048
	ds_read_b128 v[184:187], v32 offset:3072
	s_add_u32 s30, s30, 0x40000
	s_addc_u32 s31, s31, 0
	s_mov_b32 m0, s43
	v_lshl_add_u64 v[232:233], s[30:31], 0, v[130:131]
	ds_read_b128 v[188:191], v166 offset:32768
	ds_read_b128 v[192:195], v166 offset:33792
	ds_read_b128 v[196:199], v166 offset:34816
	ds_read_b128 v[208:211], v166 offset:35840
	ds_read_b128 v[216:219], v166 offset:36864
	ds_read_b128 v[220:223], v166 offset:37888
	ds_read_b128 v[224:227], v166 offset:38912
	ds_read_b128 v[228:231], v166 offset:39936
	global_load_lds_dwordx4 v[232:233], off
	v_lshl_add_u64 v[232:233], s[30:31], 0, v[134:135]
	s_mov_b32 m0, s44
	s_nop 0
	global_load_lds_dwordx4 v[232:233], off
	s_waitcnt vmcnt(8)
	s_waitcnt lgkmcnt(0)
	s_barrier
	s_setprio 1
	v_mfma_f32_16x16x32_bf16 v[126:129], v[142:145], v[188:191], v[126:129]
	v_mfma_f32_16x16x32_bf16 v[122:125], v[158:161], v[188:191], v[122:125]
	v_mfma_f32_16x16x32_bf16 v[110:113], v[142:145], v[196:199], v[110:113]
	v_mfma_f32_16x16x32_bf16 v[106:109], v[158:161], v[196:199], v[106:109]
	v_mfma_f32_16x16x32_bf16 v[94:97], v[142:145], v[216:219], v[94:97]
	v_mfma_f32_16x16x32_bf16 v[90:93], v[158:161], v[216:219], v[90:93]
	v_mfma_f32_16x16x32_bf16 v[78:81], v[142:145], v[224:227], v[78:81]
	v_mfma_f32_16x16x32_bf16 v[74:77], v[158:161], v[224:227], v[74:77]
	v_mfma_f32_16x16x32_bf16 v[126:129], v[148:151], v[192:195], v[126:129]
	v_mfma_f32_16x16x32_bf16 v[122:125], v[168:171], v[192:195], v[122:125]
	v_mfma_f32_16x16x32_bf16 v[110:113], v[148:151], v[208:211], v[110:113]
	v_mfma_f32_16x16x32_bf16 v[106:109], v[168:171], v[208:211], v[106:109]
	v_mfma_f32_16x16x32_bf16 v[94:97], v[148:151], v[220:223], v[94:97]
	v_mfma_f32_16x16x32_bf16 v[90:93], v[168:171], v[220:223], v[90:93]
	v_mfma_f32_16x16x32_bf16 v[78:81], v[148:151], v[228:231], v[78:81]
	v_mfma_f32_16x16x32_bf16 v[74:77], v[168:171], v[228:231], v[74:77]
	v_mfma_f32_16x16x32_bf16 v[118:121], v[172:175], v[188:191], v[118:121]
	v_mfma_f32_16x16x32_bf16 v[114:117], v[180:183], v[188:191], v[114:117]
	v_mfma_f32_16x16x32_bf16 v[102:105], v[172:175], v[196:199], v[102:105]
	v_mfma_f32_16x16x32_bf16 v[98:101], v[180:183], v[196:199], v[98:101]
	v_mfma_f32_16x16x32_bf16 v[86:89], v[172:175], v[216:219], v[86:89]
	v_mfma_f32_16x16x32_bf16 v[82:85], v[180:183], v[216:219], v[82:85]
	v_mfma_f32_16x16x32_bf16 v[70:73], v[172:175], v[224:227], v[70:73]
	v_mfma_f32_16x16x32_bf16 v[66:69], v[180:183], v[224:227], v[66:69]
	v_mfma_f32_16x16x32_bf16 v[118:121], v[176:179], v[192:195], v[118:121]
	v_mfma_f32_16x16x32_bf16 v[114:117], v[184:187], v[192:195], v[114:117]
	v_mfma_f32_16x16x32_bf16 v[102:105], v[176:179], v[208:211], v[102:105]
	v_mfma_f32_16x16x32_bf16 v[98:101], v[184:187], v[208:211], v[98:101]
	v_mfma_f32_16x16x32_bf16 v[86:89], v[176:179], v[220:223], v[86:89]
	v_mfma_f32_16x16x32_bf16 v[82:85], v[184:187], v[220:223], v[82:85]
	v_mfma_f32_16x16x32_bf16 v[70:73], v[176:179], v[228:231], v[70:73]
	v_mfma_f32_16x16x32_bf16 v[66:69], v[184:187], v[228:231], v[66:69]
	s_setprio 0
	s_barrier
; #define PG8_STAGE(bufoff, gbase, voff) do { _Pragma("unroll") for (int _i = 0; _i < 2; ++_i) \
;         __builtin_amdgcn_global_load_lds((const unsigned*)((const char*)(gbase) + (voff)[_i]), (PG8_LAS unsigned*)(lds + (bufoff) + ldsw + _i * 8192), 16, 0, 0); } while (0)
; #define PG8_LDA(dst, b, h) do { _Pragma("unroll") for (int m = 0; m < 4; ++m) _Pragma("unroll") for (int k = 0; k < 2; ++k) dst[m][k] = *(const PG8_LAS bf16x8*)(lds + PG8_SA(b, h) + aoff + m * 2048 + k * 1024); } while (0)
; #define PG8_WAIT_V(n) asm volatile("s_waitcnt vmcnt(" #n ")" ::: "memory")
; #define PG8_WAIT_L(n) asm volatile("s_waitcnt lgkmcnt(" #n ")" ::: "memory")
; #define PG8_BAR __builtin_amdgcn_s_barrier()
; #define PG8_SCHED __builtin_amdgcn_sched_barrier(0)
; template <class Epi, bool ALIGN_EPI = true>
; __device__ __forceinline__ void gemm_phase(PG8_LAS unsigned char* lds, const Gemm g, const StaticOrder& S, const Epi& E) {
;     ...
;         for (int t = 0; t < nt; t += 2) {
;             const bool last = (t == nt - 2);
;             const char* a1 = cA + (size_t)(t + 1) * kstep;
;             const char* a2 = last ? nA : cA + (size_t)(t + 2) * kstep; const char* b2 = last ? nB : cB + (size_t)(t + 2) * kstep;
;             const char* a3 = a2 + kstep; const char* b3 = b2 + kstep;
;     ...
;             PG8_LDA(At, 1, 1); PG8_STAGE(PG8_SB(1, 0), b3, voffB); PG8_STAGE(PG8_SB(1, 1), b3 + hstepB, voffB); PG8_STAGE(PG8_SA(1, 0), a3, voffA);
;             PG8_WAIT_V(8); PG8_WAIT_L(0); PG8_BAR; PG8_MMA(1, 0, At, B0); PG8_MMA(1, 1, At, B1); PG8_BAR; PG8_SCHED;
	s_add_i32 s30, s53, s40
	v_lshl_add_u64 v[146:147], v[146:147], 0, s[60:61]
	s_mov_b32 m0, s30
	ds_read_b128 v[188:191], v166 offset:49152
	ds_read_b128 v[192:195], v166 offset:50176
	ds_read_b128 v[196:199], v166 offset:51200
	ds_read_b128 v[208:211], v166 offset:52224
	ds_read_b128 v[216:219], v166 offset:53248
	ds_read_b128 v[220:223], v166 offset:54272
	ds_read_b128 v[224:227], v166 offset:55296
	ds_read_b128 v[228:231], v166 offset:56320
	global_load_lds_dwordx4 v[146:147], off
	s_add_i32 m0, s30, 0x2000
	s_add_u32 s28, s28, 0x40080
	v_lshl_add_u64 v[146:147], v[200:201], 0, s[60:61]
	s_addc_u32 s29, s29, 0
	s_add_i32 s30, s56, s40
	global_load_lds_dwordx4 v[146:147], off
	v_lshl_add_u64 v[146:147], s[28:29], 0, v[132:133]
	s_mov_b32 m0, s30
	s_nop 0
	global_load_lds_dwordx4 v[146:147], off
	v_lshl_add_u64 v[146:147], s[28:29], 0, v[136:137]
	s_add_i32 m0, s30, 0x2000
	s_nop 0
	global_load_lds_dwordx4 v[146:147], off
	v_lshl_add_u64 v[146:147], v[204:205], 0, s[60:61]
	s_mov_b32 m0, s45
	s_nop 0
	global_load_lds_dwordx4 v[146:147], off
	v_lshl_add_u64 v[146:147], v[206:207], 0, s[60:61]
	s_mov_b32 m0, s46
	s_nop 0
	global_load_lds_dwordx4 v[146:147], off
	s_add_i32 s52, s52, 2
	s_add_u32 s8, s8, 0x100
	s_addc_u32 s9, s9, 0
	s_add_u32 s50, s50, 0x100
	s_addc_u32 s51, s51, 0
	s_add_u32 s28, s8, 0xfffc0080
	s_addc_u32 s29, s9, -1
	s_add_i32 s53, 0, 0x10000
	s_cmp_eq_u32 s52, 12
	s_cselect_b32 s31, s3, s29
	s_cselect_b32 s30, s7, s28
	v_add_u32_e32 v32, s53, v164
	s_cselect_b32 s29, s21, s51
	s_cselect_b32 s28, s23, s50
	s_add_i32 s56, 0, 0x14000
	s_cmp_gt_u32 s52, 13
	s_waitcnt vmcnt(8)
	s_waitcnt lgkmcnt(0)
	s_barrier
	s_setprio 1
	v_mfma_f32_16x16x32_bf16 v[62:65], v[142:145], v[188:191], v[62:65]
	v_mfma_f32_16x16x32_bf16 v[58:61], v[158:161], v[188:191], v[58:61]
	v_mfma_f32_16x16x32_bf16 v[46:49], v[142:145], v[196:199], v[46:49]
	v_mfma_f32_16x16x32_bf16 v[42:45], v[158:161], v[196:199], v[42:45]
	v_mfma_f32_16x16x32_bf16 v[28:31], v[142:145], v[216:219], v[28:31]
	v_mfma_f32_16x16x32_bf16 v[24:27], v[158:161], v[216:219], v[24:27]
	v_mfma_f32_16x16x32_bf16 v[12:15], v[142:145], v[224:227], v[12:15]
	v_mfma_f32_16x16x32_bf16 v[8:11], v[158:161], v[224:227], v[8:11]
	v_mfma_f32_16x16x32_bf16 v[62:65], v[148:151], v[192:195], v[62:65]
	v_mfma_f32_16x16x32_bf16 v[58:61], v[168:171], v[192:195], v[58:61]
	v_mfma_f32_16x16x32_bf16 v[46:49], v[148:151], v[208:211], v[46:49]
	v_mfma_f32_16x16x32_bf16 v[42:45], v[168:171], v[208:211], v[42:45]
	v_mfma_f32_16x16x32_bf16 v[28:31], v[148:151], v[220:223], v[28:31]
	v_mfma_f32_16x16x32_bf16 v[24:27], v[168:171], v[220:223], v[24:27]
	v_mfma_f32_16x16x32_bf16 v[12:15], v[148:151], v[228:231], v[12:15]
	v_mfma_f32_16x16x32_bf16 v[8:11], v[168:171], v[228:231], v[8:11]
	v_mfma_f32_16x16x32_bf16 v[54:57], v[172:175], v[188:191], v[54:57]
	v_mfma_f32_16x16x32_bf16 v[50:53], v[180:183], v[188:191], v[50:53]
	v_mfma_f32_16x16x32_bf16 v[38:41], v[172:175], v[196:199], v[38:41]
	v_mfma_f32_16x16x32_bf16 v[34:37], v[180:183], v[196:199], v[34:37]
	v_mfma_f32_16x16x32_bf16 v[20:23], v[172:175], v[216:219], v[20:23]
	v_mfma_f32_16x16x32_bf16 v[16:19], v[180:183], v[216:219], v[16:19]
	v_mfma_f32_16x16x32_bf16 v[4:7], v[172:175], v[224:227], v[4:7]
	v_mfma_f32_16x16x32_bf16 v[0:3], v[180:183], v[224:227], v[0:3]
	v_mfma_f32_16x16x32_bf16 v[54:57], v[176:179], v[192:195], v[54:57]
	v_mfma_f32_16x16x32_bf16 v[50:53], v[184:187], v[192:195], v[50:53]
	v_mfma_f32_16x16x32_bf16 v[38:41], v[176:179], v[208:211], v[38:41]
	v_mfma_f32_16x16x32_bf16 v[34:37], v[184:187], v[208:211], v[34:37]
	v_mfma_f32_16x16x32_bf16 v[20:23], v[176:179], v[220:223], v[20:23]
	v_mfma_f32_16x16x32_bf16 v[16:19], v[184:187], v[220:223], v[16:19]
	v_mfma_f32_16x16x32_bf16 v[4:7], v[176:179], v[228:231], v[4:7]
	v_mfma_f32_16x16x32_bf16 v[0:3], v[184:187], v[228:231], v[0:3]
	s_setprio 0
	s_barrier
	s_cbranch_scc0 .Lrot_439
	s_and_b64 vcc, exec, s[18:19]
	s_cbranch_vccz .LBB0_442
	s_barrier

; #define PG8_STAGE(bufoff, gbase, voff) do { _Pragma("unroll") for (int _i = 0; _i < 2; ++_i) \
;         __builtin_amdgcn_global_load_lds((const unsigned*)((const char*)(gbase) + (voff)[_i]), (PG8_LAS unsigned*)(lds + (bufoff) + ldsw + _i * 8192), 16, 0, 0); } while (0)
; #define PG8_LDA(dst, b, h) do { _Pragma("unroll") for (int m = 0; m < 4; ++m) _Pragma("unroll") for (int k = 0; k < 2; ++k) dst[m][k] = *(const PG8_LAS bf16x8*)(lds + PG8_SA(b, h) + aoff + m * 2048 + k * 1024); } while (0)
; #define PG8_LDB(dst, b, h) do { _Pragma("unroll") for (int n = 0; n < 2; ++n) _Pragma("unroll") for (int k = 0; k < 2; ++k) dst[n][k] = *(const PG8_LAS bf16x8*)(lds + PG8_SB(b, h) + boff + n * 2048 + k * 1024); } while (0)
; #define PG8_WAIT_V(n) asm volatile("s_waitcnt vmcnt(" #n ")" ::: "memory")
; #define PG8_WAIT_L(n) asm volatile("s_waitcnt lgkmcnt(" #n ")" ::: "memory")
; #define PG8_BAR __builtin_amdgcn_s_barrier()
; #define PG8_SCHED __builtin_amdgcn_sched_barrier(0)
; template <class Epi, bool ALIGN_EPI = true>
; __device__ __forceinline__ void gemm_phase(PG8_LAS unsigned char* lds, const Gemm g, const StaticOrder& S, const Epi& E) {
;     ...
;         for (int t = 0; t < nt; t += 2) {
;             const bool last = (t == nt - 2);
;             const char* a1 = cA + (size_t)(t + 1) * kstep;
;             const char* a2 = last ? nA : cA + (size_t)(t + 2) * kstep; const char* b2 = last ? nB : cB + (size_t)(t + 2) * kstep;
;             const char* a3 = a2 + kstep; const char* b3 = b2 + kstep;
;             PG8_LDB(B0, 0, 0); PG8_LDB(B1, 0, 1); PG8_SCHED; PG8_LDA(At, 0, 0); PG8_STAGE(PG8_SA(1, 1), a1 + hstepA, voffA);
;             PG8_WAIT_V(8); PG8_WAIT_L(0); PG8_BAR; PG8_MMA(0, 0, At, B0); PG8_MMA(0, 1, At, B1); PG8_BAR; PG8_SCHED;
;             PG8_LDA(At, 0, 1); PG8_STAGE(PG8_SB(0, 0), b2, voffB); PG8_STAGE(PG8_SB(0, 1), b2 + hstepB, voffB); PG8_STAGE(PG8_SA(0, 0), a2, voffA);
;             PG8_WAIT_V(8); PG8_WAIT_L(0); PG8_BAR; PG8_MMA(1, 0, At, B0); PG8_MMA(1, 1, At, B1); PG8_BAR; PG8_SCHED;
.LBB0_795:
	s_add_u32 s43, s6, 0xfffc0080
	s_addc_u32 s44, s7, -1
	s_add_i32 s75, 0, 0x10000
	s_cmp_eq_u32 s37, 12
	s_cselect_b32 s47, s39, s44
	s_cselect_b32 s46, s38, s43
	v_add_u32_e32 v32, s75, v165
	s_cselect_b32 s45, s41, s35
	s_cselect_b32 s44, s40, s9
	s_add_i32 s43, 0, 0x14000
	ds_read_b128 v[142:145], v32
	ds_read_b128 v[148:151], v32 offset:1024
	ds_read_b128 v[158:161], v32 offset:2048
	ds_read_b128 v[168:171], v32 offset:3072
	v_add_u32_e32 v32, s43, v165
	ds_read_b128 v[172:175], v32
	ds_read_b128 v[176:179], v32 offset:1024
	ds_read_b128 v[180:183], v32 offset:2048
	ds_read_b128 v[184:187], v32 offset:3072
	v_lshl_add_u64 v[146:147], s[6:7], 0, v[138:139]
	s_add_i32 m0, s59, 0xc000
	ds_read_b128 v[188:191], v167
	ds_read_b128 v[192:195], v167 offset:1024
	ds_read_b128 v[196:199], v167 offset:2048
	ds_read_b128 v[208:211], v167 offset:3072
	ds_read_b128 v[216:219], v167 offset:4096
	ds_read_b128 v[220:223], v167 offset:5120
	ds_read_b128 v[224:227], v167 offset:6144
	ds_read_b128 v[228:231], v167 offset:7168
	global_load_lds_dwordx4 v[146:147], off
	v_lshl_add_u64 v[146:147], s[6:7], 0, v[140:141]
	s_add_i32 m0, s59, 0xe000
	s_nop 0
	global_load_lds_dwordx4 v[146:147], off
	s_waitcnt vmcnt(8)
	s_waitcnt lgkmcnt(0)
	s_barrier
	s_setprio 1
	v_mfma_f32_16x16x32_bf16 v[126:129], v[142:145], v[188:191], 0
	v_mfma_f32_16x16x32_bf16 v[122:125], v[158:161], v[188:191], 0
	v_mfma_f32_16x16x32_bf16 v[110:113], v[142:145], v[196:199], 0
	v_mfma_f32_16x16x32_bf16 v[106:109], v[158:161], v[196:199], 0
	v_mfma_f32_16x16x32_bf16 v[94:97], v[142:145], v[216:219], 0
	v_mfma_f32_16x16x32_bf16 v[90:93], v[158:161], v[216:219], 0
	v_mfma_f32_16x16x32_bf16 v[78:81], v[142:145], v[224:227], 0
	v_mfma_f32_16x16x32_bf16 v[74:77], v[158:161], v[224:227], 0
	v_mfma_f32_16x16x32_bf16 v[126:129], v[148:151], v[192:195], v[126:129]
	v_mfma_f32_16x16x32_bf16 v[122:125], v[168:171], v[192:195], v[122:125]
	v_mfma_f32_16x16x32_bf16 v[110:113], v[148:151], v[208:211], v[110:113]
	v_mfma_f32_16x16x32_bf16 v[106:109], v[168:171], v[208:211], v[106:109]
	v_mfma_f32_16x16x32_bf16 v[94:97], v[148:151], v[220:223], v[94:97]
	v_mfma_f32_16x16x32_bf16 v[90:93], v[168:171], v[220:223], v[90:93]
	v_mfma_f32_16x16x32_bf16 v[78:81], v[148:151], v[228:231], v[78:81]
	v_mfma_f32_16x16x32_bf16 v[74:77], v[168:171], v[228:231], v[74:77]
	v_mfma_f32_16x16x32_bf16 v[118:121], v[172:175], v[188:191], 0
	v_mfma_f32_16x16x32_bf16 v[114:117], v[180:183], v[188:191], 0
	v_mfma_f32_16x16x32_bf16 v[102:105], v[172:175], v[196:199], 0
	v_mfma_f32_16x16x32_bf16 v[98:101], v[180:183], v[196:199], 0
	v_mfma_f32_16x16x32_bf16 v[86:89], v[172:175], v[216:219], 0
	v_mfma_f32_16x16x32_bf16 v[82:85], v[180:183], v[216:219], 0
	v_mfma_f32_16x16x32_bf16 v[70:73], v[172:175], v[224:227], 0
	v_mfma_f32_16x16x32_bf16 v[66:69], v[180:183], v[224:227], 0
	v_mfma_f32_16x16x32_bf16 v[118:121], v[176:179], v[192:195], v[118:121]
	v_mfma_f32_16x16x32_bf16 v[114:117], v[184:187], v[192:195], v[114:117]
	v_mfma_f32_16x16x32_bf16 v[102:105], v[176:179], v[208:211], v[102:105]
	v_mfma_f32_16x16x32_bf16 v[98:101], v[184:187], v[208:211], v[98:101]
	v_mfma_f32_16x16x32_bf16 v[86:89], v[176:179], v[220:223], v[86:89]
	v_mfma_f32_16x16x32_bf16 v[82:85], v[184:187], v[220:223], v[82:85]
	v_mfma_f32_16x16x32_bf16 v[70:73], v[176:179], v[228:231], v[70:73]
	v_mfma_f32_16x16x32_bf16 v[66:69], v[184:187], v[228:231], v[66:69]
	s_setprio 0
	s_barrier
	s_add_i32 s75, s75, s51
	v_lshl_add_u64 v[146:147], s[44:45], 0, v[132:133]
	s_mov_b32 m0, s75
	ds_read_b128 v[188:191], v167 offset:16384
	ds_read_b128 v[192:195], v167 offset:17408
	ds_read_b128 v[196:199], v167 offset:18432
	ds_read_b128 v[208:211], v167 offset:19456
	ds_read_b128 v[216:219], v167 offset:20480
	ds_read_b128 v[220:223], v167 offset:21504
	ds_read_b128 v[224:227], v167 offset:22528
	ds_read_b128 v[228:231], v167 offset:23552
	global_load_lds_dwordx4 v[146:147], off
	s_add_i32 m0, s75, 0x2000
	s_add_u32 s76, s44, 0x40000
	v_lshl_add_u64 v[162:163], s[44:45], 0, v[136:137]
	s_addc_u32 s77, s45, 0
	s_add_i32 s43, s43, s51
	global_load_lds_dwordx4 v[162:163], off
	v_lshl_add_u64 v[200:201], s[76:77], 0, v[132:133]
	s_mov_b32 m0, s43
	v_lshl_add_u64 v[204:205], s[46:47], 0, v[134:135]
	global_load_lds_dwordx4 v[200:201], off
	v_lshl_add_u64 v[200:201], s[76:77], 0, v[136:137]
	s_add_i32 m0, s43, 0x2000
	s_nop 0
	global_load_lds_dwordx4 v[200:201], off
	v_lshl_add_u64 v[200:201], s[46:47], 0, v[130:131]
	s_mov_b32 m0, s59
	s_nop 0
	global_load_lds_dwordx4 v[200:201], off
	s_mov_b32 m0, s62
	s_nop 0
	global_load_lds_dwordx4 v[204:205], off
	s_waitcnt vmcnt(8)
	s_waitcnt lgkmcnt(0)
	s_barrier
	s_setprio 1
	v_mfma_f32_16x16x32_bf16 v[62:65], v[142:145], v[188:191], 0
	v_mfma_f32_16x16x32_bf16 v[58:61], v[158:161], v[188:191], 0
	v_mfma_f32_16x16x32_bf16 v[46:49], v[142:145], v[196:199], 0
	v_mfma_f32_16x16x32_bf16 v[42:45], v[158:161], v[196:199], 0
	v_mfma_f32_16x16x32_bf16 v[28:31], v[142:145], v[216:219], 0
	v_mfma_f32_16x16x32_bf16 v[24:27], v[158:161], v[216:219], 0
	v_mfma_f32_16x16x32_bf16 v[12:15], v[142:145], v[224:227], 0
	v_mfma_f32_16x16x32_bf16 v[8:11], v[158:161], v[224:227], 0
	v_mfma_f32_16x16x32_bf16 v[62:65], v[148:151], v[192:195], v[62:65]
	v_mfma_f32_16x16x32_bf16 v[58:61], v[168:171], v[192:195], v[58:61]
	v_mfma_f32_16x16x32_bf16 v[46:49], v[148:151], v[208:211], v[46:49]
	v_mfma_f32_16x16x32_bf16 v[42:45], v[168:171], v[208:211], v[42:45]
	v_mfma_f32_16x16x32_bf16 v[28:31], v[148:151], v[220:223], v[28:31]
	v_mfma_f32_16x16x32_bf16 v[24:27], v[168:171], v[220:223], v[24:27]
	v_mfma_f32_16x16x32_bf16 v[12:15], v[148:151], v[228:231], v[12:15]
	v_mfma_f32_16x16x32_bf16 v[8:11], v[168:171], v[228:231], v[8:11]
	v_mfma_f32_16x16x32_bf16 v[54:57], v[172:175], v[188:191], 0
	v_mfma_f32_16x16x32_bf16 v[50:53], v[180:183], v[188:191], 0
	v_mfma_f32_16x16x32_bf16 v[38:41], v[172:175], v[196:199], 0
	v_mfma_f32_16x16x32_bf16 v[34:37], v[180:183], v[196:199], 0
	v_mfma_f32_16x16x32_bf16 v[20:23], v[172:175], v[216:219], 0
	v_mfma_f32_16x16x32_bf16 v[16:19], v[180:183], v[216:219], 0
	v_mfma_f32_16x16x32_bf16 v[4:7], v[172:175], v[224:227], 0
	v_mfma_f32_16x16x32_bf16 v[0:3], v[180:183], v[224:227], 0
	v_mfma_f32_16x16x32_bf16 v[54:57], v[176:179], v[192:195], v[54:57]
	v_mfma_f32_16x16x32_bf16 v[50:53], v[184:187], v[192:195], v[50:53]
	v_mfma_f32_16x16x32_bf16 v[38:41], v[176:179], v[208:211], v[38:41]
	v_mfma_f32_16x16x32_bf16 v[34:37], v[184:187], v[208:211], v[34:37]
	v_mfma_f32_16x16x32_bf16 v[20:23], v[176:179], v[220:223], v[20:23]
	v_mfma_f32_16x16x32_bf16 v[16:19], v[184:187], v[220:223], v[16:19]
	v_mfma_f32_16x16x32_bf16 v[4:7], v[176:179], v[228:231], v[4:7]
	v_mfma_f32_16x16x32_bf16 v[0:3], v[184:187], v[228:231], v[0:3]
	s_setprio 0
	s_barrier
	s_branch .Lp3_795
; #define PG8_STAGE(bufoff, gbase, voff) do { _Pragma("unroll") for (int _i = 0; _i < 2; ++_i) \
;         __builtin_amdgcn_global_load_lds((const unsigned*)((const char*)(gbase) + (voff)[_i]), (PG8_LAS unsigned*)(lds + (bufoff) + ldsw + _i * 8192), 16, 0, 0); } while (0)
; #define PG8_LDA(dst, b, h) do { _Pragma("unroll") for (int m = 0; m < 4; ++m) _Pragma("unroll") for (int k = 0; k < 2; ++k) dst[m][k] = *(const PG8_LAS bf16x8*)(lds + PG8_SA(b, h) + aoff + m * 2048 + k * 1024); } while (0)
; #define PG8_LDB(dst, b, h) do { _Pragma("unroll") for (int n = 0; n < 2; ++n) _Pragma("unroll") for (int k = 0; k < 2; ++k) dst[n][k] = *(const PG8_LAS bf16x8*)(lds + PG8_SB(b, h) + boff + n * 2048 + k * 1024); } while (0)
; #define PG8_WAIT_V(n) asm volatile("s_waitcnt vmcnt(" #n ")" ::: "memory")
; #define PG8_WAIT_L(n) asm volatile("s_waitcnt lgkmcnt(" #n ")" ::: "memory")
; #define PG8_BAR __builtin_amdgcn_s_barrier()
; #define PG8_SCHED __builtin_amdgcn_sched_barrier(0)
; template <class Epi, bool ALIGN_EPI = true>
; __device__ __forceinline__ void gemm_phase(PG8_LAS unsigned char* lds, const Gemm g, const StaticOrder& S, const Epi& E) {
;     ...
;             PG8_LDB(B0, 0, 0); PG8_LDB(B1, 0, 1); PG8_SCHED; PG8_LDA(At, 0, 0); PG8_STAGE(PG8_SA(1, 1), a1 + hstepA, voffA);
;             PG8_WAIT_V(8); PG8_WAIT_L(0); PG8_BAR; PG8_MMA(0, 0, At, B0); PG8_MMA(0, 1, At, B1); PG8_BAR; PG8_SCHED;
;             PG8_LDA(At, 0, 1); PG8_STAGE(PG8_SB(0, 0), b2, voffB); PG8_STAGE(PG8_SB(0, 1), b2 + hstepB, voffB); PG8_STAGE(PG8_SA(0, 0), a2, voffA);
;             PG8_WAIT_V(8); PG8_WAIT_L(0); PG8_BAR; PG8_MMA(1, 0, At, B0); PG8_MMA(1, 1, At, B1); PG8_BAR; PG8_SCHED;
.Lrot_795:
	ds_read_b128 v[142:145], v32
	ds_read_b128 v[148:151], v32 offset:1024
	ds_read_b128 v[158:161], v32 offset:2048
	ds_read_b128 v[168:171], v32 offset:3072
	v_add_u32_e32 v32, s43, v165
	ds_read_b128 v[172:175], v32
	ds_read_b128 v[176:179], v32 offset:1024
	ds_read_b128 v[180:183], v32 offset:2048
	ds_read_b128 v[184:187], v32 offset:3072
	v_lshl_add_u64 v[146:147], s[6:7], 0, v[138:139]
	s_add_i32 m0, s59, 0xc000
	ds_read_b128 v[188:191], v167
	ds_read_b128 v[192:195], v167 offset:1024
	ds_read_b128 v[196:199], v167 offset:2048
	ds_read_b128 v[208:211], v167 offset:3072
	ds_read_b128 v[216:219], v167 offset:4096
	ds_read_b128 v[220:223], v167 offset:5120
	ds_read_b128 v[224:227], v167 offset:6144
	ds_read_b128 v[228:231], v167 offset:7168
	global_load_lds_dwordx4 v[146:147], off
	v_lshl_add_u64 v[146:147], s[6:7], 0, v[140:141]
	s_add_i32 m0, s59, 0xe000
	s_nop 0
	global_load_lds_dwordx4 v[146:147], off
	s_waitcnt vmcnt(8)
	s_waitcnt lgkmcnt(0)
	s_barrier
	s_setprio 1
	v_mfma_f32_16x16x32_bf16 v[126:129], v[142:145], v[188:191], v[126:129]
	v_mfma_f32_16x16x32_bf16 v[122:125], v[158:161], v[188:191], v[122:125]
	v_mfma_f32_16x16x32_bf16 v[110:113], v[142:145], v[196:199], v[110:113]
	v_mfma_f32_16x16x32_bf16 v[106:109], v[158:161], v[196:199], v[106:109]
	v_mfma_f32_16x16x32_bf16 v[94:97], v[142:145], v[216:219], v[94:97]
	v_mfma_f32_16x16x32_bf16 v[90:93], v[158:161], v[216:219], v[90:93]
	v_mfma_f32_16x16x32_bf16 v[78:81], v[142:145], v[224:227], v[78:81]
	v_mfma_f32_16x16x32_bf16 v[74:77], v[158:161], v[224:227], v[74:77]
	v_mfma_f32_16x16x32_bf16 v[126:129], v[148:151], v[192:195], v[126:129]
	v_mfma_f32_16x16x32_bf16 v[122:125], v[168:171], v[192:195], v[122:125]
	v_mfma_f32_16x16x32_bf16 v[110:113], v[148:151], v[208:211], v[110:113]
	v_mfma_f32_16x16x32_bf16 v[106:109], v[168:171], v[208:211], v[106:109]
	v_mfma_f32_16x16x32_bf16 v[94:97], v[148:151], v[220:223], v[94:97]
	v_mfma_f32_16x16x32_bf16 v[90:93], v[168:171], v[220:223], v[90:93]
	v_mfma_f32_16x16x32_bf16 v[78:81], v[148:151], v[228:231], v[78:81]
	v_mfma_f32_16x16x32_bf16 v[74:77], v[168:171], v[228:231], v[74:77]
	v_mfma_f32_16x16x32_bf16 v[118:121], v[172:175], v[188:191], v[118:121]
	v_mfma_f32_16x16x32_bf16 v[114:117], v[180:183], v[188:191], v[114:117]
	v_mfma_f32_16x16x32_bf16 v[102:105], v[172:175], v[196:199], v[102:105]
	v_mfma_f32_16x16x32_bf16 v[98:101], v[180:183], v[196:199], v[98:101]
	v_mfma_f32_16x16x32_bf16 v[86:89], v[172:175], v[216:219], v[86:89]
	v_mfma_f32_16x16x32_bf16 v[82:85], v[180:183], v[216:219], v[82:85]
	v_mfma_f32_16x16x32_bf16 v[70:73], v[172:175], v[224:227], v[70:73]
	v_mfma_f32_16x16x32_bf16 v[66:69], v[180:183], v[224:227], v[66:69]
	v_mfma_f32_16x16x32_bf16 v[118:121], v[176:179], v[192:195], v[118:121]
	v_mfma_f32_16x16x32_bf16 v[114:117], v[184:187], v[192:195], v[114:117]
	v_mfma_f32_16x16x32_bf16 v[102:105], v[176:179], v[208:211], v[102:105]
	v_mfma_f32_16x16x32_bf16 v[98:101], v[184:187], v[208:211], v[98:101]
	v_mfma_f32_16x16x32_bf16 v[86:89], v[176:179], v[220:223], v[86:89]
	v_mfma_f32_16x16x32_bf16 v[82:85], v[184:187], v[220:223], v[82:85]
	v_mfma_f32_16x16x32_bf16 v[70:73], v[176:179], v[228:231], v[70:73]
	v_mfma_f32_16x16x32_bf16 v[66:69], v[184:187], v[228:231], v[66:69]
	s_setprio 0
	s_barrier
	s_add_i32 s75, s75, s51
	v_lshl_add_u64 v[146:147], s[44:45], 0, v[132:133]
	s_mov_b32 m0, s75
	ds_read_b128 v[188:191], v167 offset:16384
	ds_read_b128 v[192:195], v167 offset:17408
	ds_read_b128 v[196:199], v167 offset:18432
	ds_read_b128 v[208:211], v167 offset:19456
	ds_read_b128 v[216:219], v167 offset:20480
	ds_read_b128 v[220:223], v167 offset:21504
	ds_read_b128 v[224:227], v167 offset:22528
	ds_read_b128 v[228:231], v167 offset:23552
	global_load_lds_dwordx4 v[146:147], off
	s_add_i32 m0, s75, 0x2000
	s_add_u32 s76, s44, 0x40000
	v_lshl_add_u64 v[162:163], s[44:45], 0, v[136:137]
	s_addc_u32 s77, s45, 0
	s_add_i32 s43, s43, s51
	global_load_lds_dwordx4 v[162:163], off
	v_lshl_add_u64 v[200:201], s[76:77], 0, v[132:133]
	s_mov_b32 m0, s43
	v_lshl_add_u64 v[204:205], s[46:47], 0, v[134:135]
	global_load_lds_dwordx4 v[200:201], off
	v_lshl_add_u64 v[200:201], s[76:77], 0, v[136:137]
	s_add_i32 m0, s43, 0x2000
	s_nop 0
	global_load_lds_dwordx4 v[200:201], off
	v_lshl_add_u64 v[200:201], s[46:47], 0, v[130:131]
	s_mov_b32 m0, s59
	s_nop 0
	global_load_lds_dwordx4 v[200:201], off
	s_mov_b32 m0, s62
	s_nop 0
	global_load_lds_dwordx4 v[204:205], off
	s_waitcnt vmcnt(8)
	s_waitcnt lgkmcnt(0)
	s_barrier
	s_setprio 1
	v_mfma_f32_16x16x32_bf16 v[62:65], v[142:145], v[188:191], v[62:65]
	v_mfma_f32_16x16x32_bf16 v[58:61], v[158:161], v[188:191], v[58:61]
	v_mfma_f32_16x16x32_bf16 v[46:49], v[142:145], v[196:199], v[46:49]
	v_mfma_f32_16x16x32_bf16 v[42:45], v[158:161], v[196:199], v[42:45]
	v_mfma_f32_16x16x32_bf16 v[28:31], v[142:145], v[216:219], v[28:31]
	v_mfma_f32_16x16x32_bf16 v[24:27], v[158:161], v[216:219], v[24:27]
	v_mfma_f32_16x16x32_bf16 v[12:15], v[142:145], v[224:227], v[12:15]
	v_mfma_f32_16x16x32_bf16 v[8:11], v[158:161], v[224:227], v[8:11]
	v_mfma_f32_16x16x32_bf16 v[62:65], v[148:151], v[192:195], v[62:65]
	v_mfma_f32_16x16x32_bf16 v[58:61], v[168:171], v[192:195], v[58:61]
	v_mfma_f32_16x16x32_bf16 v[46:49], v[148:151], v[208:211], v[46:49]
	v_mfma_f32_16x16x32_bf16 v[42:45], v[168:171], v[208:211], v[42:45]
	v_mfma_f32_16x16x32_bf16 v[28:31], v[148:151], v[220:223], v[28:31]
	v_mfma_f32_16x16x32_bf16 v[24:27], v[168:171], v[220:223], v[24:27]
	v_mfma_f32_16x16x32_bf16 v[12:15], v[148:151], v[228:231], v[12:15]
	v_mfma_f32_16x16x32_bf16 v[8:11], v[168:171], v[228:231], v[8:11]
	v_mfma_f32_16x16x32_bf16 v[54:57], v[172:175], v[188:191], v[54:57]
	v_mfma_f32_16x16x32_bf16 v[50:53], v[180:183], v[188:191], v[50:53]
	v_mfma_f32_16x16x32_bf16 v[38:41], v[172:175], v[196:199], v[38:41]
	v_mfma_f32_16x16x32_bf16 v[34:37], v[180:183], v[196:199], v[34:37]
	v_mfma_f32_16x16x32_bf16 v[20:23], v[172:175], v[216:219], v[20:23]
	v_mfma_f32_16x16x32_bf16 v[16:19], v[180:183], v[216:219], v[16:19]
	v_mfma_f32_16x16x32_bf16 v[4:7], v[172:175], v[224:227], v[4:7]
	v_mfma_f32_16x16x32_bf16 v[0:3], v[180:183], v[224:227], v[0:3]
	v_mfma_f32_16x16x32_bf16 v[54:57], v[176:179], v[192:195], v[54:57]
	v_mfma_f32_16x16x32_bf16 v[50:53], v[184:187], v[192:195], v[50:53]
	v_mfma_f32_16x16x32_bf16 v[38:41], v[176:179], v[208:211], v[38:41]
	v_mfma_f32_16x16x32_bf16 v[34:37], v[184:187], v[208:211], v[34:37]
	v_mfma_f32_16x16x32_bf16 v[20:23], v[176:179], v[220:223], v[20:23]
	v_mfma_f32_16x16x32_bf16 v[16:19], v[184:187], v[220:223], v[16:19]
	v_mfma_f32_16x16x32_bf16 v[4:7], v[176:179], v[228:231], v[4:7]
	v_mfma_f32_16x16x32_bf16 v[0:3], v[184:187], v[228:231], v[0:3]
	s_setprio 0
	s_barrier
; #define PG8_STAGE(bufoff, gbase, voff) do { _Pragma("unroll") for (int _i = 0; _i < 2; ++_i) \
;         __builtin_amdgcn_global_load_lds((const unsigned*)((const char*)(gbase) + (voff)[_i]), (PG8_LAS unsigned*)(lds + (bufoff) + ldsw + _i * 8192), 16, 0, 0); } while (0)
; #define PG8_LDA(dst, b, h) do { _Pragma("unroll") for (int m = 0; m < 4; ++m) _Pragma("unroll") for (int k = 0; k < 2; ++k) dst[m][k] = *(const PG8_LAS bf16x8*)(lds + PG8_SA(b, h) + aoff + m * 2048 + k * 1024); } while (0)
; #define PG8_LDB(dst, b, h) do { _Pragma("unroll") for (int n = 0; n < 2; ++n) _Pragma("unroll") for (int k = 0; k < 2; ++k) dst[n][k] = *(const PG8_LAS bf16x8*)(lds + PG8_SB(b, h) + boff + n * 2048 + k * 1024); } while (0)
; #define PG8_WAIT_V(n) asm volatile("s_waitcnt vmcnt(" #n ")" ::: "memory")
; #define PG8_WAIT_L(n) asm volatile("s_waitcnt lgkmcnt(" #n ")" ::: "memory")
; #define PG8_BAR __builtin_amdgcn_s_barrier()
; #define PG8_SCHED __builtin_amdgcn_sched_barrier(0)
; template <class Epi, bool ALIGN_EPI = true>
; __device__ __forceinline__ void gemm_phase(PG8_LAS unsigned char* lds, const Gemm g, const StaticOrder& S, const Epi& E) {
;     ...
;             PG8_LDB(B0, 1, 0); PG8_LDB(B1, 1, 1); PG8_SCHED; PG8_LDA(At, 1, 0); PG8_STAGE(PG8_SA(0, 1), a2 + hstepA, voffA);
;             PG8_WAIT_V(8); PG8_WAIT_L(0); PG8_BAR; PG8_MMA(0, 0, At, B0); PG8_MMA(0, 1, At, B1); PG8_BAR; PG8_SCHED;
.Lp3_795:
	s_add_i32 s43, 0, 0x18000
	v_add_u32_e32 v32, s43, v165
	s_add_i32 s75, 0, 0x1c000
	ds_read_b128 v[142:145], v32
	ds_read_b128 v[148:151], v32 offset:1024
	ds_read_b128 v[158:161], v32 offset:2048
	ds_read_b128 v[168:171], v32 offset:3072
	v_add_u32_e32 v32, s75, v165
	ds_read_b128 v[172:175], v32
	ds_read_b128 v[176:179], v32 offset:1024
	ds_read_b128 v[180:183], v32 offset:2048
	ds_read_b128 v[184:187], v32 offset:3072
	s_add_u32 s46, s46, 0x40000
	s_addc_u32 s47, s47, 0
	s_mov_b32 m0, s63
	v_lshl_add_u64 v[206:207], s[46:47], 0, v[130:131]
	ds_read_b128 v[188:191], v167 offset:32768
	ds_read_b128 v[192:195], v167 offset:33792
	ds_read_b128 v[196:199], v167 offset:34816
	ds_read_b128 v[208:211], v167 offset:35840
	ds_read_b128 v[216:219], v167 offset:36864
	ds_read_b128 v[220:223], v167 offset:37888
	ds_read_b128 v[224:227], v167 offset:38912
	ds_read_b128 v[228:231], v167 offset:39936
	global_load_lds_dwordx4 v[206:207], off
	v_lshl_add_u64 v[206:207], s[46:47], 0, v[134:135]
	s_mov_b32 m0, s66
	s_nop 0
	global_load_lds_dwordx4 v[206:207], off
	s_waitcnt vmcnt(8)
	s_waitcnt lgkmcnt(0)
	s_barrier
	s_setprio 1
	v_mfma_f32_16x16x32_bf16 v[126:129], v[142:145], v[188:191], v[126:129]
	v_mfma_f32_16x16x32_bf16 v[122:125], v[158:161], v[188:191], v[122:125]
	v_mfma_f32_16x16x32_bf16 v[110:113], v[142:145], v[196:199], v[110:113]
	v_mfma_f32_16x16x32_bf16 v[106:109], v[158:161], v[196:199], v[106:109]
	v_mfma_f32_16x16x32_bf16 v[94:97], v[142:145], v[216:219], v[94:97]
	v_mfma_f32_16x16x32_bf16 v[90:93], v[158:161], v[216:219], v[90:93]
	v_mfma_f32_16x16x32_bf16 v[78:81], v[142:145], v[224:227], v[78:81]
	v_mfma_f32_16x16x32_bf16 v[74:77], v[158:161], v[224:227], v[74:77]
	v_mfma_f32_16x16x32_bf16 v[126:129], v[148:151], v[192:195], v[126:129]
	v_mfma_f32_16x16x32_bf16 v[122:125], v[168:171], v[192:195], v[122:125]
	v_mfma_f32_16x16x32_bf16 v[110:113], v[148:151], v[208:211], v[110:113]
	v_mfma_f32_16x16x32_bf16 v[106:109], v[168:171], v[208:211], v[106:109]
	v_mfma_f32_16x16x32_bf16 v[94:97], v[148:151], v[220:223], v[94:97]
	v_mfma_f32_16x16x32_bf16 v[90:93], v[168:171], v[220:223], v[90:93]
	v_mfma_f32_16x16x32_bf16 v[78:81], v[148:151], v[228:231], v[78:81]
	v_mfma_f32_16x16x32_bf16 v[74:77], v[168:171], v[228:231], v[74:77]
	v_mfma_f32_16x16x32_bf16 v[118:121], v[172:175], v[188:191], v[118:121]
	v_mfma_f32_16x16x32_bf16 v[114:117], v[180:183], v[188:191], v[114:117]
	v_mfma_f32_16x16x32_bf16 v[102:105], v[172:175], v[196:199], v[102:105]
	v_mfma_f32_16x16x32_bf16 v[98:101], v[180:183], v[196:199], v[98:101]
	v_mfma_f32_16x16x32_bf16 v[86:89], v[172:175], v[216:219], v[86:89]
	v_mfma_f32_16x16x32_bf16 v[82:85], v[180:183], v[216:219], v[82:85]
	v_mfma_f32_16x16x32_bf16 v[70:73], v[172:175], v[224:227], v[70:73]
	v_mfma_f32_16x16x32_bf16 v[66:69], v[180:183], v[224:227], v[66:69]
	v_mfma_f32_16x16x32_bf16 v[118:121], v[176:179], v[192:195], v[118:121]
	v_mfma_f32_16x16x32_bf16 v[114:117], v[184:187], v[192:195], v[114:117]
	v_mfma_f32_16x16x32_bf16 v[102:105], v[176:179], v[208:211], v[102:105]
	v_mfma_f32_16x16x32_bf16 v[98:101], v[184:187], v[208:211], v[98:101]
	v_mfma_f32_16x16x32_bf16 v[86:89], v[176:179], v[220:223], v[86:89]
	v_mfma_f32_16x16x32_bf16 v[82:85], v[184:187], v[220:223], v[82:85]
	v_mfma_f32_16x16x32_bf16 v[70:73], v[176:179], v[228:231], v[70:73]
	v_mfma_f32_16x16x32_bf16 v[66:69], v[184:187], v[228:231], v[66:69]
	s_setprio 0
	s_barrier
; #define PG8_STAGE(bufoff, gbase, voff) do { _Pragma("unroll") for (int _i = 0; _i < 2; ++_i) \
;         __builtin_amdgcn_global_load_lds((const unsigned*)((const char*)(gbase) + (voff)[_i]), (PG8_LAS unsigned*)(lds + (bufoff) + ldsw + _i * 8192), 16, 0, 0); } while (0)
; #define PG8_LDA(dst, b, h) do { _Pragma("unroll") for (int m = 0; m < 4; ++m) _Pragma("unroll") for (int k = 0; k < 2; ++k) dst[m][k] = *(const PG8_LAS bf16x8*)(lds + PG8_SA(b, h) + aoff + m * 2048 + k * 1024); } while (0)
; #define PG8_WAIT_V(n) asm volatile("s_waitcnt vmcnt(" #n ")" ::: "memory")
; #define PG8_WAIT_L(n) asm volatile("s_waitcnt lgkmcnt(" #n ")" ::: "memory")
; #define PG8_BAR __builtin_amdgcn_s_barrier()
; #define PG8_SCHED __builtin_amdgcn_sched_barrier(0)
; template <class Epi, bool ALIGN_EPI = true>
; __device__ __forceinline__ void gemm_phase(PG8_LAS unsigned char* lds, const Gemm g, const StaticOrder& S, const Epi& E) {
;     ...
;         for (int t = 0; t < nt; t += 2) {
;             const bool last = (t == nt - 2);
;             const char* a1 = cA + (size_t)(t + 1) * kstep;
;             const char* a2 = last ? nA : cA + (size_t)(t + 2) * kstep; const char* b2 = last ? nB : cB + (size_t)(t + 2) * kstep;
;     ...
;             PG8_LDA(At, 1, 1); PG8_STAGE(PG8_SB(1, 0), b3, voffB); PG8_STAGE(PG8_SB(1, 1), b3 + hstepB, voffB); PG8_STAGE(PG8_SA(1, 0), a3, voffA);
;             PG8_WAIT_V(8); PG8_WAIT_L(0); PG8_BAR; PG8_MMA(1, 0, At, B0); PG8_MMA(1, 1, At, B1); PG8_BAR; PG8_SCHED;
	s_add_i32 s43, s43, s51
	v_lshl_add_u64 v[146:147], v[146:147], 0, s[60:61]
	s_mov_b32 m0, s43
	ds_read_b128 v[188:191], v167 offset:49152
	ds_read_b128 v[192:195], v167 offset:50176
	ds_read_b128 v[196:199], v167 offset:51200
	ds_read_b128 v[208:211], v167 offset:52224
	ds_read_b128 v[216:219], v167 offset:53248
	ds_read_b128 v[220:223], v167 offset:54272
	ds_read_b128 v[224:227], v167 offset:55296
	ds_read_b128 v[228:231], v167 offset:56320
	global_load_lds_dwordx4 v[146:147], off
	s_add_i32 m0, s43, 0x2000
	s_add_u32 s44, s44, 0x40080
	v_lshl_add_u64 v[146:147], v[162:163], 0, s[60:61]
	s_addc_u32 s45, s45, 0
	s_add_i32 s43, s75, s51
	global_load_lds_dwordx4 v[146:147], off
	v_lshl_add_u64 v[146:147], s[44:45], 0, v[132:133]
	s_mov_b32 m0, s43
	s_nop 0
	global_load_lds_dwordx4 v[146:147], off
	v_lshl_add_u64 v[146:147], s[44:45], 0, v[136:137]
	s_add_i32 m0, s43, 0x2000
	s_nop 0
	global_load_lds_dwordx4 v[146:147], off
	v_lshl_add_u64 v[146:147], v[200:201], 0, s[60:61]
	s_mov_b32 m0, s70
	s_nop 0
	global_load_lds_dwordx4 v[146:147], off
	v_lshl_add_u64 v[146:147], v[204:205], 0, s[60:61]
	s_mov_b32 m0, s71
	s_nop 0
	global_load_lds_dwordx4 v[146:147], off
	s_add_i32 s37, s37, 2
	s_add_u32 s6, s6, 0x100
	s_addc_u32 s7, s7, 0
	s_add_u32 s9, s9, 0x100
	s_addc_u32 s35, s35, 0
	s_add_u32 s43, s6, 0xfffc0080
	s_addc_u32 s44, s7, -1
	s_add_i32 s75, 0, 0x10000
	s_cmp_eq_u32 s37, 12
	s_cselect_b32 s47, s39, s44
	s_cselect_b32 s46, s38, s43
	v_add_u32_e32 v32, s75, v165
	s_cselect_b32 s45, s41, s35
	s_cselect_b32 s44, s40, s9
	s_add_i32 s43, 0, 0x14000
	s_cmp_gt_u32 s37, 13
	s_waitcnt vmcnt(8)
	s_waitcnt lgkmcnt(0)
	s_barrier
	s_setprio 1
	v_mfma_f32_16x16x32_bf16 v[62:65], v[142:145], v[188:191], v[62:65]
	v_mfma_f32_16x16x32_bf16 v[58:61], v[158:161], v[188:191], v[58:61]
	v_mfma_f32_16x16x32_bf16 v[46:49], v[142:145], v[196:199], v[46:49]
	v_mfma_f32_16x16x32_bf16 v[42:45], v[158:161], v[196:199], v[42:45]
	v_mfma_f32_16x16x32_bf16 v[28:31], v[142:145], v[216:219], v[28:31]
	v_mfma_f32_16x16x32_bf16 v[24:27], v[158:161], v[216:219], v[24:27]
	v_mfma_f32_16x16x32_bf16 v[12:15], v[142:145], v[224:227], v[12:15]
	v_mfma_f32_16x16x32_bf16 v[8:11], v[158:161], v[224:227], v[8:11]
	v_mfma_f32_16x16x32_bf16 v[62:65], v[148:151], v[192:195], v[62:65]
	v_mfma_f32_16x16x32_bf16 v[58:61], v[168:171], v[192:195], v[58:61]
	v_mfma_f32_16x16x32_bf16 v[46:49], v[148:151], v[208:211], v[46:49]
	v_mfma_f32_16x16x32_bf16 v[42:45], v[168:171], v[208:211], v[42:45]
	v_mfma_f32_16x16x32_bf16 v[28:31], v[148:151], v[220:223], v[28:31]
	v_mfma_f32_16x16x32_bf16 v[24:27], v[168:171], v[220:223], v[24:27]
	v_mfma_f32_16x16x32_bf16 v[12:15], v[148:151], v[228:231], v[12:15]
	v_mfma_f32_16x16x32_bf16 v[8:11], v[168:171], v[228:231], v[8:11]
	v_mfma_f32_16x16x32_bf16 v[54:57], v[172:175], v[188:191], v[54:57]
	v_mfma_f32_16x16x32_bf16 v[50:53], v[180:183], v[188:191], v[50:53]
	v_mfma_f32_16x16x32_bf16 v[38:41], v[172:175], v[196:199], v[38:41]
	v_mfma_f32_16x16x32_bf16 v[34:37], v[180:183], v[196:199], v[34:37]
	v_mfma_f32_16x16x32_bf16 v[20:23], v[172:175], v[216:219], v[20:23]
	v_mfma_f32_16x16x32_bf16 v[16:19], v[180:183], v[216:219], v[16:19]
	v_mfma_f32_16x16x32_bf16 v[4:7], v[172:175], v[224:227], v[4:7]
	v_mfma_f32_16x16x32_bf16 v[0:3], v[180:183], v[224:227], v[0:3]
	v_mfma_f32_16x16x32_bf16 v[54:57], v[176:179], v[192:195], v[54:57]
	v_mfma_f32_16x16x32_bf16 v[50:53], v[184:187], v[192:195], v[50:53]
	v_mfma_f32_16x16x32_bf16 v[38:41], v[176:179], v[208:211], v[38:41]
	v_mfma_f32_16x16x32_bf16 v[34:37], v[184:187], v[208:211], v[34:37]
	v_mfma_f32_16x16x32_bf16 v[20:23], v[176:179], v[220:223], v[20:23]
	v_mfma_f32_16x16x32_bf16 v[16:19], v[184:187], v[220:223], v[16:19]
	v_mfma_f32_16x16x32_bf16 v[4:7], v[176:179], v[228:231], v[4:7]
	v_mfma_f32_16x16x32_bf16 v[0:3], v[184:187], v[228:231], v[0:3]
	s_setprio 0
	s_barrier
	s_cbranch_scc0 .Lrot_795
	s_and_b64 vcc, exec, s[26:27]
	s_cbranch_vccz .LBB0_798
	s_barrier

; #define PG8_STAGE(bufoff, gbase, voff) do { _Pragma("unroll") for (int _i = 0; _i < 2; ++_i) \
;         __builtin_amdgcn_global_load_lds((const unsigned*)((const char*)(gbase) + (voff)[_i]), (PG8_LAS unsigned*)(lds + (bufoff) + ldsw + _i * 8192), 16, 0, 0); } while (0)
; #define PG8_LDA(dst, b, h) do { _Pragma("unroll") for (int m = 0; m < 4; ++m) _Pragma("unroll") for (int k = 0; k < 2; ++k) dst[m][k] = *(const PG8_LAS bf16x8*)(lds + PG8_SA(b, h) + aoff + m * 2048 + k * 1024); } while (0)
; #define PG8_LDB(dst, b, h) do { _Pragma("unroll") for (int n = 0; n < 2; ++n) _Pragma("unroll") for (int k = 0; k < 2; ++k) dst[n][k] = *(const PG8_LAS bf16x8*)(lds + PG8_SB(b, h) + boff + n * 2048 + k * 1024); } while (0)
; #define PG8_WAIT_V(n) asm volatile("s_waitcnt vmcnt(" #n ")" ::: "memory")
; #define PG8_WAIT_L(n) asm volatile("s_waitcnt lgkmcnt(" #n ")" ::: "memory")
; #define PG8_BAR __builtin_amdgcn_s_barrier()
; #define PG8_SCHED __builtin_amdgcn_sched_barrier(0)
; template <class Epi, bool ALIGN_EPI = true>
; __device__ __forceinline__ void gemm_phase(PG8_LAS unsigned char* lds, const Gemm g, const StaticOrder& S, const Epi& E) {
;     ...
;             PG8_LDB(B0, 0, 0); PG8_LDB(B1, 0, 1); PG8_SCHED; PG8_LDA(At, 0, 0); PG8_STAGE(PG8_SA(1, 1), a1 + hstepA, voffA);
;             PG8_WAIT_V(8); PG8_WAIT_L(0); PG8_BAR; PG8_MMA(0, 0, At, B0); PG8_MMA(0, 1, At, B1); PG8_BAR; PG8_SCHED;
;             PG8_LDA(At, 0, 1); PG8_STAGE(PG8_SB(0, 0), b2, voffB); PG8_STAGE(PG8_SB(0, 1), b2 + hstepB, voffB); PG8_STAGE(PG8_SA(0, 0), a2, voffA);
;             PG8_WAIT_V(8); PG8_WAIT_L(0); PG8_BAR; PG8_MMA(1, 0, At, B0); PG8_MMA(1, 1, At, B1); PG8_BAR; PG8_SCHED;
.LBB0_1004:
	s_add_u32 s22, s20, 0xfffc0080
	s_addc_u32 s23, s21, -1
	s_add_i32 s50, 0, 0x10000
	s_cmp_eq_u32 s49, 12
	s_cselect_b32 s25, s11, s23
	s_cselect_b32 s24, s17, s22
	v_add_u32_e32 v32, s50, v143
	s_cselect_b32 s23, s9, s48
	s_cselect_b32 s22, s19, s47
	s_add_i32 s52, 0, 0x14000
	ds_read_b128 v[130:133], v32
	ds_read_b128 v[134:137], v32 offset:1024
	ds_read_b128 v[164:167], v32 offset:2048
	ds_read_b128 v[168:171], v32 offset:3072
	v_add_u32_e32 v32, s52, v143
	ds_read_b128 v[172:175], v32
	ds_read_b128 v[176:179], v32 offset:1024
	ds_read_b128 v[180:183], v32 offset:2048
	ds_read_b128 v[184:187], v32 offset:3072
	v_lshl_add_u64 v[146:147], s[20:21], 0, v[158:159]
	s_add_i32 m0, s35, 0xc000
	ds_read_b128 v[188:191], v163
	ds_read_b128 v[192:195], v163 offset:1024
	ds_read_b128 v[196:199], v163 offset:2048
	ds_read_b128 v[216:219], v163 offset:3072
	ds_read_b128 v[220:223], v163 offset:4096
	ds_read_b128 v[224:227], v163 offset:5120
	ds_read_b128 v[228:231], v163 offset:6144
	ds_read_b128 v[232:235], v163 offset:7168
	global_load_lds_dwordx4 v[146:147], off
	v_lshl_add_u64 v[146:147], s[20:21], 0, v[160:161]
	s_add_i32 m0, s35, 0xe000
	s_nop 0
	global_load_lds_dwordx4 v[146:147], off
	s_waitcnt vmcnt(8)
	s_waitcnt lgkmcnt(0)
	s_barrier
	s_setprio 1
	v_mfma_f32_16x16x32_bf16 v[126:129], v[188:191], v[130:133], 0
	v_mfma_f32_16x16x32_bf16 v[122:125], v[188:191], v[164:167], 0
	v_mfma_f32_16x16x32_bf16 v[110:113], v[196:199], v[130:133], 0
	v_mfma_f32_16x16x32_bf16 v[106:109], v[196:199], v[164:167], 0
	v_mfma_f32_16x16x32_bf16 v[94:97], v[220:223], v[130:133], 0
	v_mfma_f32_16x16x32_bf16 v[90:93], v[220:223], v[164:167], 0
	v_mfma_f32_16x16x32_bf16 v[78:81], v[228:231], v[130:133], 0
	v_mfma_f32_16x16x32_bf16 v[74:77], v[228:231], v[164:167], 0
	v_mfma_f32_16x16x32_bf16 v[126:129], v[192:195], v[134:137], v[126:129]
	v_mfma_f32_16x16x32_bf16 v[122:125], v[192:195], v[168:171], v[122:125]
	v_mfma_f32_16x16x32_bf16 v[110:113], v[216:219], v[134:137], v[110:113]
	v_mfma_f32_16x16x32_bf16 v[106:109], v[216:219], v[168:171], v[106:109]
	v_mfma_f32_16x16x32_bf16 v[94:97], v[224:227], v[134:137], v[94:97]
	v_mfma_f32_16x16x32_bf16 v[90:93], v[224:227], v[168:171], v[90:93]
	v_mfma_f32_16x16x32_bf16 v[78:81], v[232:235], v[134:137], v[78:81]
	v_mfma_f32_16x16x32_bf16 v[74:77], v[232:235], v[168:171], v[74:77]
	v_mfma_f32_16x16x32_bf16 v[118:121], v[188:191], v[172:175], 0
	v_mfma_f32_16x16x32_bf16 v[114:117], v[188:191], v[180:183], 0
	v_mfma_f32_16x16x32_bf16 v[102:105], v[196:199], v[172:175], 0
	v_mfma_f32_16x16x32_bf16 v[98:101], v[196:199], v[180:183], 0
	v_mfma_f32_16x16x32_bf16 v[86:89], v[220:223], v[172:175], 0
	v_mfma_f32_16x16x32_bf16 v[82:85], v[220:223], v[180:183], 0
	v_mfma_f32_16x16x32_bf16 v[70:73], v[228:231], v[172:175], 0
	v_mfma_f32_16x16x32_bf16 v[66:69], v[228:231], v[180:183], 0
	v_mfma_f32_16x16x32_bf16 v[118:121], v[192:195], v[176:179], v[118:121]
	v_mfma_f32_16x16x32_bf16 v[114:117], v[192:195], v[184:187], v[114:117]
	v_mfma_f32_16x16x32_bf16 v[102:105], v[216:219], v[176:179], v[102:105]
	v_mfma_f32_16x16x32_bf16 v[98:101], v[216:219], v[184:187], v[98:101]
	v_mfma_f32_16x16x32_bf16 v[86:89], v[224:227], v[176:179], v[86:89]
	v_mfma_f32_16x16x32_bf16 v[82:85], v[224:227], v[184:187], v[82:85]
	v_mfma_f32_16x16x32_bf16 v[70:73], v[232:235], v[176:179], v[70:73]
	v_mfma_f32_16x16x32_bf16 v[66:69], v[232:235], v[184:187], v[66:69]
	s_setprio 0
	s_barrier
	s_add_i32 s50, s50, s34
	v_lshl_add_u64 v[146:147], s[22:23], 0, v[138:139]
	s_mov_b32 m0, s50
	ds_read_b128 v[188:191], v163 offset:16384
	ds_read_b128 v[192:195], v163 offset:17408
	ds_read_b128 v[196:199], v163 offset:18432
	ds_read_b128 v[216:219], v163 offset:19456
	ds_read_b128 v[220:223], v163 offset:20480
	ds_read_b128 v[224:227], v163 offset:21504
	ds_read_b128 v[228:231], v163 offset:22528
	ds_read_b128 v[232:235], v163 offset:23552
	global_load_lds_dwordx4 v[146:147], off
	s_add_i32 m0, s50, 0x2000
	s_add_u32 s50, s22, 0x40000
	v_lshl_add_u64 v[148:149], s[22:23], 0, v[140:141]
	s_addc_u32 s51, s23, 0
	s_add_i32 s52, s52, s34
	global_load_lds_dwordx4 v[148:149], off
	v_lshl_add_u64 v[150:151], s[50:51], 0, v[138:139]
	s_mov_b32 m0, s52
	v_lshl_add_u64 v[200:201], s[24:25], 0, v[140:141]
	global_load_lds_dwordx4 v[150:151], off
	v_lshl_add_u64 v[150:151], s[50:51], 0, v[140:141]
	s_add_i32 m0, s52, 0x2000
	s_nop 0
	global_load_lds_dwordx4 v[150:151], off
	v_lshl_add_u64 v[150:151], s[24:25], 0, v[138:139]
	s_mov_b32 m0, s35
	s_nop 0
	global_load_lds_dwordx4 v[150:151], off
	s_mov_b32 m0, s36
	s_nop 0
	global_load_lds_dwordx4 v[200:201], off
	s_waitcnt vmcnt(8)
	s_waitcnt lgkmcnt(0)
	s_barrier
	s_setprio 1
	v_mfma_f32_16x16x32_bf16 v[62:65], v[188:191], v[130:133], 0
	v_mfma_f32_16x16x32_bf16 v[58:61], v[188:191], v[164:167], 0
	v_mfma_f32_16x16x32_bf16 v[46:49], v[196:199], v[130:133], 0
	v_mfma_f32_16x16x32_bf16 v[42:45], v[196:199], v[164:167], 0
	v_mfma_f32_16x16x32_bf16 v[28:31], v[220:223], v[130:133], 0
	v_mfma_f32_16x16x32_bf16 v[24:27], v[220:223], v[164:167], 0
	v_mfma_f32_16x16x32_bf16 v[12:15], v[228:231], v[130:133], 0
	v_mfma_f32_16x16x32_bf16 v[8:11], v[228:231], v[164:167], 0
	v_mfma_f32_16x16x32_bf16 v[62:65], v[192:195], v[134:137], v[62:65]
	v_mfma_f32_16x16x32_bf16 v[58:61], v[192:195], v[168:171], v[58:61]
	v_mfma_f32_16x16x32_bf16 v[46:49], v[216:219], v[134:137], v[46:49]
	v_mfma_f32_16x16x32_bf16 v[42:45], v[216:219], v[168:171], v[42:45]
	v_mfma_f32_16x16x32_bf16 v[28:31], v[224:227], v[134:137], v[28:31]
	v_mfma_f32_16x16x32_bf16 v[24:27], v[224:227], v[168:171], v[24:27]
	v_mfma_f32_16x16x32_bf16 v[12:15], v[232:235], v[134:137], v[12:15]
	v_mfma_f32_16x16x32_bf16 v[8:11], v[232:235], v[168:171], v[8:11]
	v_mfma_f32_16x16x32_bf16 v[54:57], v[188:191], v[172:175], 0
	v_mfma_f32_16x16x32_bf16 v[50:53], v[188:191], v[180:183], 0
	v_mfma_f32_16x16x32_bf16 v[38:41], v[196:199], v[172:175], 0
	v_mfma_f32_16x16x32_bf16 v[34:37], v[196:199], v[180:183], 0
	v_mfma_f32_16x16x32_bf16 v[20:23], v[220:223], v[172:175], 0
	v_mfma_f32_16x16x32_bf16 v[16:19], v[220:223], v[180:183], 0
	v_mfma_f32_16x16x32_bf16 v[4:7], v[228:231], v[172:175], 0
	v_mfma_f32_16x16x32_bf16 v[0:3], v[228:231], v[180:183], 0
	v_mfma_f32_16x16x32_bf16 v[54:57], v[192:195], v[176:179], v[54:57]
	v_mfma_f32_16x16x32_bf16 v[50:53], v[192:195], v[184:187], v[50:53]
	v_mfma_f32_16x16x32_bf16 v[38:41], v[216:219], v[176:179], v[38:41]
	v_mfma_f32_16x16x32_bf16 v[34:37], v[216:219], v[184:187], v[34:37]
	v_mfma_f32_16x16x32_bf16 v[20:23], v[224:227], v[176:179], v[20:23]
	v_mfma_f32_16x16x32_bf16 v[16:19], v[224:227], v[184:187], v[16:19]
	v_mfma_f32_16x16x32_bf16 v[4:7], v[232:235], v[176:179], v[4:7]
	v_mfma_f32_16x16x32_bf16 v[0:3], v[232:235], v[184:187], v[0:3]
	s_setprio 0
	s_barrier
	s_branch .Lp3_1004
; #define PG8_STAGE(bufoff, gbase, voff) do { _Pragma("unroll") for (int _i = 0; _i < 2; ++_i) \
;         __builtin_amdgcn_global_load_lds((const unsigned*)((const char*)(gbase) + (voff)[_i]), (PG8_LAS unsigned*)(lds + (bufoff) + ldsw + _i * 8192), 16, 0, 0); } while (0)
; #define PG8_LDA(dst, b, h) do { _Pragma("unroll") for (int m = 0; m < 4; ++m) _Pragma("unroll") for (int k = 0; k < 2; ++k) dst[m][k] = *(const PG8_LAS bf16x8*)(lds + PG8_SA(b, h) + aoff + m * 2048 + k * 1024); } while (0)
; #define PG8_LDB(dst, b, h) do { _Pragma("unroll") for (int n = 0; n < 2; ++n) _Pragma("unroll") for (int k = 0; k < 2; ++k) dst[n][k] = *(const PG8_LAS bf16x8*)(lds + PG8_SB(b, h) + boff + n * 2048 + k * 1024); } while (0)
; #define PG8_WAIT_V(n) asm volatile("s_waitcnt vmcnt(" #n ")" ::: "memory")
; #define PG8_WAIT_L(n) asm volatile("s_waitcnt lgkmcnt(" #n ")" ::: "memory")
; #define PG8_BAR __builtin_amdgcn_s_barrier()
; #define PG8_SCHED __builtin_amdgcn_sched_barrier(0)
; template <class Epi, bool ALIGN_EPI = true>
; __device__ __forceinline__ void gemm_phase(PG8_LAS unsigned char* lds, const Gemm g, const StaticOrder& S, const Epi& E) {
;     ...
;             PG8_LDB(B0, 0, 0); PG8_LDB(B1, 0, 1); PG8_SCHED; PG8_LDA(At, 0, 0); PG8_STAGE(PG8_SA(1, 1), a1 + hstepA, voffA);
;             PG8_WAIT_V(8); PG8_WAIT_L(0); PG8_BAR; PG8_MMA(0, 0, At, B0); PG8_MMA(0, 1, At, B1); PG8_BAR; PG8_SCHED;
;             PG8_LDA(At, 0, 1); PG8_STAGE(PG8_SB(0, 0), b2, voffB); PG8_STAGE(PG8_SB(0, 1), b2 + hstepB, voffB); PG8_STAGE(PG8_SA(0, 0), a2, voffA);
;             PG8_WAIT_V(8); PG8_WAIT_L(0); PG8_BAR; PG8_MMA(1, 0, At, B0); PG8_MMA(1, 1, At, B1); PG8_BAR; PG8_SCHED;
.Lrot_1004:
	ds_read_b128 v[130:133], v32
	ds_read_b128 v[134:137], v32 offset:1024
	ds_read_b128 v[164:167], v32 offset:2048
	ds_read_b128 v[168:171], v32 offset:3072
	v_add_u32_e32 v32, s52, v143
	ds_read_b128 v[172:175], v32
	ds_read_b128 v[176:179], v32 offset:1024
	ds_read_b128 v[180:183], v32 offset:2048
	ds_read_b128 v[184:187], v32 offset:3072
	v_lshl_add_u64 v[146:147], s[20:21], 0, v[158:159]
	s_add_i32 m0, s35, 0xc000
	ds_read_b128 v[188:191], v163
	ds_read_b128 v[192:195], v163 offset:1024
	ds_read_b128 v[196:199], v163 offset:2048
	ds_read_b128 v[216:219], v163 offset:3072
	ds_read_b128 v[220:223], v163 offset:4096
	ds_read_b128 v[224:227], v163 offset:5120
	ds_read_b128 v[228:231], v163 offset:6144
	ds_read_b128 v[232:235], v163 offset:7168
	global_load_lds_dwordx4 v[146:147], off
	v_lshl_add_u64 v[146:147], s[20:21], 0, v[160:161]
	s_add_i32 m0, s35, 0xe000
	s_nop 0
	global_load_lds_dwordx4 v[146:147], off
	s_waitcnt vmcnt(8)
	s_waitcnt lgkmcnt(0)
	s_barrier
	s_setprio 1
	v_mfma_f32_16x16x32_bf16 v[126:129], v[188:191], v[130:133], v[126:129]
	v_mfma_f32_16x16x32_bf16 v[122:125], v[188:191], v[164:167], v[122:125]
	v_mfma_f32_16x16x32_bf16 v[110:113], v[196:199], v[130:133], v[110:113]
	v_mfma_f32_16x16x32_bf16 v[106:109], v[196:199], v[164:167], v[106:109]
	v_mfma_f32_16x16x32_bf16 v[94:97], v[220:223], v[130:133], v[94:97]
	v_mfma_f32_16x16x32_bf16 v[90:93], v[220:223], v[164:167], v[90:93]
	v_mfma_f32_16x16x32_bf16 v[78:81], v[228:231], v[130:133], v[78:81]
	v_mfma_f32_16x16x32_bf16 v[74:77], v[228:231], v[164:167], v[74:77]
	v_mfma_f32_16x16x32_bf16 v[126:129], v[192:195], v[134:137], v[126:129]
	v_mfma_f32_16x16x32_bf16 v[122:125], v[192:195], v[168:171], v[122:125]
	v_mfma_f32_16x16x32_bf16 v[110:113], v[216:219], v[134:137], v[110:113]
	v_mfma_f32_16x16x32_bf16 v[106:109], v[216:219], v[168:171], v[106:109]
	v_mfma_f32_16x16x32_bf16 v[94:97], v[224:227], v[134:137], v[94:97]
	v_mfma_f32_16x16x32_bf16 v[90:93], v[224:227], v[168:171], v[90:93]
	v_mfma_f32_16x16x32_bf16 v[78:81], v[232:235], v[134:137], v[78:81]
	v_mfma_f32_16x16x32_bf16 v[74:77], v[232:235], v[168:171], v[74:77]
	v_mfma_f32_16x16x32_bf16 v[118:121], v[188:191], v[172:175], v[118:121]
	v_mfma_f32_16x16x32_bf16 v[114:117], v[188:191], v[180:183], v[114:117]
	v_mfma_f32_16x16x32_bf16 v[102:105], v[196:199], v[172:175], v[102:105]
	v_mfma_f32_16x16x32_bf16 v[98:101], v[196:199], v[180:183], v[98:101]
	v_mfma_f32_16x16x32_bf16 v[86:89], v[220:223], v[172:175], v[86:89]
	v_mfma_f32_16x16x32_bf16 v[82:85], v[220:223], v[180:183], v[82:85]
	v_mfma_f32_16x16x32_bf16 v[70:73], v[228:231], v[172:175], v[70:73]
	v_mfma_f32_16x16x32_bf16 v[66:69], v[228:231], v[180:183], v[66:69]
	v_mfma_f32_16x16x32_bf16 v[118:121], v[192:195], v[176:179], v[118:121]
	v_mfma_f32_16x16x32_bf16 v[114:117], v[192:195], v[184:187], v[114:117]
	v_mfma_f32_16x16x32_bf16 v[102:105], v[216:219], v[176:179], v[102:105]
	v_mfma_f32_16x16x32_bf16 v[98:101], v[216:219], v[184:187], v[98:101]
	v_mfma_f32_16x16x32_bf16 v[86:89], v[224:227], v[176:179], v[86:89]
	v_mfma_f32_16x16x32_bf16 v[82:85], v[224:227], v[184:187], v[82:85]
	v_mfma_f32_16x16x32_bf16 v[70:73], v[232:235], v[176:179], v[70:73]
	v_mfma_f32_16x16x32_bf16 v[66:69], v[232:235], v[184:187], v[66:69]
	s_setprio 0
	s_barrier
	s_add_i32 s50, s50, s34
	v_lshl_add_u64 v[146:147], s[22:23], 0, v[138:139]
	s_mov_b32 m0, s50
	ds_read_b128 v[188:191], v163 offset:16384
	ds_read_b128 v[192:195], v163 offset:17408
	ds_read_b128 v[196:199], v163 offset:18432
	ds_read_b128 v[216:219], v163 offset:19456
	ds_read_b128 v[220:223], v163 offset:20480
	ds_read_b128 v[224:227], v163 offset:21504
	ds_read_b128 v[228:231], v163 offset:22528
	ds_read_b128 v[232:235], v163 offset:23552
	global_load_lds_dwordx4 v[146:147], off
	s_add_i32 m0, s50, 0x2000
	s_add_u32 s50, s22, 0x40000
	v_lshl_add_u64 v[148:149], s[22:23], 0, v[140:141]
	s_addc_u32 s51, s23, 0
	s_add_i32 s52, s52, s34
	global_load_lds_dwordx4 v[148:149], off
	v_lshl_add_u64 v[150:151], s[50:51], 0, v[138:139]
	s_mov_b32 m0, s52
	v_lshl_add_u64 v[200:201], s[24:25], 0, v[140:141]
	global_load_lds_dwordx4 v[150:151], off
	v_lshl_add_u64 v[150:151], s[50:51], 0, v[140:141]
	s_add_i32 m0, s52, 0x2000
	s_nop 0
	global_load_lds_dwordx4 v[150:151], off
	v_lshl_add_u64 v[150:151], s[24:25], 0, v[138:139]
	s_mov_b32 m0, s35
	s_nop 0
	global_load_lds_dwordx4 v[150:151], off
	s_mov_b32 m0, s36
	s_nop 0
	global_load_lds_dwordx4 v[200:201], off
	s_waitcnt vmcnt(8)
	s_waitcnt lgkmcnt(0)
	s_barrier
	s_setprio 1
	v_mfma_f32_16x16x32_bf16 v[62:65], v[188:191], v[130:133], v[62:65]
	v_mfma_f32_16x16x32_bf16 v[58:61], v[188:191], v[164:167], v[58:61]
	v_mfma_f32_16x16x32_bf16 v[46:49], v[196:199], v[130:133], v[46:49]
	v_mfma_f32_16x16x32_bf16 v[42:45], v[196:199], v[164:167], v[42:45]
	v_mfma_f32_16x16x32_bf16 v[28:31], v[220:223], v[130:133], v[28:31]
	v_mfma_f32_16x16x32_bf16 v[24:27], v[220:223], v[164:167], v[24:27]
	v_mfma_f32_16x16x32_bf16 v[12:15], v[228:231], v[130:133], v[12:15]
	v_mfma_f32_16x16x32_bf16 v[8:11], v[228:231], v[164:167], v[8:11]
	v_mfma_f32_16x16x32_bf16 v[62:65], v[192:195], v[134:137], v[62:65]
	v_mfma_f32_16x16x32_bf16 v[58:61], v[192:195], v[168:171], v[58:61]
	v_mfma_f32_16x16x32_bf16 v[46:49], v[216:219], v[134:137], v[46:49]
	v_mfma_f32_16x16x32_bf16 v[42:45], v[216:219], v[168:171], v[42:45]
	v_mfma_f32_16x16x32_bf16 v[28:31], v[224:227], v[134:137], v[28:31]
	v_mfma_f32_16x16x32_bf16 v[24:27], v[224:227], v[168:171], v[24:27]
	v_mfma_f32_16x16x32_bf16 v[12:15], v[232:235], v[134:137], v[12:15]
	v_mfma_f32_16x16x32_bf16 v[8:11], v[232:235], v[168:171], v[8:11]
	v_mfma_f32_16x16x32_bf16 v[54:57], v[188:191], v[172:175], v[54:57]
	v_mfma_f32_16x16x32_bf16 v[50:53], v[188:191], v[180:183], v[50:53]
	v_mfma_f32_16x16x32_bf16 v[38:41], v[196:199], v[172:175], v[38:41]
	v_mfma_f32_16x16x32_bf16 v[34:37], v[196:199], v[180:183], v[34:37]
	v_mfma_f32_16x16x32_bf16 v[20:23], v[220:223], v[172:175], v[20:23]
	v_mfma_f32_16x16x32_bf16 v[16:19], v[220:223], v[180:183], v[16:19]
	v_mfma_f32_16x16x32_bf16 v[4:7], v[228:231], v[172:175], v[4:7]
	v_mfma_f32_16x16x32_bf16 v[0:3], v[228:231], v[180:183], v[0:3]
	v_mfma_f32_16x16x32_bf16 v[54:57], v[192:195], v[176:179], v[54:57]
	v_mfma_f32_16x16x32_bf16 v[50:53], v[192:195], v[184:187], v[50:53]
	v_mfma_f32_16x16x32_bf16 v[38:41], v[216:219], v[176:179], v[38:41]
	v_mfma_f32_16x16x32_bf16 v[34:37], v[216:219], v[184:187], v[34:37]
	v_mfma_f32_16x16x32_bf16 v[20:23], v[224:227], v[176:179], v[20:23]
	v_mfma_f32_16x16x32_bf16 v[16:19], v[224:227], v[184:187], v[16:19]
	v_mfma_f32_16x16x32_bf16 v[4:7], v[232:235], v[176:179], v[4:7]
	v_mfma_f32_16x16x32_bf16 v[0:3], v[232:235], v[184:187], v[0:3]
	s_setprio 0
	s_barrier
; #define PG8_STAGE(bufoff, gbase, voff) do { _Pragma("unroll") for (int _i = 0; _i < 2; ++_i) \
;         __builtin_amdgcn_global_load_lds((const unsigned*)((const char*)(gbase) + (voff)[_i]), (PG8_LAS unsigned*)(lds + (bufoff) + ldsw + _i * 8192), 16, 0, 0); } while (0)
; #define PG8_LDA(dst, b, h) do { _Pragma("unroll") for (int m = 0; m < 4; ++m) _Pragma("unroll") for (int k = 0; k < 2; ++k) dst[m][k] = *(const PG8_LAS bf16x8*)(lds + PG8_SA(b, h) + aoff + m * 2048 + k * 1024); } while (0)
; #define PG8_LDB(dst, b, h) do { _Pragma("unroll") for (int n = 0; n < 2; ++n) _Pragma("unroll") for (int k = 0; k < 2; ++k) dst[n][k] = *(const PG8_LAS bf16x8*)(lds + PG8_SB(b, h) + boff + n * 2048 + k * 1024); } while (0)
; #define PG8_WAIT_V(n) asm volatile("s_waitcnt vmcnt(" #n ")" ::: "memory")
; #define PG8_WAIT_L(n) asm volatile("s_waitcnt lgkmcnt(" #n ")" ::: "memory")
; #define PG8_BAR __builtin_amdgcn_s_barrier()
; #define PG8_SCHED __builtin_amdgcn_sched_barrier(0)
; template <class Epi, bool ALIGN_EPI = true>
; __device__ __forceinline__ void gemm_phase(PG8_LAS unsigned char* lds, const Gemm g, const StaticOrder& S, const Epi& E) {
;     ...
;             PG8_LDB(B0, 1, 0); PG8_LDB(B1, 1, 1); PG8_SCHED; PG8_LDA(At, 1, 0); PG8_STAGE(PG8_SA(0, 1), a2 + hstepA, voffA);
;             PG8_WAIT_V(8); PG8_WAIT_L(0); PG8_BAR; PG8_MMA(0, 0, At, B0); PG8_MMA(0, 1, At, B1); PG8_BAR; PG8_SCHED;
.Lp3_1004:
	s_add_i32 s50, 0, 0x18000
	v_add_u32_e32 v32, s50, v143
	s_add_i32 s51, 0, 0x1c000
	ds_read_b128 v[130:133], v32
	ds_read_b128 v[134:137], v32 offset:1024
	ds_read_b128 v[164:167], v32 offset:2048
	ds_read_b128 v[168:171], v32 offset:3072
	v_add_u32_e32 v32, s51, v143
	ds_read_b128 v[172:175], v32
	ds_read_b128 v[176:179], v32 offset:1024
	ds_read_b128 v[180:183], v32 offset:2048
	ds_read_b128 v[184:187], v32 offset:3072
	s_add_u32 s24, s24, 0x40000
	s_addc_u32 s25, s25, 0
	s_mov_b32 m0, s37
	v_lshl_add_u64 v[204:205], s[24:25], 0, v[138:139]
	ds_read_b128 v[188:191], v163 offset:32768
	ds_read_b128 v[192:195], v163 offset:33792
	ds_read_b128 v[196:199], v163 offset:34816
	ds_read_b128 v[216:219], v163 offset:35840
	ds_read_b128 v[220:223], v163 offset:36864
	ds_read_b128 v[224:227], v163 offset:37888
	ds_read_b128 v[228:231], v163 offset:38912
	ds_read_b128 v[232:235], v163 offset:39936
	global_load_lds_dwordx4 v[204:205], off
	v_lshl_add_u64 v[204:205], s[24:25], 0, v[140:141]
	s_mov_b32 m0, s38
	s_nop 0
	global_load_lds_dwordx4 v[204:205], off
	s_waitcnt vmcnt(8)
	s_waitcnt lgkmcnt(0)
	s_barrier
	s_setprio 1
	v_mfma_f32_16x16x32_bf16 v[126:129], v[188:191], v[130:133], v[126:129]
	v_mfma_f32_16x16x32_bf16 v[122:125], v[188:191], v[164:167], v[122:125]
	v_mfma_f32_16x16x32_bf16 v[110:113], v[196:199], v[130:133], v[110:113]
	v_mfma_f32_16x16x32_bf16 v[106:109], v[196:199], v[164:167], v[106:109]
	v_mfma_f32_16x16x32_bf16 v[94:97], v[220:223], v[130:133], v[94:97]
	v_mfma_f32_16x16x32_bf16 v[90:93], v[220:223], v[164:167], v[90:93]
	v_mfma_f32_16x16x32_bf16 v[78:81], v[228:231], v[130:133], v[78:81]
	v_mfma_f32_16x16x32_bf16 v[74:77], v[228:231], v[164:167], v[74:77]
	v_mfma_f32_16x16x32_bf16 v[126:129], v[192:195], v[134:137], v[126:129]
	v_mfma_f32_16x16x32_bf16 v[122:125], v[192:195], v[168:171], v[122:125]
	v_mfma_f32_16x16x32_bf16 v[110:113], v[216:219], v[134:137], v[110:113]
	v_mfma_f32_16x16x32_bf16 v[106:109], v[216:219], v[168:171], v[106:109]
	v_mfma_f32_16x16x32_bf16 v[94:97], v[224:227], v[134:137], v[94:97]
	v_mfma_f32_16x16x32_bf16 v[90:93], v[224:227], v[168:171], v[90:93]
	v_mfma_f32_16x16x32_bf16 v[78:81], v[232:235], v[134:137], v[78:81]
	v_mfma_f32_16x16x32_bf16 v[74:77], v[232:235], v[168:171], v[74:77]
	v_mfma_f32_16x16x32_bf16 v[118:121], v[188:191], v[172:175], v[118:121]
	v_mfma_f32_16x16x32_bf16 v[114:117], v[188:191], v[180:183], v[114:117]
	v_mfma_f32_16x16x32_bf16 v[102:105], v[196:199], v[172:175], v[102:105]
	v_mfma_f32_16x16x32_bf16 v[98:101], v[196:199], v[180:183], v[98:101]
	v_mfma_f32_16x16x32_bf16 v[86:89], v[220:223], v[172:175], v[86:89]
	v_mfma_f32_16x16x32_bf16 v[82:85], v[220:223], v[180:183], v[82:85]
	v_mfma_f32_16x16x32_bf16 v[70:73], v[228:231], v[172:175], v[70:73]
	v_mfma_f32_16x16x32_bf16 v[66:69], v[228:231], v[180:183], v[66:69]
	v_mfma_f32_16x16x32_bf16 v[118:121], v[192:195], v[176:179], v[118:121]
	v_mfma_f32_16x16x32_bf16 v[114:117], v[192:195], v[184:187], v[114:117]
	v_mfma_f32_16x16x32_bf16 v[102:105], v[216:219], v[176:179], v[102:105]
	v_mfma_f32_16x16x32_bf16 v[98:101], v[216:219], v[184:187], v[98:101]
	v_mfma_f32_16x16x32_bf16 v[86:89], v[224:227], v[176:179], v[86:89]
	v_mfma_f32_16x16x32_bf16 v[82:85], v[224:227], v[184:187], v[82:85]
	v_mfma_f32_16x16x32_bf16 v[70:73], v[232:235], v[176:179], v[70:73]
	v_mfma_f32_16x16x32_bf16 v[66:69], v[232:235], v[184:187], v[66:69]
	s_setprio 0
	s_barrier
; #define PG8_STAGE(bufoff, gbase, voff) do { _Pragma("unroll") for (int _i = 0; _i < 2; ++_i) \
;         __builtin_amdgcn_global_load_lds((const unsigned*)((const char*)(gbase) + (voff)[_i]), (PG8_LAS unsigned*)(lds + (bufoff) + ldsw + _i * 8192), 16, 0, 0); } while (0)
; #define PG8_LDA(dst, b, h) do { _Pragma("unroll") for (int m = 0; m < 4; ++m) _Pragma("unroll") for (int k = 0; k < 2; ++k) dst[m][k] = *(const PG8_LAS bf16x8*)(lds + PG8_SA(b, h) + aoff + m * 2048 + k * 1024); } while (0)
; #define PG8_WAIT_V(n) asm volatile("s_waitcnt vmcnt(" #n ")" ::: "memory")
; #define PG8_WAIT_L(n) asm volatile("s_waitcnt lgkmcnt(" #n ")" ::: "memory")
; #define PG8_BAR __builtin_amdgcn_s_barrier()
; #define PG8_SCHED __builtin_amdgcn_sched_barrier(0)
; template <class Epi, bool ALIGN_EPI = true>
; __device__ __forceinline__ void gemm_phase(PG8_LAS unsigned char* lds, const Gemm g, const StaticOrder& S, const Epi& E) {
;     ...
;         for (int t = 0; t < nt; t += 2) {
;             const bool last = (t == nt - 2);
;             const char* a1 = cA + (size_t)(t + 1) * kstep;
;             const char* a2 = last ? nA : cA + (size_t)(t + 2) * kstep; const char* b2 = last ? nB : cB + (size_t)(t + 2) * kstep;
;     ...
;             PG8_LDA(At, 1, 1); PG8_STAGE(PG8_SB(1, 0), b3, voffB); PG8_STAGE(PG8_SB(1, 1), b3 + hstepB, voffB); PG8_STAGE(PG8_SA(1, 0), a3, voffA);
;             PG8_WAIT_V(8); PG8_WAIT_L(0); PG8_BAR; PG8_MMA(1, 0, At, B0); PG8_MMA(1, 1, At, B1); PG8_BAR; PG8_SCHED;
	s_add_i32 s24, s50, s34
	v_lshl_add_u64 v[146:147], v[146:147], 0, s[60:61]
	s_mov_b32 m0, s24
	ds_read_b128 v[188:191], v163 offset:49152
	ds_read_b128 v[192:195], v163 offset:50176
	ds_read_b128 v[196:199], v163 offset:51200
	ds_read_b128 v[216:219], v163 offset:52224
	ds_read_b128 v[220:223], v163 offset:53248
	ds_read_b128 v[224:227], v163 offset:54272
	ds_read_b128 v[228:231], v163 offset:55296
	ds_read_b128 v[232:235], v163 offset:56320
	global_load_lds_dwordx4 v[146:147], off
	s_add_i32 m0, s24, 0x2000
	s_add_u32 s22, s22, 0x40080
	v_lshl_add_u64 v[146:147], v[148:149], 0, s[60:61]
	s_addc_u32 s23, s23, 0
	s_add_i32 s24, s51, s34
	global_load_lds_dwordx4 v[146:147], off
	v_lshl_add_u64 v[146:147], s[22:23], 0, v[138:139]
	s_mov_b32 m0, s24
	s_nop 0
	global_load_lds_dwordx4 v[146:147], off
	v_lshl_add_u64 v[146:147], s[22:23], 0, v[140:141]
	s_add_i32 m0, s24, 0x2000
	s_nop 0
	global_load_lds_dwordx4 v[146:147], off
	v_lshl_add_u64 v[146:147], v[150:151], 0, s[60:61]
	s_mov_b32 m0, s42
	s_nop 0
	global_load_lds_dwordx4 v[146:147], off
	v_lshl_add_u64 v[146:147], v[200:201], 0, s[60:61]
	s_mov_b32 m0, s43
	s_nop 0
	global_load_lds_dwordx4 v[146:147], off
	s_add_i32 s49, s49, 2
	s_add_u32 s20, s20, 0x100
	s_addc_u32 s21, s21, 0
	s_add_u32 s47, s47, 0x100
	s_addc_u32 s48, s48, 0
	s_add_u32 s22, s20, 0xfffc0080
	s_addc_u32 s23, s21, -1
	s_add_i32 s50, 0, 0x10000
	s_cmp_eq_u32 s49, 12
	s_cselect_b32 s25, s11, s23
	s_cselect_b32 s24, s17, s22
	v_add_u32_e32 v32, s50, v143
	s_cselect_b32 s23, s9, s48
	s_cselect_b32 s22, s19, s47
	s_add_i32 s52, 0, 0x14000
	s_cmp_gt_u32 s49, 13
	s_waitcnt vmcnt(8)
	s_waitcnt lgkmcnt(0)
	s_barrier
	s_setprio 1
	v_mfma_f32_16x16x32_bf16 v[62:65], v[188:191], v[130:133], v[62:65]
	v_mfma_f32_16x16x32_bf16 v[58:61], v[188:191], v[164:167], v[58:61]
	v_mfma_f32_16x16x32_bf16 v[46:49], v[196:199], v[130:133], v[46:49]
	v_mfma_f32_16x16x32_bf16 v[42:45], v[196:199], v[164:167], v[42:45]
	v_mfma_f32_16x16x32_bf16 v[28:31], v[220:223], v[130:133], v[28:31]
	v_mfma_f32_16x16x32_bf16 v[24:27], v[220:223], v[164:167], v[24:27]
	v_mfma_f32_16x16x32_bf16 v[12:15], v[228:231], v[130:133], v[12:15]
	v_mfma_f32_16x16x32_bf16 v[8:11], v[228:231], v[164:167], v[8:11]
	v_mfma_f32_16x16x32_bf16 v[62:65], v[192:195], v[134:137], v[62:65]
	v_mfma_f32_16x16x32_bf16 v[58:61], v[192:195], v[168:171], v[58:61]
	v_mfma_f32_16x16x32_bf16 v[46:49], v[216:219], v[134:137], v[46:49]
	v_mfma_f32_16x16x32_bf16 v[42:45], v[216:219], v[168:171], v[42:45]
	v_mfma_f32_16x16x32_bf16 v[28:31], v[224:227], v[134:137], v[28:31]
	v_mfma_f32_16x16x32_bf16 v[24:27], v[224:227], v[168:171], v[24:27]
	v_mfma_f32_16x16x32_bf16 v[12:15], v[232:235], v[134:137], v[12:15]
	v_mfma_f32_16x16x32_bf16 v[8:11], v[232:235], v[168:171], v[8:11]
	v_mfma_f32_16x16x32_bf16 v[54:57], v[188:191], v[172:175], v[54:57]
	v_mfma_f32_16x16x32_bf16 v[50:53], v[188:191], v[180:183], v[50:53]
	v_mfma_f32_16x16x32_bf16 v[38:41], v[196:199], v[172:175], v[38:41]
	v_mfma_f32_16x16x32_bf16 v[34:37], v[196:199], v[180:183], v[34:37]
	v_mfma_f32_16x16x32_bf16 v[20:23], v[220:223], v[172:175], v[20:23]
	v_mfma_f32_16x16x32_bf16 v[16:19], v[220:223], v[180:183], v[16:19]
	v_mfma_f32_16x16x32_bf16 v[4:7], v[228:231], v[172:175], v[4:7]
	v_mfma_f32_16x16x32_bf16 v[0:3], v[228:231], v[180:183], v[0:3]
	v_mfma_f32_16x16x32_bf16 v[54:57], v[192:195], v[176:179], v[54:57]
	v_mfma_f32_16x16x32_bf16 v[50:53], v[192:195], v[184:187], v[50:53]
	v_mfma_f32_16x16x32_bf16 v[38:41], v[216:219], v[176:179], v[38:41]
	v_mfma_f32_16x16x32_bf16 v[34:37], v[216:219], v[184:187], v[34:37]
	v_mfma_f32_16x16x32_bf16 v[20:23], v[224:227], v[176:179], v[20:23]
	v_mfma_f32_16x16x32_bf16 v[16:19], v[224:227], v[184:187], v[16:19]
	v_mfma_f32_16x16x32_bf16 v[4:7], v[232:235], v[176:179], v[4:7]
	v_mfma_f32_16x16x32_bf16 v[0:3], v[232:235], v[184:187], v[0:3]
	s_setprio 0
	s_barrier
	s_cbranch_scc0 .Lrot_1004
	s_and_b64 vcc, exec, s[6:7]
	s_cbranch_vccz .LBB0_1007
	s_barrier

; #define PG8_STAGE(bufoff, gbase, voff) do { _Pragma("unroll") for (int _i = 0; _i < 2; ++_i) \
;         __builtin_amdgcn_global_load_lds((const unsigned*)((const char*)(gbase) + (voff)[_i]), (PG8_LAS unsigned*)(lds + (bufoff) + ldsw + _i * 8192), 16, 0, 0); } while (0)
; #define PG8_LDA(dst, b, h) do { _Pragma("unroll") for (int m = 0; m < 4; ++m) _Pragma("unroll") for (int k = 0; k < 2; ++k) dst[m][k] = *(const PG8_LAS bf16x8*)(lds + PG8_SA(b, h) + aoff + m * 2048 + k * 1024); } while (0)
; #define PG8_LDB(dst, b, h) do { _Pragma("unroll") for (int n = 0; n < 2; ++n) _Pragma("unroll") for (int k = 0; k < 2; ++k) dst[n][k] = *(const PG8_LAS bf16x8*)(lds + PG8_SB(b, h) + boff + n * 2048 + k * 1024); } while (0)
; #define PG8_WAIT_V(n) asm volatile("s_waitcnt vmcnt(" #n ")" ::: "memory")
; #define PG8_WAIT_L(n) asm volatile("s_waitcnt lgkmcnt(" #n ")" ::: "memory")
; #define PG8_BAR __builtin_amdgcn_s_barrier()
; #define PG8_SCHED __builtin_amdgcn_sched_barrier(0)
; template <class Epi, bool ALIGN_EPI = true>
; __device__ __forceinline__ void gemm_phase(PG8_LAS unsigned char* lds, const Gemm g, const StaticOrder& S, const Epi& E) {
;     ...
;             PG8_LDB(B0, 0, 0); PG8_LDB(B1, 0, 1); PG8_SCHED; PG8_LDA(At, 0, 0); PG8_STAGE(PG8_SA(1, 1), a1 + hstepA, voffA);
;             PG8_WAIT_V(8); PG8_WAIT_L(0); PG8_BAR; PG8_MMA(0, 0, At, B0); PG8_MMA(0, 1, At, B1); PG8_BAR; PG8_SCHED;
;             PG8_LDA(At, 0, 1); PG8_STAGE(PG8_SB(0, 0), b2, voffB); PG8_STAGE(PG8_SB(0, 1), b2 + hstepB, voffB); PG8_STAGE(PG8_SA(0, 0), a2, voffA);
;             PG8_WAIT_V(8); PG8_WAIT_L(0); PG8_BAR; PG8_MMA(1, 0, At, B0); PG8_MMA(1, 1, At, B1); PG8_BAR; PG8_SCHED;
.LBB0_1829:
	s_add_u32 s43, s6, 0xfffc0080
	s_addc_u32 s44, s7, -1
	s_add_i32 s75, 0, 0x10000
	s_cmp_eq_u32 s37, 12
	s_cselect_b32 s47, s39, s44
	s_cselect_b32 s46, s38, s43
	v_add_u32_e32 v32, s75, v165
	s_cselect_b32 s45, s41, s35
	s_cselect_b32 s44, s40, s9
	s_add_i32 s43, 0, 0x14000
	ds_read_b128 v[142:145], v32
	ds_read_b128 v[148:151], v32 offset:1024
	ds_read_b128 v[158:161], v32 offset:2048
	ds_read_b128 v[168:171], v32 offset:3072
	v_add_u32_e32 v32, s43, v165
	ds_read_b128 v[172:175], v32
	ds_read_b128 v[176:179], v32 offset:1024
	ds_read_b128 v[180:183], v32 offset:2048
	ds_read_b128 v[184:187], v32 offset:3072
	v_lshl_add_u64 v[146:147], s[6:7], 0, v[138:139]
	s_add_i32 m0, s59, 0xc000
	ds_read_b128 v[188:191], v167
	ds_read_b128 v[192:195], v167 offset:1024
	ds_read_b128 v[196:199], v167 offset:2048
	ds_read_b128 v[208:211], v167 offset:3072
	ds_read_b128 v[216:219], v167 offset:4096
	ds_read_b128 v[220:223], v167 offset:5120
	ds_read_b128 v[224:227], v167 offset:6144
	ds_read_b128 v[228:231], v167 offset:7168
	global_load_lds_dwordx4 v[146:147], off
	v_lshl_add_u64 v[146:147], s[6:7], 0, v[140:141]
	s_add_i32 m0, s59, 0xe000
	s_nop 0
	global_load_lds_dwordx4 v[146:147], off
	s_waitcnt vmcnt(8)
	s_waitcnt lgkmcnt(0)
	s_barrier
	s_setprio 1
	v_mfma_f32_16x16x32_bf16 v[126:129], v[142:145], v[188:191], 0
	v_mfma_f32_16x16x32_bf16 v[122:125], v[158:161], v[188:191], 0
	v_mfma_f32_16x16x32_bf16 v[110:113], v[142:145], v[196:199], 0
	v_mfma_f32_16x16x32_bf16 v[106:109], v[158:161], v[196:199], 0
	v_mfma_f32_16x16x32_bf16 v[94:97], v[142:145], v[216:219], 0
	v_mfma_f32_16x16x32_bf16 v[90:93], v[158:161], v[216:219], 0
	v_mfma_f32_16x16x32_bf16 v[78:81], v[142:145], v[224:227], 0
	v_mfma_f32_16x16x32_bf16 v[74:77], v[158:161], v[224:227], 0
	v_mfma_f32_16x16x32_bf16 v[126:129], v[148:151], v[192:195], v[126:129]
	v_mfma_f32_16x16x32_bf16 v[122:125], v[168:171], v[192:195], v[122:125]
	v_mfma_f32_16x16x32_bf16 v[110:113], v[148:151], v[208:211], v[110:113]
	v_mfma_f32_16x16x32_bf16 v[106:109], v[168:171], v[208:211], v[106:109]
	v_mfma_f32_16x16x32_bf16 v[94:97], v[148:151], v[220:223], v[94:97]
	v_mfma_f32_16x16x32_bf16 v[90:93], v[168:171], v[220:223], v[90:93]
	v_mfma_f32_16x16x32_bf16 v[78:81], v[148:151], v[228:231], v[78:81]
	v_mfma_f32_16x16x32_bf16 v[74:77], v[168:171], v[228:231], v[74:77]
	v_mfma_f32_16x16x32_bf16 v[118:121], v[172:175], v[188:191], 0
	v_mfma_f32_16x16x32_bf16 v[114:117], v[180:183], v[188:191], 0
	v_mfma_f32_16x16x32_bf16 v[102:105], v[172:175], v[196:199], 0
	v_mfma_f32_16x16x32_bf16 v[98:101], v[180:183], v[196:199], 0
	v_mfma_f32_16x16x32_bf16 v[86:89], v[172:175], v[216:219], 0
	v_mfma_f32_16x16x32_bf16 v[82:85], v[180:183], v[216:219], 0
	v_mfma_f32_16x16x32_bf16 v[70:73], v[172:175], v[224:227], 0
	v_mfma_f32_16x16x32_bf16 v[66:69], v[180:183], v[224:227], 0
	v_mfma_f32_16x16x32_bf16 v[118:121], v[176:179], v[192:195], v[118:121]
	v_mfma_f32_16x16x32_bf16 v[114:117], v[184:187], v[192:195], v[114:117]
	v_mfma_f32_16x16x32_bf16 v[102:105], v[176:179], v[208:211], v[102:105]
	v_mfma_f32_16x16x32_bf16 v[98:101], v[184:187], v[208:211], v[98:101]
	v_mfma_f32_16x16x32_bf16 v[86:89], v[176:179], v[220:223], v[86:89]
	v_mfma_f32_16x16x32_bf16 v[82:85], v[184:187], v[220:223], v[82:85]
	v_mfma_f32_16x16x32_bf16 v[70:73], v[176:179], v[228:231], v[70:73]
	v_mfma_f32_16x16x32_bf16 v[66:69], v[184:187], v[228:231], v[66:69]
	s_setprio 0
	s_barrier
	s_add_i32 s75, s75, s53
	v_lshl_add_u64 v[146:147], s[44:45], 0, v[132:133]
	s_mov_b32 m0, s75
	ds_read_b128 v[188:191], v167 offset:16384
	ds_read_b128 v[192:195], v167 offset:17408
	ds_read_b128 v[196:199], v167 offset:18432
	ds_read_b128 v[208:211], v167 offset:19456
	ds_read_b128 v[216:219], v167 offset:20480
	ds_read_b128 v[220:223], v167 offset:21504
	ds_read_b128 v[224:227], v167 offset:22528
	ds_read_b128 v[228:231], v167 offset:23552
	global_load_lds_dwordx4 v[146:147], off
	s_add_i32 m0, s75, 0x2000
	s_add_u32 s76, s44, 0x40000
	v_lshl_add_u64 v[162:163], s[44:45], 0, v[136:137]
	s_addc_u32 s77, s45, 0
	s_add_i32 s43, s43, s53
	global_load_lds_dwordx4 v[162:163], off
	v_lshl_add_u64 v[200:201], s[76:77], 0, v[132:133]
	s_mov_b32 m0, s43
	v_lshl_add_u64 v[204:205], s[46:47], 0, v[134:135]
	global_load_lds_dwordx4 v[200:201], off
	v_lshl_add_u64 v[200:201], s[76:77], 0, v[136:137]
	s_add_i32 m0, s43, 0x2000
	s_nop 0
	global_load_lds_dwordx4 v[200:201], off
	v_lshl_add_u64 v[200:201], s[46:47], 0, v[130:131]
	s_mov_b32 m0, s59
	s_nop 0
	global_load_lds_dwordx4 v[200:201], off
	s_mov_b32 m0, s62
	s_nop 0
	global_load_lds_dwordx4 v[204:205], off
	s_waitcnt vmcnt(8)
	s_waitcnt lgkmcnt(0)
	s_barrier
	s_setprio 1
	v_mfma_f32_16x16x32_bf16 v[62:65], v[142:145], v[188:191], 0
	v_mfma_f32_16x16x32_bf16 v[58:61], v[158:161], v[188:191], 0
	v_mfma_f32_16x16x32_bf16 v[46:49], v[142:145], v[196:199], 0
	v_mfma_f32_16x16x32_bf16 v[42:45], v[158:161], v[196:199], 0
	v_mfma_f32_16x16x32_bf16 v[28:31], v[142:145], v[216:219], 0
	v_mfma_f32_16x16x32_bf16 v[24:27], v[158:161], v[216:219], 0
	v_mfma_f32_16x16x32_bf16 v[12:15], v[142:145], v[224:227], 0
	v_mfma_f32_16x16x32_bf16 v[8:11], v[158:161], v[224:227], 0
	v_mfma_f32_16x16x32_bf16 v[62:65], v[148:151], v[192:195], v[62:65]
	v_mfma_f32_16x16x32_bf16 v[58:61], v[168:171], v[192:195], v[58:61]
	v_mfma_f32_16x16x32_bf16 v[46:49], v[148:151], v[208:211], v[46:49]
	v_mfma_f32_16x16x32_bf16 v[42:45], v[168:171], v[208:211], v[42:45]
	v_mfma_f32_16x16x32_bf16 v[28:31], v[148:151], v[220:223], v[28:31]
	v_mfma_f32_16x16x32_bf16 v[24:27], v[168:171], v[220:223], v[24:27]
	v_mfma_f32_16x16x32_bf16 v[12:15], v[148:151], v[228:231], v[12:15]
	v_mfma_f32_16x16x32_bf16 v[8:11], v[168:171], v[228:231], v[8:11]
	v_mfma_f32_16x16x32_bf16 v[54:57], v[172:175], v[188:191], 0
	v_mfma_f32_16x16x32_bf16 v[50:53], v[180:183], v[188:191], 0
	v_mfma_f32_16x16x32_bf16 v[38:41], v[172:175], v[196:199], 0
	v_mfma_f32_16x16x32_bf16 v[34:37], v[180:183], v[196:199], 0
	v_mfma_f32_16x16x32_bf16 v[20:23], v[172:175], v[216:219], 0
	v_mfma_f32_16x16x32_bf16 v[16:19], v[180:183], v[216:219], 0
	v_mfma_f32_16x16x32_bf16 v[4:7], v[172:175], v[224:227], 0
	v_mfma_f32_16x16x32_bf16 v[0:3], v[180:183], v[224:227], 0
	v_mfma_f32_16x16x32_bf16 v[54:57], v[176:179], v[192:195], v[54:57]
	v_mfma_f32_16x16x32_bf16 v[50:53], v[184:187], v[192:195], v[50:53]
	v_mfma_f32_16x16x32_bf16 v[38:41], v[176:179], v[208:211], v[38:41]
	v_mfma_f32_16x16x32_bf16 v[34:37], v[184:187], v[208:211], v[34:37]
	v_mfma_f32_16x16x32_bf16 v[20:23], v[176:179], v[220:223], v[20:23]
	v_mfma_f32_16x16x32_bf16 v[16:19], v[184:187], v[220:223], v[16:19]
	v_mfma_f32_16x16x32_bf16 v[4:7], v[176:179], v[228:231], v[4:7]
	v_mfma_f32_16x16x32_bf16 v[0:3], v[184:187], v[228:231], v[0:3]
	s_setprio 0
	s_barrier
	s_branch .Lp3_1829
; #define PG8_STAGE(bufoff, gbase, voff) do { _Pragma("unroll") for (int _i = 0; _i < 2; ++_i) \
;         __builtin_amdgcn_global_load_lds((const unsigned*)((const char*)(gbase) + (voff)[_i]), (PG8_LAS unsigned*)(lds + (bufoff) + ldsw + _i * 8192), 16, 0, 0); } while (0)
; #define PG8_LDA(dst, b, h) do { _Pragma("unroll") for (int m = 0; m < 4; ++m) _Pragma("unroll") for (int k = 0; k < 2; ++k) dst[m][k] = *(const PG8_LAS bf16x8*)(lds + PG8_SA(b, h) + aoff + m * 2048 + k * 1024); } while (0)
; #define PG8_LDB(dst, b, h) do { _Pragma("unroll") for (int n = 0; n < 2; ++n) _Pragma("unroll") for (int k = 0; k < 2; ++k) dst[n][k] = *(const PG8_LAS bf16x8*)(lds + PG8_SB(b, h) + boff + n * 2048 + k * 1024); } while (0)
; #define PG8_WAIT_V(n) asm volatile("s_waitcnt vmcnt(" #n ")" ::: "memory")
; #define PG8_WAIT_L(n) asm volatile("s_waitcnt lgkmcnt(" #n ")" ::: "memory")
; #define PG8_BAR __builtin_amdgcn_s_barrier()
; #define PG8_SCHED __builtin_amdgcn_sched_barrier(0)
; template <class Epi, bool ALIGN_EPI = true>
; __device__ __forceinline__ void gemm_phase(PG8_LAS unsigned char* lds, const Gemm g, const StaticOrder& S, const Epi& E) {
;     ...
;             PG8_LDB(B0, 0, 0); PG8_LDB(B1, 0, 1); PG8_SCHED; PG8_LDA(At, 0, 0); PG8_STAGE(PG8_SA(1, 1), a1 + hstepA, voffA);
;             PG8_WAIT_V(8); PG8_WAIT_L(0); PG8_BAR; PG8_MMA(0, 0, At, B0); PG8_MMA(0, 1, At, B1); PG8_BAR; PG8_SCHED;
;             PG8_LDA(At, 0, 1); PG8_STAGE(PG8_SB(0, 0), b2, voffB); PG8_STAGE(PG8_SB(0, 1), b2 + hstepB, voffB); PG8_STAGE(PG8_SA(0, 0), a2, voffA);
;             PG8_WAIT_V(8); PG8_WAIT_L(0); PG8_BAR; PG8_MMA(1, 0, At, B0); PG8_MMA(1, 1, At, B1); PG8_BAR; PG8_SCHED;
.Lrot_1829:
	ds_read_b128 v[142:145], v32
	ds_read_b128 v[148:151], v32 offset:1024
	ds_read_b128 v[158:161], v32 offset:2048
	ds_read_b128 v[168:171], v32 offset:3072
	v_add_u32_e32 v32, s43, v165
	ds_read_b128 v[172:175], v32
	ds_read_b128 v[176:179], v32 offset:1024
	ds_read_b128 v[180:183], v32 offset:2048
	ds_read_b128 v[184:187], v32 offset:3072
	v_lshl_add_u64 v[146:147], s[6:7], 0, v[138:139]
	s_add_i32 m0, s59, 0xc000
	ds_read_b128 v[188:191], v167
	ds_read_b128 v[192:195], v167 offset:1024
	ds_read_b128 v[196:199], v167 offset:2048
	ds_read_b128 v[208:211], v167 offset:3072
	ds_read_b128 v[216:219], v167 offset:4096
	ds_read_b128 v[220:223], v167 offset:5120
	ds_read_b128 v[224:227], v167 offset:6144
	ds_read_b128 v[228:231], v167 offset:7168
	global_load_lds_dwordx4 v[146:147], off
	v_lshl_add_u64 v[146:147], s[6:7], 0, v[140:141]
	s_add_i32 m0, s59, 0xe000
	s_nop 0
	global_load_lds_dwordx4 v[146:147], off
	s_waitcnt vmcnt(8)
	s_waitcnt lgkmcnt(0)
	s_barrier
	s_setprio 1
	v_mfma_f32_16x16x32_bf16 v[126:129], v[142:145], v[188:191], v[126:129]
	v_mfma_f32_16x16x32_bf16 v[122:125], v[158:161], v[188:191], v[122:125]
	v_mfma_f32_16x16x32_bf16 v[110:113], v[142:145], v[196:199], v[110:113]
	v_mfma_f32_16x16x32_bf16 v[106:109], v[158:161], v[196:199], v[106:109]
	v_mfma_f32_16x16x32_bf16 v[94:97], v[142:145], v[216:219], v[94:97]
	v_mfma_f32_16x16x32_bf16 v[90:93], v[158:161], v[216:219], v[90:93]
	v_mfma_f32_16x16x32_bf16 v[78:81], v[142:145], v[224:227], v[78:81]
	v_mfma_f32_16x16x32_bf16 v[74:77], v[158:161], v[224:227], v[74:77]
	v_mfma_f32_16x16x32_bf16 v[126:129], v[148:151], v[192:195], v[126:129]
	v_mfma_f32_16x16x32_bf16 v[122:125], v[168:171], v[192:195], v[122:125]
	v_mfma_f32_16x16x32_bf16 v[110:113], v[148:151], v[208:211], v[110:113]
	v_mfma_f32_16x16x32_bf16 v[106:109], v[168:171], v[208:211], v[106:109]
	v_mfma_f32_16x16x32_bf16 v[94:97], v[148:151], v[220:223], v[94:97]
	v_mfma_f32_16x16x32_bf16 v[90:93], v[168:171], v[220:223], v[90:93]
	v_mfma_f32_16x16x32_bf16 v[78:81], v[148:151], v[228:231], v[78:81]
	v_mfma_f32_16x16x32_bf16 v[74:77], v[168:171], v[228:231], v[74:77]
	v_mfma_f32_16x16x32_bf16 v[118:121], v[172:175], v[188:191], v[118:121]
	v_mfma_f32_16x16x32_bf16 v[114:117], v[180:183], v[188:191], v[114:117]
	v_mfma_f32_16x16x32_bf16 v[102:105], v[172:175], v[196:199], v[102:105]
	v_mfma_f32_16x16x32_bf16 v[98:101], v[180:183], v[196:199], v[98:101]
	v_mfma_f32_16x16x32_bf16 v[86:89], v[172:175], v[216:219], v[86:89]
	v_mfma_f32_16x16x32_bf16 v[82:85], v[180:183], v[216:219], v[82:85]
	v_mfma_f32_16x16x32_bf16 v[70:73], v[172:175], v[224:227], v[70:73]
	v_mfma_f32_16x16x32_bf16 v[66:69], v[180:183], v[224:227], v[66:69]
	v_mfma_f32_16x16x32_bf16 v[118:121], v[176:179], v[192:195], v[118:121]
	v_mfma_f32_16x16x32_bf16 v[114:117], v[184:187], v[192:195], v[114:117]
	v_mfma_f32_16x16x32_bf16 v[102:105], v[176:179], v[208:211], v[102:105]
	v_mfma_f32_16x16x32_bf16 v[98:101], v[184:187], v[208:211], v[98:101]
	v_mfma_f32_16x16x32_bf16 v[86:89], v[176:179], v[220:223], v[86:89]
	v_mfma_f32_16x16x32_bf16 v[82:85], v[184:187], v[220:223], v[82:85]
	v_mfma_f32_16x16x32_bf16 v[70:73], v[176:179], v[228:231], v[70:73]
	v_mfma_f32_16x16x32_bf16 v[66:69], v[184:187], v[228:231], v[66:69]
	s_setprio 0
	s_barrier
	s_add_i32 s75, s75, s53
	v_lshl_add_u64 v[146:147], s[44:45], 0, v[132:133]
	s_mov_b32 m0, s75
	ds_read_b128 v[188:191], v167 offset:16384
	ds_read_b128 v[192:195], v167 offset:17408
	ds_read_b128 v[196:199], v167 offset:18432
	ds_read_b128 v[208:211], v167 offset:19456
	ds_read_b128 v[216:219], v167 offset:20480
	ds_read_b128 v[220:223], v167 offset:21504
	ds_read_b128 v[224:227], v167 offset:22528
	ds_read_b128 v[228:231], v167 offset:23552
	global_load_lds_dwordx4 v[146:147], off
	s_add_i32 m0, s75, 0x2000
	s_add_u32 s76, s44, 0x40000
	v_lshl_add_u64 v[162:163], s[44:45], 0, v[136:137]
	s_addc_u32 s77, s45, 0
	s_add_i32 s43, s43, s53
	global_load_lds_dwordx4 v[162:163], off
	v_lshl_add_u64 v[200:201], s[76:77], 0, v[132:133]
	s_mov_b32 m0, s43
	v_lshl_add_u64 v[204:205], s[46:47], 0, v[134:135]
	global_load_lds_dwordx4 v[200:201], off
	v_lshl_add_u64 v[200:201], s[76:77], 0, v[136:137]
	s_add_i32 m0, s43, 0x2000
	s_nop 0
	global_load_lds_dwordx4 v[200:201], off
	v_lshl_add_u64 v[200:201], s[46:47], 0, v[130:131]
	s_mov_b32 m0, s59
	s_nop 0
	global_load_lds_dwordx4 v[200:201], off
	s_mov_b32 m0, s62
	s_nop 0
	global_load_lds_dwordx4 v[204:205], off
	s_waitcnt vmcnt(8)
	s_waitcnt lgkmcnt(0)
	s_barrier
	s_setprio 1
	v_mfma_f32_16x16x32_bf16 v[62:65], v[142:145], v[188:191], v[62:65]
	v_mfma_f32_16x16x32_bf16 v[58:61], v[158:161], v[188:191], v[58:61]
	v_mfma_f32_16x16x32_bf16 v[46:49], v[142:145], v[196:199], v[46:49]
	v_mfma_f32_16x16x32_bf16 v[42:45], v[158:161], v[196:199], v[42:45]
	v_mfma_f32_16x16x32_bf16 v[28:31], v[142:145], v[216:219], v[28:31]
	v_mfma_f32_16x16x32_bf16 v[24:27], v[158:161], v[216:219], v[24:27]
	v_mfma_f32_16x16x32_bf16 v[12:15], v[142:145], v[224:227], v[12:15]
	v_mfma_f32_16x16x32_bf16 v[8:11], v[158:161], v[224:227], v[8:11]
	v_mfma_f32_16x16x32_bf16 v[62:65], v[148:151], v[192:195], v[62:65]
	v_mfma_f32_16x16x32_bf16 v[58:61], v[168:171], v[192:195], v[58:61]
	v_mfma_f32_16x16x32_bf16 v[46:49], v[148:151], v[208:211], v[46:49]
	v_mfma_f32_16x16x32_bf16 v[42:45], v[168:171], v[208:211], v[42:45]
	v_mfma_f32_16x16x32_bf16 v[28:31], v[148:151], v[220:223], v[28:31]
	v_mfma_f32_16x16x32_bf16 v[24:27], v[168:171], v[220:223], v[24:27]
	v_mfma_f32_16x16x32_bf16 v[12:15], v[148:151], v[228:231], v[12:15]
	v_mfma_f32_16x16x32_bf16 v[8:11], v[168:171], v[228:231], v[8:11]
	v_mfma_f32_16x16x32_bf16 v[54:57], v[172:175], v[188:191], v[54:57]
	v_mfma_f32_16x16x32_bf16 v[50:53], v[180:183], v[188:191], v[50:53]
	v_mfma_f32_16x16x32_bf16 v[38:41], v[172:175], v[196:199], v[38:41]
	v_mfma_f32_16x16x32_bf16 v[34:37], v[180:183], v[196:199], v[34:37]
	v_mfma_f32_16x16x32_bf16 v[20:23], v[172:175], v[216:219], v[20:23]
	v_mfma_f32_16x16x32_bf16 v[16:19], v[180:183], v[216:219], v[16:19]
	v_mfma_f32_16x16x32_bf16 v[4:7], v[172:175], v[224:227], v[4:7]
	v_mfma_f32_16x16x32_bf16 v[0:3], v[180:183], v[224:227], v[0:3]
	v_mfma_f32_16x16x32_bf16 v[54:57], v[176:179], v[192:195], v[54:57]
	v_mfma_f32_16x16x32_bf16 v[50:53], v[184:187], v[192:195], v[50:53]
	v_mfma_f32_16x16x32_bf16 v[38:41], v[176:179], v[208:211], v[38:41]
	v_mfma_f32_16x16x32_bf16 v[34:37], v[184:187], v[208:211], v[34:37]
	v_mfma_f32_16x16x32_bf16 v[20:23], v[176:179], v[220:223], v[20:23]
	v_mfma_f32_16x16x32_bf16 v[16:19], v[184:187], v[220:223], v[16:19]
	v_mfma_f32_16x16x32_bf16 v[4:7], v[176:179], v[228:231], v[4:7]
	v_mfma_f32_16x16x32_bf16 v[0:3], v[184:187], v[228:231], v[0:3]
	s_setprio 0
	s_barrier
; #define PG8_STAGE(bufoff, gbase, voff) do { _Pragma("unroll") for (int _i = 0; _i < 2; ++_i) \
;         __builtin_amdgcn_global_load_lds((const unsigned*)((const char*)(gbase) + (voff)[_i]), (PG8_LAS unsigned*)(lds + (bufoff) + ldsw + _i * 8192), 16, 0, 0); } while (0)
; #define PG8_LDA(dst, b, h) do { _Pragma("unroll") for (int m = 0; m < 4; ++m) _Pragma("unroll") for (int k = 0; k < 2; ++k) dst[m][k] = *(const PG8_LAS bf16x8*)(lds + PG8_SA(b, h) + aoff + m * 2048 + k * 1024); } while (0)
; #define PG8_LDB(dst, b, h) do { _Pragma("unroll") for (int n = 0; n < 2; ++n) _Pragma("unroll") for (int k = 0; k < 2; ++k) dst[n][k] = *(const PG8_LAS bf16x8*)(lds + PG8_SB(b, h) + boff + n * 2048 + k * 1024); } while (0)
; #define PG8_WAIT_V(n) asm volatile("s_waitcnt vmcnt(" #n ")" ::: "memory")
; #define PG8_WAIT_L(n) asm volatile("s_waitcnt lgkmcnt(" #n ")" ::: "memory")
; #define PG8_BAR __builtin_amdgcn_s_barrier()
; #define PG8_SCHED __builtin_amdgcn_sched_barrier(0)
; template <class Epi, bool ALIGN_EPI = true>
; __device__ __forceinline__ void gemm_phase(PG8_LAS unsigned char* lds, const Gemm g, const StaticOrder& S, const Epi& E) {
;     ...
;             PG8_LDB(B0, 1, 0); PG8_LDB(B1, 1, 1); PG8_SCHED; PG8_LDA(At, 1, 0); PG8_STAGE(PG8_SA(0, 1), a2 + hstepA, voffA);
;             PG8_WAIT_V(8); PG8_WAIT_L(0); PG8_BAR; PG8_MMA(0, 0, At, B0); PG8_MMA(0, 1, At, B1); PG8_BAR; PG8_SCHED;
.Lp3_1829:
	s_add_i32 s43, 0, 0x18000
	v_add_u32_e32 v32, s43, v165
	s_add_i32 s75, 0, 0x1c000
	ds_read_b128 v[142:145], v32
	ds_read_b128 v[148:151], v32 offset:1024
	ds_read_b128 v[158:161], v32 offset:2048
	ds_read_b128 v[168:171], v32 offset:3072
	v_add_u32_e32 v32, s75, v165
	ds_read_b128 v[172:175], v32
	ds_read_b128 v[176:179], v32 offset:1024
	ds_read_b128 v[180:183], v32 offset:2048
	ds_read_b128 v[184:187], v32 offset:3072
	s_add_u32 s46, s46, 0x40000
	s_addc_u32 s47, s47, 0
	s_mov_b32 m0, s63
	v_lshl_add_u64 v[206:207], s[46:47], 0, v[130:131]
	ds_read_b128 v[188:191], v167 offset:32768
	ds_read_b128 v[192:195], v167 offset:33792
	ds_read_b128 v[196:199], v167 offset:34816
	ds_read_b128 v[208:211], v167 offset:35840
	ds_read_b128 v[216:219], v167 offset:36864
	ds_read_b128 v[220:223], v167 offset:37888
	ds_read_b128 v[224:227], v167 offset:38912
	ds_read_b128 v[228:231], v167 offset:39936
	global_load_lds_dwordx4 v[206:207], off
	v_lshl_add_u64 v[206:207], s[46:47], 0, v[134:135]
	s_mov_b32 m0, s66
	s_nop 0
	global_load_lds_dwordx4 v[206:207], off
	s_waitcnt vmcnt(8)
	s_waitcnt lgkmcnt(0)
	s_barrier
	s_setprio 1
	v_mfma_f32_16x16x32_bf16 v[126:129], v[142:145], v[188:191], v[126:129]
	v_mfma_f32_16x16x32_bf16 v[122:125], v[158:161], v[188:191], v[122:125]
	v_mfma_f32_16x16x32_bf16 v[110:113], v[142:145], v[196:199], v[110:113]
	v_mfma_f32_16x16x32_bf16 v[106:109], v[158:161], v[196:199], v[106:109]
	v_mfma_f32_16x16x32_bf16 v[94:97], v[142:145], v[216:219], v[94:97]
	v_mfma_f32_16x16x32_bf16 v[90:93], v[158:161], v[216:219], v[90:93]
	v_mfma_f32_16x16x32_bf16 v[78:81], v[142:145], v[224:227], v[78:81]
	v_mfma_f32_16x16x32_bf16 v[74:77], v[158:161], v[224:227], v[74:77]
	v_mfma_f32_16x16x32_bf16 v[126:129], v[148:151], v[192:195], v[126:129]
	v_mfma_f32_16x16x32_bf16 v[122:125], v[168:171], v[192:195], v[122:125]
	v_mfma_f32_16x16x32_bf16 v[110:113], v[148:151], v[208:211], v[110:113]
	v_mfma_f32_16x16x32_bf16 v[106:109], v[168:171], v[208:211], v[106:109]
	v_mfma_f32_16x16x32_bf16 v[94:97], v[148:151], v[220:223], v[94:97]
	v_mfma_f32_16x16x32_bf16 v[90:93], v[168:171], v[220:223], v[90:93]
	v_mfma_f32_16x16x32_bf16 v[78:81], v[148:151], v[228:231], v[78:81]
	v_mfma_f32_16x16x32_bf16 v[74:77], v[168:171], v[228:231], v[74:77]
	v_mfma_f32_16x16x32_bf16 v[118:121], v[172:175], v[188:191], v[118:121]
	v_mfma_f32_16x16x32_bf16 v[114:117], v[180:183], v[188:191], v[114:117]
	v_mfma_f32_16x16x32_bf16 v[102:105], v[172:175], v[196:199], v[102:105]
	v_mfma_f32_16x16x32_bf16 v[98:101], v[180:183], v[196:199], v[98:101]
	v_mfma_f32_16x16x32_bf16 v[86:89], v[172:175], v[216:219], v[86:89]
	v_mfma_f32_16x16x32_bf16 v[82:85], v[180:183], v[216:219], v[82:85]
	v_mfma_f32_16x16x32_bf16 v[70:73], v[172:175], v[224:227], v[70:73]
	v_mfma_f32_16x16x32_bf16 v[66:69], v[180:183], v[224:227], v[66:69]
	v_mfma_f32_16x16x32_bf16 v[118:121], v[176:179], v[192:195], v[118:121]
	v_mfma_f32_16x16x32_bf16 v[114:117], v[184:187], v[192:195], v[114:117]
	v_mfma_f32_16x16x32_bf16 v[102:105], v[176:179], v[208:211], v[102:105]
	v_mfma_f32_16x16x32_bf16 v[98:101], v[184:187], v[208:211], v[98:101]
	v_mfma_f32_16x16x32_bf16 v[86:89], v[176:179], v[220:223], v[86:89]
	v_mfma_f32_16x16x32_bf16 v[82:85], v[184:187], v[220:223], v[82:85]
	v_mfma_f32_16x16x32_bf16 v[70:73], v[176:179], v[228:231], v[70:73]
	v_mfma_f32_16x16x32_bf16 v[66:69], v[184:187], v[228:231], v[66:69]
	s_setprio 0
	s_barrier
; #define PG8_STAGE(bufoff, gbase, voff) do { _Pragma("unroll") for (int _i = 0; _i < 2; ++_i) \
;         __builtin_amdgcn_global_load_lds((const unsigned*)((const char*)(gbase) + (voff)[_i]), (PG8_LAS unsigned*)(lds + (bufoff) + ldsw + _i * 8192), 16, 0, 0); } while (0)
; #define PG8_LDA(dst, b, h) do { _Pragma("unroll") for (int m = 0; m < 4; ++m) _Pragma("unroll") for (int k = 0; k < 2; ++k) dst[m][k] = *(const PG8_LAS bf16x8*)(lds + PG8_SA(b, h) + aoff + m * 2048 + k * 1024); } while (0)
; #define PG8_WAIT_V(n) asm volatile("s_waitcnt vmcnt(" #n ")" ::: "memory")
; #define PG8_WAIT_L(n) asm volatile("s_waitcnt lgkmcnt(" #n ")" ::: "memory")
; #define PG8_BAR __builtin_amdgcn_s_barrier()
; #define PG8_SCHED __builtin_amdgcn_sched_barrier(0)
; template <class Epi, bool ALIGN_EPI = true>
; __device__ __forceinline__ void gemm_phase(PG8_LAS unsigned char* lds, const Gemm g, const StaticOrder& S, const Epi& E) {
;     ...
;         for (int t = 0; t < nt; t += 2) {
;             const bool last = (t == nt - 2);
;             const char* a1 = cA + (size_t)(t + 1) * kstep;
;             const char* a2 = last ? nA : cA + (size_t)(t + 2) * kstep; const char* b2 = last ? nB : cB + (size_t)(t + 2) * kstep;
;     ...
;             PG8_LDA(At, 1, 1); PG8_STAGE(PG8_SB(1, 0), b3, voffB); PG8_STAGE(PG8_SB(1, 1), b3 + hstepB, voffB); PG8_STAGE(PG8_SA(1, 0), a3, voffA);
;             PG8_WAIT_V(8); PG8_WAIT_L(0); PG8_BAR; PG8_MMA(1, 0, At, B0); PG8_MMA(1, 1, At, B1); PG8_BAR; PG8_SCHED;
	s_add_i32 s43, s43, s53
	v_lshl_add_u64 v[146:147], v[146:147], 0, s[60:61]
	s_mov_b32 m0, s43
	ds_read_b128 v[188:191], v167 offset:49152
	ds_read_b128 v[192:195], v167 offset:50176
	ds_read_b128 v[196:199], v167 offset:51200
	ds_read_b128 v[208:211], v167 offset:52224
	ds_read_b128 v[216:219], v167 offset:53248
	ds_read_b128 v[220:223], v167 offset:54272
	ds_read_b128 v[224:227], v167 offset:55296
	ds_read_b128 v[228:231], v167 offset:56320
	global_load_lds_dwordx4 v[146:147], off
	s_add_i32 m0, s43, 0x2000
	s_add_u32 s44, s44, 0x40080
	v_lshl_add_u64 v[146:147], v[162:163], 0, s[60:61]
	s_addc_u32 s45, s45, 0
	s_add_i32 s43, s75, s53
	global_load_lds_dwordx4 v[146:147], off
	v_lshl_add_u64 v[146:147], s[44:45], 0, v[132:133]
	s_mov_b32 m0, s43
	s_nop 0
	global_load_lds_dwordx4 v[146:147], off
	v_lshl_add_u64 v[146:147], s[44:45], 0, v[136:137]
	s_add_i32 m0, s43, 0x2000
	s_nop 0
	global_load_lds_dwordx4 v[146:147], off
	v_lshl_add_u64 v[146:147], v[200:201], 0, s[60:61]
	s_mov_b32 m0, s70
	s_nop 0
	global_load_lds_dwordx4 v[146:147], off
	v_lshl_add_u64 v[146:147], v[204:205], 0, s[60:61]
	s_mov_b32 m0, s71
	s_nop 0
	global_load_lds_dwordx4 v[146:147], off
	s_add_i32 s37, s37, 2
	s_add_u32 s6, s6, 0x100
	s_addc_u32 s7, s7, 0
	s_add_u32 s9, s9, 0x100
	s_addc_u32 s35, s35, 0
	s_add_u32 s43, s6, 0xfffc0080
	s_addc_u32 s44, s7, -1
	s_add_i32 s75, 0, 0x10000
	s_cmp_eq_u32 s37, 12
	s_cselect_b32 s47, s39, s44
	s_cselect_b32 s46, s38, s43
	v_add_u32_e32 v32, s75, v165
	s_cselect_b32 s45, s41, s35
	s_cselect_b32 s44, s40, s9
	s_add_i32 s43, 0, 0x14000
	s_cmp_gt_u32 s37, 13
	s_waitcnt vmcnt(8)
	s_waitcnt lgkmcnt(0)
	s_barrier
	s_setprio 1
	v_mfma_f32_16x16x32_bf16 v[62:65], v[142:145], v[188:191], v[62:65]
	v_mfma_f32_16x16x32_bf16 v[58:61], v[158:161], v[188:191], v[58:61]
	v_mfma_f32_16x16x32_bf16 v[46:49], v[142:145], v[196:199], v[46:49]
	v_mfma_f32_16x16x32_bf16 v[42:45], v[158:161], v[196:199], v[42:45]
	v_mfma_f32_16x16x32_bf16 v[28:31], v[142:145], v[216:219], v[28:31]
	v_mfma_f32_16x16x32_bf16 v[24:27], v[158:161], v[216:219], v[24:27]
	v_mfma_f32_16x16x32_bf16 v[12:15], v[142:145], v[224:227], v[12:15]
	v_mfma_f32_16x16x32_bf16 v[8:11], v[158:161], v[224:227], v[8:11]
	v_mfma_f32_16x16x32_bf16 v[62:65], v[148:151], v[192:195], v[62:65]
	v_mfma_f32_16x16x32_bf16 v[58:61], v[168:171], v[192:195], v[58:61]
	v_mfma_f32_16x16x32_bf16 v[46:49], v[148:151], v[208:211], v[46:49]
	v_mfma_f32_16x16x32_bf16 v[42:45], v[168:171], v[208:211], v[42:45]
	v_mfma_f32_16x16x32_bf16 v[28:31], v[148:151], v[220:223], v[28:31]
	v_mfma_f32_16x16x32_bf16 v[24:27], v[168:171], v[220:223], v[24:27]
	v_mfma_f32_16x16x32_bf16 v[12:15], v[148:151], v[228:231], v[12:15]
	v_mfma_f32_16x16x32_bf16 v[8:11], v[168:171], v[228:231], v[8:11]
	v_mfma_f32_16x16x32_bf16 v[54:57], v[172:175], v[188:191], v[54:57]
	v_mfma_f32_16x16x32_bf16 v[50:53], v[180:183], v[188:191], v[50:53]
	v_mfma_f32_16x16x32_bf16 v[38:41], v[172:175], v[196:199], v[38:41]
	v_mfma_f32_16x16x32_bf16 v[34:37], v[180:183], v[196:199], v[34:37]
	v_mfma_f32_16x16x32_bf16 v[20:23], v[172:175], v[216:219], v[20:23]
	v_mfma_f32_16x16x32_bf16 v[16:19], v[180:183], v[216:219], v[16:19]
	v_mfma_f32_16x16x32_bf16 v[4:7], v[172:175], v[224:227], v[4:7]
	v_mfma_f32_16x16x32_bf16 v[0:3], v[180:183], v[224:227], v[0:3]
	v_mfma_f32_16x16x32_bf16 v[54:57], v[176:179], v[192:195], v[54:57]
	v_mfma_f32_16x16x32_bf16 v[50:53], v[184:187], v[192:195], v[50:53]
	v_mfma_f32_16x16x32_bf16 v[38:41], v[176:179], v[208:211], v[38:41]
	v_mfma_f32_16x16x32_bf16 v[34:37], v[184:187], v[208:211], v[34:37]
	v_mfma_f32_16x16x32_bf16 v[20:23], v[176:179], v[220:223], v[20:23]
	v_mfma_f32_16x16x32_bf16 v[16:19], v[184:187], v[220:223], v[16:19]
	v_mfma_f32_16x16x32_bf16 v[4:7], v[176:179], v[228:231], v[4:7]
	v_mfma_f32_16x16x32_bf16 v[0:3], v[184:187], v[228:231], v[0:3]
	s_setprio 0
	s_barrier
	s_cbranch_scc0 .Lrot_1829
	s_and_b64 vcc, exec, s[26:27]
	s_cbranch_vccz .LBB0_1832
	s_barrier

; #define PG8_STAGE(bufoff, gbase, voff) do { _Pragma("unroll") for (int _i = 0; _i < 2; ++_i) \
;         __builtin_amdgcn_global_load_lds((const unsigned*)((const char*)(gbase) + (voff)[_i]), (PG8_LAS unsigned*)(lds + (bufoff) + ldsw + _i * 8192), 16, 0, 0); } while (0)
; #define PG8_LDA(dst, b, h) do { _Pragma("unroll") for (int m = 0; m < 4; ++m) _Pragma("unroll") for (int k = 0; k < 2; ++k) dst[m][k] = *(const PG8_LAS bf16x8*)(lds + PG8_SA(b, h) + aoff + m * 2048 + k * 1024); } while (0)
; #define PG8_LDB(dst, b, h) do { _Pragma("unroll") for (int n = 0; n < 2; ++n) _Pragma("unroll") for (int k = 0; k < 2; ++k) dst[n][k] = *(const PG8_LAS bf16x8*)(lds + PG8_SB(b, h) + boff + n * 2048 + k * 1024); } while (0)
; #define PG8_WAIT_V(n) asm volatile("s_waitcnt vmcnt(" #n ")" ::: "memory")
; #define PG8_WAIT_L(n) asm volatile("s_waitcnt lgkmcnt(" #n ")" ::: "memory")
; #define PG8_BAR __builtin_amdgcn_s_barrier()
; #define PG8_SCHED __builtin_amdgcn_sched_barrier(0)
; template <class Epi, bool ALIGN_EPI = true>
; __device__ __forceinline__ void gemm_phase(PG8_LAS unsigned char* lds, const Gemm g, const StaticOrder& S, const Epi& E) {
;     ...
;             PG8_LDB(B0, 0, 0); PG8_LDB(B1, 0, 1); PG8_SCHED; PG8_LDA(At, 0, 0); PG8_STAGE(PG8_SA(1, 1), a1 + hstepA, voffA);
;             PG8_WAIT_V(8); PG8_WAIT_L(0); PG8_BAR; PG8_MMA(0, 0, At, B0); PG8_MMA(0, 1, At, B1); PG8_BAR; PG8_SCHED;
;             PG8_LDA(At, 0, 1); PG8_STAGE(PG8_SB(0, 0), b2, voffB); PG8_STAGE(PG8_SB(0, 1), b2 + hstepB, voffB); PG8_STAGE(PG8_SA(0, 0), a2, voffA);
;             PG8_WAIT_V(8); PG8_WAIT_L(0); PG8_BAR; PG8_MMA(1, 0, At, B0); PG8_MMA(1, 1, At, B1); PG8_BAR; PG8_SCHED;
.LBB0_2032:
	s_add_u32 s42, s40, 0xfffc0080
	s_addc_u32 s43, s41, -1
	s_add_i32 s87, 0, 0x10000
	s_cmp_eq_u32 s86, 12
	s_cselect_b32 s45, s29, s43
	s_cselect_b32 s44, s37, s42
	v_add_u32_e32 v144, s87, v159
	s_cselect_b32 s43, s27, s85
	s_cselect_b32 s42, s82, s83
	s_add_i32 s90, 0, 0x14000
	ds_read_b128 v[140:143], v144
	ds_read_b128 v[148:151], v144 offset:1024
	ds_read_b128 v[162:165], v144 offset:2048
	ds_read_b128 v[166:169], v144 offset:3072
	v_add_u32_e32 v144, s90, v159
	ds_read_b128 v[170:173], v144
	ds_read_b128 v[174:177], v144 offset:1024
	ds_read_b128 v[178:181], v144 offset:2048
	ds_read_b128 v[182:185], v144 offset:3072
	v_lshl_add_u64 v[144:145], s[40:41], 0, v[136:137]
	s_add_i32 m0, s39, 0xc000
	ds_read_b128 v[186:189], v161
	ds_read_b128 v[190:193], v161 offset:1024
	ds_read_b128 v[194:197], v161 offset:2048
	ds_read_b128 v[198:201], v161 offset:3072
	ds_read_b128 v[208:211], v161 offset:4096
	ds_read_b128 v[216:219], v161 offset:5120
	ds_read_b128 v[220:223], v161 offset:6144
	ds_read_b128 v[224:227], v161 offset:7168
	global_load_lds_dwordx4 v[144:145], off
	v_lshl_add_u64 v[144:145], s[40:41], 0, v[138:139]
	s_add_i32 m0, s39, 0xe000
	s_nop 0
	global_load_lds_dwordx4 v[144:145], off
	s_waitcnt vmcnt(8)
	s_waitcnt lgkmcnt(0)
	s_barrier
	s_setprio 1
	v_mfma_f32_16x16x32_bf16 v[126:129], v[140:143], v[186:189], 0
	v_mfma_f32_16x16x32_bf16 v[122:125], v[162:165], v[186:189], 0
	v_mfma_f32_16x16x32_bf16 v[110:113], v[140:143], v[194:197], 0
	v_mfma_f32_16x16x32_bf16 v[106:109], v[162:165], v[194:197], 0
	v_mfma_f32_16x16x32_bf16 v[94:97], v[140:143], v[208:211], 0
	v_mfma_f32_16x16x32_bf16 v[90:93], v[162:165], v[208:211], 0
	v_mfma_f32_16x16x32_bf16 v[78:81], v[140:143], v[220:223], 0
	v_mfma_f32_16x16x32_bf16 v[74:77], v[162:165], v[220:223], 0
	v_mfma_f32_16x16x32_bf16 v[126:129], v[148:151], v[190:193], v[126:129]
	v_mfma_f32_16x16x32_bf16 v[122:125], v[166:169], v[190:193], v[122:125]
	v_mfma_f32_16x16x32_bf16 v[110:113], v[148:151], v[198:201], v[110:113]
	v_mfma_f32_16x16x32_bf16 v[106:109], v[166:169], v[198:201], v[106:109]
	v_mfma_f32_16x16x32_bf16 v[94:97], v[148:151], v[216:219], v[94:97]
	v_mfma_f32_16x16x32_bf16 v[90:93], v[166:169], v[216:219], v[90:93]
	v_mfma_f32_16x16x32_bf16 v[78:81], v[148:151], v[224:227], v[78:81]
	v_mfma_f32_16x16x32_bf16 v[74:77], v[166:169], v[224:227], v[74:77]
	v_mfma_f32_16x16x32_bf16 v[118:121], v[170:173], v[186:189], 0
	v_mfma_f32_16x16x32_bf16 v[114:117], v[178:181], v[186:189], 0
	v_mfma_f32_16x16x32_bf16 v[102:105], v[170:173], v[194:197], 0
	v_mfma_f32_16x16x32_bf16 v[98:101], v[178:181], v[194:197], 0
	v_mfma_f32_16x16x32_bf16 v[86:89], v[170:173], v[208:211], 0
	v_mfma_f32_16x16x32_bf16 v[82:85], v[178:181], v[208:211], 0
	v_mfma_f32_16x16x32_bf16 v[70:73], v[170:173], v[220:223], 0
	v_mfma_f32_16x16x32_bf16 v[66:69], v[178:181], v[220:223], 0
	v_mfma_f32_16x16x32_bf16 v[118:121], v[174:177], v[190:193], v[118:121]
	v_mfma_f32_16x16x32_bf16 v[114:117], v[182:185], v[190:193], v[114:117]
	v_mfma_f32_16x16x32_bf16 v[102:105], v[174:177], v[198:201], v[102:105]
	v_mfma_f32_16x16x32_bf16 v[98:101], v[182:185], v[198:201], v[98:101]
	v_mfma_f32_16x16x32_bf16 v[86:89], v[174:177], v[216:219], v[86:89]
	v_mfma_f32_16x16x32_bf16 v[82:85], v[182:185], v[216:219], v[82:85]
	v_mfma_f32_16x16x32_bf16 v[70:73], v[174:177], v[224:227], v[70:73]
	v_mfma_f32_16x16x32_bf16 v[66:69], v[182:185], v[224:227], v[66:69]
	s_setprio 0
	s_barrier
	s_add_i32 s87, s87, s53
	v_lshl_add_u64 v[144:145], s[42:43], 0, v[32:33]
	s_mov_b32 m0, s87
	ds_read_b128 v[186:189], v161 offset:16384
	ds_read_b128 v[190:193], v161 offset:17408
	ds_read_b128 v[194:197], v161 offset:18432
	ds_read_b128 v[198:201], v161 offset:19456
	ds_read_b128 v[208:211], v161 offset:20480
	ds_read_b128 v[216:219], v161 offset:21504
	ds_read_b128 v[220:223], v161 offset:22528
	ds_read_b128 v[224:227], v161 offset:23552
	global_load_lds_dwordx4 v[144:145], off
	s_add_i32 m0, s87, 0x2000
	s_add_u32 s88, s42, 0x40000
	v_lshl_add_u64 v[146:147], s[42:43], 0, v[134:135]
	s_addc_u32 s89, s43, 0
	s_add_i32 s87, s90, s53
	global_load_lds_dwordx4 v[146:147], off
	v_lshl_add_u64 v[204:205], s[88:89], 0, v[32:33]
	s_mov_b32 m0, s87
	v_lshl_add_u64 v[206:207], s[44:45], 0, v[132:133]
	global_load_lds_dwordx4 v[204:205], off
	v_lshl_add_u64 v[204:205], s[88:89], 0, v[134:135]
	s_add_i32 m0, s87, 0x2000
	s_nop 0
	global_load_lds_dwordx4 v[204:205], off
	v_lshl_add_u64 v[204:205], s[44:45], 0, v[130:131]
	s_mov_b32 m0, s39
	s_nop 0
	global_load_lds_dwordx4 v[204:205], off
	s_mov_b32 m0, s67
	s_nop 0
	global_load_lds_dwordx4 v[206:207], off
	s_waitcnt vmcnt(8)
	s_waitcnt lgkmcnt(0)
	s_barrier
	s_setprio 1
	v_mfma_f32_16x16x32_bf16 v[62:65], v[140:143], v[186:189], 0
	v_mfma_f32_16x16x32_bf16 v[58:61], v[162:165], v[186:189], 0
	v_mfma_f32_16x16x32_bf16 v[46:49], v[140:143], v[194:197], 0
	v_mfma_f32_16x16x32_bf16 v[42:45], v[162:165], v[194:197], 0
	v_mfma_f32_16x16x32_bf16 v[28:31], v[140:143], v[208:211], 0
	v_mfma_f32_16x16x32_bf16 v[24:27], v[162:165], v[208:211], 0
	v_mfma_f32_16x16x32_bf16 v[12:15], v[140:143], v[220:223], 0
	v_mfma_f32_16x16x32_bf16 v[8:11], v[162:165], v[220:223], 0
	v_mfma_f32_16x16x32_bf16 v[62:65], v[148:151], v[190:193], v[62:65]
	v_mfma_f32_16x16x32_bf16 v[58:61], v[166:169], v[190:193], v[58:61]
	v_mfma_f32_16x16x32_bf16 v[46:49], v[148:151], v[198:201], v[46:49]
	v_mfma_f32_16x16x32_bf16 v[42:45], v[166:169], v[198:201], v[42:45]
	v_mfma_f32_16x16x32_bf16 v[28:31], v[148:151], v[216:219], v[28:31]
	v_mfma_f32_16x16x32_bf16 v[24:27], v[166:169], v[216:219], v[24:27]
	v_mfma_f32_16x16x32_bf16 v[12:15], v[148:151], v[224:227], v[12:15]
	v_mfma_f32_16x16x32_bf16 v[8:11], v[166:169], v[224:227], v[8:11]
	v_mfma_f32_16x16x32_bf16 v[54:57], v[170:173], v[186:189], 0
	v_mfma_f32_16x16x32_bf16 v[50:53], v[178:181], v[186:189], 0
	v_mfma_f32_16x16x32_bf16 v[38:41], v[170:173], v[194:197], 0
	v_mfma_f32_16x16x32_bf16 v[34:37], v[178:181], v[194:197], 0
	v_mfma_f32_16x16x32_bf16 v[20:23], v[170:173], v[208:211], 0
	v_mfma_f32_16x16x32_bf16 v[16:19], v[178:181], v[208:211], 0
	v_mfma_f32_16x16x32_bf16 v[4:7], v[170:173], v[220:223], 0
	v_mfma_f32_16x16x32_bf16 v[0:3], v[178:181], v[220:223], 0
	v_mfma_f32_16x16x32_bf16 v[54:57], v[174:177], v[190:193], v[54:57]
	v_mfma_f32_16x16x32_bf16 v[50:53], v[182:185], v[190:193], v[50:53]
	v_mfma_f32_16x16x32_bf16 v[38:41], v[174:177], v[198:201], v[38:41]
	v_mfma_f32_16x16x32_bf16 v[34:37], v[182:185], v[198:201], v[34:37]
	v_mfma_f32_16x16x32_bf16 v[20:23], v[174:177], v[216:219], v[20:23]
	v_mfma_f32_16x16x32_bf16 v[16:19], v[182:185], v[216:219], v[16:19]
	v_mfma_f32_16x16x32_bf16 v[4:7], v[174:177], v[224:227], v[4:7]
	v_mfma_f32_16x16x32_bf16 v[0:3], v[182:185], v[224:227], v[0:3]
	s_setprio 0
	s_barrier
	s_branch .Lp3_2032
; #define PG8_STAGE(bufoff, gbase, voff) do { _Pragma("unroll") for (int _i = 0; _i < 2; ++_i) \
;         __builtin_amdgcn_global_load_lds((const unsigned*)((const char*)(gbase) + (voff)[_i]), (PG8_LAS unsigned*)(lds + (bufoff) + ldsw + _i * 8192), 16, 0, 0); } while (0)
; #define PG8_LDA(dst, b, h) do { _Pragma("unroll") for (int m = 0; m < 4; ++m) _Pragma("unroll") for (int k = 0; k < 2; ++k) dst[m][k] = *(const PG8_LAS bf16x8*)(lds + PG8_SA(b, h) + aoff + m * 2048 + k * 1024); } while (0)
; #define PG8_LDB(dst, b, h) do { _Pragma("unroll") for (int n = 0; n < 2; ++n) _Pragma("unroll") for (int k = 0; k < 2; ++k) dst[n][k] = *(const PG8_LAS bf16x8*)(lds + PG8_SB(b, h) + boff + n * 2048 + k * 1024); } while (0)
; #define PG8_WAIT_V(n) asm volatile("s_waitcnt vmcnt(" #n ")" ::: "memory")
; #define PG8_WAIT_L(n) asm volatile("s_waitcnt lgkmcnt(" #n ")" ::: "memory")
; #define PG8_BAR __builtin_amdgcn_s_barrier()
; #define PG8_SCHED __builtin_amdgcn_sched_barrier(0)
; template <class Epi, bool ALIGN_EPI = true>
; __device__ __forceinline__ void gemm_phase(PG8_LAS unsigned char* lds, const Gemm g, const StaticOrder& S, const Epi& E) {
;     ...
;             PG8_LDB(B0, 0, 0); PG8_LDB(B1, 0, 1); PG8_SCHED; PG8_LDA(At, 0, 0); PG8_STAGE(PG8_SA(1, 1), a1 + hstepA, voffA);
;             PG8_WAIT_V(8); PG8_WAIT_L(0); PG8_BAR; PG8_MMA(0, 0, At, B0); PG8_MMA(0, 1, At, B1); PG8_BAR; PG8_SCHED;
;             PG8_LDA(At, 0, 1); PG8_STAGE(PG8_SB(0, 0), b2, voffB); PG8_STAGE(PG8_SB(0, 1), b2 + hstepB, voffB); PG8_STAGE(PG8_SA(0, 0), a2, voffA);
;             PG8_WAIT_V(8); PG8_WAIT_L(0); PG8_BAR; PG8_MMA(1, 0, At, B0); PG8_MMA(1, 1, At, B1); PG8_BAR; PG8_SCHED;
.Lrot_2032:
	ds_read_b128 v[140:143], v144
	ds_read_b128 v[148:151], v144 offset:1024
	ds_read_b128 v[162:165], v144 offset:2048
	ds_read_b128 v[166:169], v144 offset:3072
	v_add_u32_e32 v144, s90, v159
	ds_read_b128 v[170:173], v144
	ds_read_b128 v[174:177], v144 offset:1024
	ds_read_b128 v[178:181], v144 offset:2048
	ds_read_b128 v[182:185], v144 offset:3072
	v_lshl_add_u64 v[144:145], s[40:41], 0, v[136:137]
	s_add_i32 m0, s39, 0xc000
	ds_read_b128 v[186:189], v161
	ds_read_b128 v[190:193], v161 offset:1024
	ds_read_b128 v[194:197], v161 offset:2048
	ds_read_b128 v[198:201], v161 offset:3072
	ds_read_b128 v[208:211], v161 offset:4096
	ds_read_b128 v[216:219], v161 offset:5120
	ds_read_b128 v[220:223], v161 offset:6144
	ds_read_b128 v[224:227], v161 offset:7168
	global_load_lds_dwordx4 v[144:145], off
	v_lshl_add_u64 v[144:145], s[40:41], 0, v[138:139]
	s_add_i32 m0, s39, 0xe000
	s_nop 0
	global_load_lds_dwordx4 v[144:145], off
	s_waitcnt vmcnt(8)
	s_waitcnt lgkmcnt(0)
	s_barrier
	s_setprio 1
	v_mfma_f32_16x16x32_bf16 v[126:129], v[140:143], v[186:189], v[126:129]
	v_mfma_f32_16x16x32_bf16 v[122:125], v[162:165], v[186:189], v[122:125]
	v_mfma_f32_16x16x32_bf16 v[110:113], v[140:143], v[194:197], v[110:113]
	v_mfma_f32_16x16x32_bf16 v[106:109], v[162:165], v[194:197], v[106:109]
	v_mfma_f32_16x16x32_bf16 v[94:97], v[140:143], v[208:211], v[94:97]
	v_mfma_f32_16x16x32_bf16 v[90:93], v[162:165], v[208:211], v[90:93]
	v_mfma_f32_16x16x32_bf16 v[78:81], v[140:143], v[220:223], v[78:81]
	v_mfma_f32_16x16x32_bf16 v[74:77], v[162:165], v[220:223], v[74:77]
	v_mfma_f32_16x16x32_bf16 v[126:129], v[148:151], v[190:193], v[126:129]
	v_mfma_f32_16x16x32_bf16 v[122:125], v[166:169], v[190:193], v[122:125]
	v_mfma_f32_16x16x32_bf16 v[110:113], v[148:151], v[198:201], v[110:113]
	v_mfma_f32_16x16x32_bf16 v[106:109], v[166:169], v[198:201], v[106:109]
	v_mfma_f32_16x16x32_bf16 v[94:97], v[148:151], v[216:219], v[94:97]
	v_mfma_f32_16x16x32_bf16 v[90:93], v[166:169], v[216:219], v[90:93]
	v_mfma_f32_16x16x32_bf16 v[78:81], v[148:151], v[224:227], v[78:81]
	v_mfma_f32_16x16x32_bf16 v[74:77], v[166:169], v[224:227], v[74:77]
	v_mfma_f32_16x16x32_bf16 v[118:121], v[170:173], v[186:189], v[118:121]
	v_mfma_f32_16x16x32_bf16 v[114:117], v[178:181], v[186:189], v[114:117]
	v_mfma_f32_16x16x32_bf16 v[102:105], v[170:173], v[194:197], v[102:105]
	v_mfma_f32_16x16x32_bf16 v[98:101], v[178:181], v[194:197], v[98:101]
	v_mfma_f32_16x16x32_bf16 v[86:89], v[170:173], v[208:211], v[86:89]
	v_mfma_f32_16x16x32_bf16 v[82:85], v[178:181], v[208:211], v[82:85]
	v_mfma_f32_16x16x32_bf16 v[70:73], v[170:173], v[220:223], v[70:73]
	v_mfma_f32_16x16x32_bf16 v[66:69], v[178:181], v[220:223], v[66:69]
	v_mfma_f32_16x16x32_bf16 v[118:121], v[174:177], v[190:193], v[118:121]
	v_mfma_f32_16x16x32_bf16 v[114:117], v[182:185], v[190:193], v[114:117]
	v_mfma_f32_16x16x32_bf16 v[102:105], v[174:177], v[198:201], v[102:105]
	v_mfma_f32_16x16x32_bf16 v[98:101], v[182:185], v[198:201], v[98:101]
	v_mfma_f32_16x16x32_bf16 v[86:89], v[174:177], v[216:219], v[86:89]
	v_mfma_f32_16x16x32_bf16 v[82:85], v[182:185], v[216:219], v[82:85]
	v_mfma_f32_16x16x32_bf16 v[70:73], v[174:177], v[224:227], v[70:73]
	v_mfma_f32_16x16x32_bf16 v[66:69], v[182:185], v[224:227], v[66:69]
	s_setprio 0
	s_barrier
	s_add_i32 s87, s87, s53
	v_lshl_add_u64 v[144:145], s[42:43], 0, v[32:33]
	s_mov_b32 m0, s87
	ds_read_b128 v[186:189], v161 offset:16384
	ds_read_b128 v[190:193], v161 offset:17408
	ds_read_b128 v[194:197], v161 offset:18432
	ds_read_b128 v[198:201], v161 offset:19456
	ds_read_b128 v[208:211], v161 offset:20480
	ds_read_b128 v[216:219], v161 offset:21504
	ds_read_b128 v[220:223], v161 offset:22528
	ds_read_b128 v[224:227], v161 offset:23552
	global_load_lds_dwordx4 v[144:145], off
	s_add_i32 m0, s87, 0x2000
	s_add_u32 s88, s42, 0x40000
	v_lshl_add_u64 v[146:147], s[42:43], 0, v[134:135]
	s_addc_u32 s89, s43, 0
	s_add_i32 s87, s90, s53
	global_load_lds_dwordx4 v[146:147], off
	v_lshl_add_u64 v[204:205], s[88:89], 0, v[32:33]
	s_mov_b32 m0, s87
	v_lshl_add_u64 v[206:207], s[44:45], 0, v[132:133]
	global_load_lds_dwordx4 v[204:205], off
	v_lshl_add_u64 v[204:205], s[88:89], 0, v[134:135]
	s_add_i32 m0, s87, 0x2000
	s_nop 0
	global_load_lds_dwordx4 v[204:205], off
	v_lshl_add_u64 v[204:205], s[44:45], 0, v[130:131]
	s_mov_b32 m0, s39
	s_nop 0
	global_load_lds_dwordx4 v[204:205], off
	s_mov_b32 m0, s67
	s_nop 0
	global_load_lds_dwordx4 v[206:207], off
	s_waitcnt vmcnt(8)
	s_waitcnt lgkmcnt(0)
	s_barrier
	s_setprio 1
	v_mfma_f32_16x16x32_bf16 v[62:65], v[140:143], v[186:189], v[62:65]
	v_mfma_f32_16x16x32_bf16 v[58:61], v[162:165], v[186:189], v[58:61]
	v_mfma_f32_16x16x32_bf16 v[46:49], v[140:143], v[194:197], v[46:49]
	v_mfma_f32_16x16x32_bf16 v[42:45], v[162:165], v[194:197], v[42:45]
	v_mfma_f32_16x16x32_bf16 v[28:31], v[140:143], v[208:211], v[28:31]
	v_mfma_f32_16x16x32_bf16 v[24:27], v[162:165], v[208:211], v[24:27]
	v_mfma_f32_16x16x32_bf16 v[12:15], v[140:143], v[220:223], v[12:15]
	v_mfma_f32_16x16x32_bf16 v[8:11], v[162:165], v[220:223], v[8:11]
	v_mfma_f32_16x16x32_bf16 v[62:65], v[148:151], v[190:193], v[62:65]
	v_mfma_f32_16x16x32_bf16 v[58:61], v[166:169], v[190:193], v[58:61]
	v_mfma_f32_16x16x32_bf16 v[46:49], v[148:151], v[198:201], v[46:49]
	v_mfma_f32_16x16x32_bf16 v[42:45], v[166:169], v[198:201], v[42:45]
	v_mfma_f32_16x16x32_bf16 v[28:31], v[148:151], v[216:219], v[28:31]
	v_mfma_f32_16x16x32_bf16 v[24:27], v[166:169], v[216:219], v[24:27]
	v_mfma_f32_16x16x32_bf16 v[12:15], v[148:151], v[224:227], v[12:15]
	v_mfma_f32_16x16x32_bf16 v[8:11], v[166:169], v[224:227], v[8:11]
	v_mfma_f32_16x16x32_bf16 v[54:57], v[170:173], v[186:189], v[54:57]
	v_mfma_f32_16x16x32_bf16 v[50:53], v[178:181], v[186:189], v[50:53]
	v_mfma_f32_16x16x32_bf16 v[38:41], v[170:173], v[194:197], v[38:41]
	v_mfma_f32_16x16x32_bf16 v[34:37], v[178:181], v[194:197], v[34:37]
	v_mfma_f32_16x16x32_bf16 v[20:23], v[170:173], v[208:211], v[20:23]
	v_mfma_f32_16x16x32_bf16 v[16:19], v[178:181], v[208:211], v[16:19]
	v_mfma_f32_16x16x32_bf16 v[4:7], v[170:173], v[220:223], v[4:7]
	v_mfma_f32_16x16x32_bf16 v[0:3], v[178:181], v[220:223], v[0:3]
	v_mfma_f32_16x16x32_bf16 v[54:57], v[174:177], v[190:193], v[54:57]
	v_mfma_f32_16x16x32_bf16 v[50:53], v[182:185], v[190:193], v[50:53]
	v_mfma_f32_16x16x32_bf16 v[38:41], v[174:177], v[198:201], v[38:41]
	v_mfma_f32_16x16x32_bf16 v[34:37], v[182:185], v[198:201], v[34:37]
	v_mfma_f32_16x16x32_bf16 v[20:23], v[174:177], v[216:219], v[20:23]
	v_mfma_f32_16x16x32_bf16 v[16:19], v[182:185], v[216:219], v[16:19]
	v_mfma_f32_16x16x32_bf16 v[4:7], v[174:177], v[224:227], v[4:7]
	v_mfma_f32_16x16x32_bf16 v[0:3], v[182:185], v[224:227], v[0:3]
	s_setprio 0
	s_barrier
; #define PG8_STAGE(bufoff, gbase, voff) do { _Pragma("unroll") for (int _i = 0; _i < 2; ++_i) \
;         __builtin_amdgcn_global_load_lds((const unsigned*)((const char*)(gbase) + (voff)[_i]), (PG8_LAS unsigned*)(lds + (bufoff) + ldsw + _i * 8192), 16, 0, 0); } while (0)
; #define PG8_LDA(dst, b, h) do { _Pragma("unroll") for (int m = 0; m < 4; ++m) _Pragma("unroll") for (int k = 0; k < 2; ++k) dst[m][k] = *(const PG8_LAS bf16x8*)(lds + PG8_SA(b, h) + aoff + m * 2048 + k * 1024); } while (0)
; #define PG8_LDB(dst, b, h) do { _Pragma("unroll") for (int n = 0; n < 2; ++n) _Pragma("unroll") for (int k = 0; k < 2; ++k) dst[n][k] = *(const PG8_LAS bf16x8*)(lds + PG8_SB(b, h) + boff + n * 2048 + k * 1024); } while (0)
; #define PG8_WAIT_V(n) asm volatile("s_waitcnt vmcnt(" #n ")" ::: "memory")
; #define PG8_WAIT_L(n) asm volatile("s_waitcnt lgkmcnt(" #n ")" ::: "memory")
; #define PG8_BAR __builtin_amdgcn_s_barrier()
; #define PG8_SCHED __builtin_amdgcn_sched_barrier(0)
; template <class Epi, bool ALIGN_EPI = true>
; __device__ __forceinline__ void gemm_phase(PG8_LAS unsigned char* lds, const Gemm g, const StaticOrder& S, const Epi& E) {
;     ...
;             PG8_LDB(B0, 1, 0); PG8_LDB(B1, 1, 1); PG8_SCHED; PG8_LDA(At, 1, 0); PG8_STAGE(PG8_SA(0, 1), a2 + hstepA, voffA);
;             PG8_WAIT_V(8); PG8_WAIT_L(0); PG8_BAR; PG8_MMA(0, 0, At, B0); PG8_MMA(0, 1, At, B1); PG8_BAR; PG8_SCHED;
.Lp3_2032:
	s_add_i32 s87, 0, 0x18000
	v_add_u32_e32 v154, s87, v159
	s_add_i32 s88, 0, 0x1c000
	ds_read_b128 v[140:143], v154
	ds_read_b128 v[148:151], v154 offset:1024
	ds_read_b128 v[162:165], v154 offset:2048
	ds_read_b128 v[166:169], v154 offset:3072
	v_add_u32_e32 v154, s88, v159
	ds_read_b128 v[170:173], v154
	ds_read_b128 v[174:177], v154 offset:1024
	ds_read_b128 v[178:181], v154 offset:2048
	ds_read_b128 v[182:185], v154 offset:3072
	s_add_u32 s44, s44, 0x40000
	s_addc_u32 s45, s45, 0
	s_mov_b32 m0, s70
	v_lshl_add_u64 v[228:229], s[44:45], 0, v[130:131]
	ds_read_b128 v[186:189], v161 offset:32768
	ds_read_b128 v[190:193], v161 offset:33792
	ds_read_b128 v[194:197], v161 offset:34816
	ds_read_b128 v[198:201], v161 offset:35840
	ds_read_b128 v[208:211], v161 offset:36864
	ds_read_b128 v[216:219], v161 offset:37888
	ds_read_b128 v[220:223], v161 offset:38912
	ds_read_b128 v[224:227], v161 offset:39936
	global_load_lds_dwordx4 v[228:229], off
	v_lshl_add_u64 v[228:229], s[44:45], 0, v[132:133]
	s_mov_b32 m0, s71
	s_nop 0
	global_load_lds_dwordx4 v[228:229], off
	s_waitcnt vmcnt(8)
	s_waitcnt lgkmcnt(0)
	s_barrier
	s_setprio 1
	v_mfma_f32_16x16x32_bf16 v[126:129], v[140:143], v[186:189], v[126:129]
	v_mfma_f32_16x16x32_bf16 v[122:125], v[162:165], v[186:189], v[122:125]
	v_mfma_f32_16x16x32_bf16 v[110:113], v[140:143], v[194:197], v[110:113]
	v_mfma_f32_16x16x32_bf16 v[106:109], v[162:165], v[194:197], v[106:109]
	v_mfma_f32_16x16x32_bf16 v[94:97], v[140:143], v[208:211], v[94:97]
	v_mfma_f32_16x16x32_bf16 v[90:93], v[162:165], v[208:211], v[90:93]
	v_mfma_f32_16x16x32_bf16 v[78:81], v[140:143], v[220:223], v[78:81]
	v_mfma_f32_16x16x32_bf16 v[74:77], v[162:165], v[220:223], v[74:77]
	v_mfma_f32_16x16x32_bf16 v[126:129], v[148:151], v[190:193], v[126:129]
	v_mfma_f32_16x16x32_bf16 v[122:125], v[166:169], v[190:193], v[122:125]
	v_mfma_f32_16x16x32_bf16 v[110:113], v[148:151], v[198:201], v[110:113]
	v_mfma_f32_16x16x32_bf16 v[106:109], v[166:169], v[198:201], v[106:109]
	v_mfma_f32_16x16x32_bf16 v[94:97], v[148:151], v[216:219], v[94:97]
	v_mfma_f32_16x16x32_bf16 v[90:93], v[166:169], v[216:219], v[90:93]
	v_mfma_f32_16x16x32_bf16 v[78:81], v[148:151], v[224:227], v[78:81]
	v_mfma_f32_16x16x32_bf16 v[74:77], v[166:169], v[224:227], v[74:77]
	v_mfma_f32_16x16x32_bf16 v[118:121], v[170:173], v[186:189], v[118:121]
	v_mfma_f32_16x16x32_bf16 v[114:117], v[178:181], v[186:189], v[114:117]
	v_mfma_f32_16x16x32_bf16 v[102:105], v[170:173], v[194:197], v[102:105]
	v_mfma_f32_16x16x32_bf16 v[98:101], v[178:181], v[194:197], v[98:101]
	v_mfma_f32_16x16x32_bf16 v[86:89], v[170:173], v[208:211], v[86:89]
	v_mfma_f32_16x16x32_bf16 v[82:85], v[178:181], v[208:211], v[82:85]
	v_mfma_f32_16x16x32_bf16 v[70:73], v[170:173], v[220:223], v[70:73]
	v_mfma_f32_16x16x32_bf16 v[66:69], v[178:181], v[220:223], v[66:69]
	v_mfma_f32_16x16x32_bf16 v[118:121], v[174:177], v[190:193], v[118:121]
	v_mfma_f32_16x16x32_bf16 v[114:117], v[182:185], v[190:193], v[114:117]
	v_mfma_f32_16x16x32_bf16 v[102:105], v[174:177], v[198:201], v[102:105]
	v_mfma_f32_16x16x32_bf16 v[98:101], v[182:185], v[198:201], v[98:101]
	v_mfma_f32_16x16x32_bf16 v[86:89], v[174:177], v[216:219], v[86:89]
	v_mfma_f32_16x16x32_bf16 v[82:85], v[182:185], v[216:219], v[82:85]
	v_mfma_f32_16x16x32_bf16 v[70:73], v[174:177], v[224:227], v[70:73]
	v_mfma_f32_16x16x32_bf16 v[66:69], v[182:185], v[224:227], v[66:69]
	s_setprio 0
	s_barrier
; #define PG8_STAGE(bufoff, gbase, voff) do { _Pragma("unroll") for (int _i = 0; _i < 2; ++_i) \
;         __builtin_amdgcn_global_load_lds((const unsigned*)((const char*)(gbase) + (voff)[_i]), (PG8_LAS unsigned*)(lds + (bufoff) + ldsw + _i * 8192), 16, 0, 0); } while (0)
; #define PG8_LDA(dst, b, h) do { _Pragma("unroll") for (int m = 0; m < 4; ++m) _Pragma("unroll") for (int k = 0; k < 2; ++k) dst[m][k] = *(const PG8_LAS bf16x8*)(lds + PG8_SA(b, h) + aoff + m * 2048 + k * 1024); } while (0)
; #define PG8_WAIT_V(n) asm volatile("s_waitcnt vmcnt(" #n ")" ::: "memory")
; #define PG8_WAIT_L(n) asm volatile("s_waitcnt lgkmcnt(" #n ")" ::: "memory")
; #define PG8_BAR __builtin_amdgcn_s_barrier()
; #define PG8_SCHED __builtin_amdgcn_sched_barrier(0)
; template <class Epi, bool ALIGN_EPI = true>
; __device__ __forceinline__ void gemm_phase(PG8_LAS unsigned char* lds, const Gemm g, const StaticOrder& S, const Epi& E) {
;     ...
;         for (int t = 0; t < nt; t += 2) {
;             const bool last = (t == nt - 2);
;             const char* a1 = cA + (size_t)(t + 1) * kstep;
;             const char* a2 = last ? nA : cA + (size_t)(t + 2) * kstep; const char* b2 = last ? nB : cB + (size_t)(t + 2) * kstep;
;     ...
;             PG8_LDA(At, 1, 1); PG8_STAGE(PG8_SB(1, 0), b3, voffB); PG8_STAGE(PG8_SB(1, 1), b3 + hstepB, voffB); PG8_STAGE(PG8_SA(1, 0), a3, voffA);
;             PG8_WAIT_V(8); PG8_WAIT_L(0); PG8_BAR; PG8_MMA(1, 0, At, B0); PG8_MMA(1, 1, At, B1); PG8_BAR; PG8_SCHED;
	s_add_i32 s44, s87, s53
	v_lshl_add_u64 v[144:145], v[144:145], 0, s[60:61]
	s_mov_b32 m0, s44
	ds_read_b128 v[186:189], v161 offset:49152
	ds_read_b128 v[190:193], v161 offset:50176
	ds_read_b128 v[194:197], v161 offset:51200
	ds_read_b128 v[198:201], v161 offset:52224
	ds_read_b128 v[208:211], v161 offset:53248
	ds_read_b128 v[216:219], v161 offset:54272
	ds_read_b128 v[220:223], v161 offset:55296
	ds_read_b128 v[224:227], v161 offset:56320
	global_load_lds_dwordx4 v[144:145], off
	s_add_i32 m0, s44, 0x2000
	s_add_u32 s42, s42, 0x40080
	v_lshl_add_u64 v[144:145], v[146:147], 0, s[60:61]
	s_addc_u32 s43, s43, 0
	s_add_i32 s44, s88, s53
	global_load_lds_dwordx4 v[144:145], off
	v_lshl_add_u64 v[144:145], s[42:43], 0, v[32:33]
	s_mov_b32 m0, s44
	s_nop 0
	global_load_lds_dwordx4 v[144:145], off
	v_lshl_add_u64 v[144:145], s[42:43], 0, v[134:135]
	s_add_i32 m0, s44, 0x2000
	s_nop 0
	global_load_lds_dwordx4 v[144:145], off
	v_lshl_add_u64 v[144:145], v[204:205], 0, s[60:61]
	s_mov_b32 m0, s72
	s_nop 0
	global_load_lds_dwordx4 v[144:145], off
	v_lshl_add_u64 v[144:145], v[206:207], 0, s[60:61]
	s_mov_b32 m0, s73
	s_nop 0
	global_load_lds_dwordx4 v[144:145], off
	s_add_i32 s86, s86, 2
	s_add_u32 s40, s40, 0x100
	s_addc_u32 s41, s41, 0
	s_add_u32 s83, s83, 0x100
	s_addc_u32 s85, s85, 0
	s_add_u32 s42, s40, 0xfffc0080
	s_addc_u32 s43, s41, -1
	s_add_i32 s87, 0, 0x10000
	s_cmp_eq_u32 s86, 12
	s_cselect_b32 s45, s29, s43
	s_cselect_b32 s44, s37, s42
	v_add_u32_e32 v144, s87, v159
	s_cselect_b32 s43, s27, s85
	s_cselect_b32 s42, s82, s83
	s_add_i32 s90, 0, 0x14000
	s_cmp_gt_u32 s86, 13
	s_waitcnt vmcnt(8)
	s_waitcnt lgkmcnt(0)
	s_barrier
	s_setprio 1
	v_mfma_f32_16x16x32_bf16 v[62:65], v[140:143], v[186:189], v[62:65]
	v_mfma_f32_16x16x32_bf16 v[58:61], v[162:165], v[186:189], v[58:61]
	v_mfma_f32_16x16x32_bf16 v[46:49], v[140:143], v[194:197], v[46:49]
	v_mfma_f32_16x16x32_bf16 v[42:45], v[162:165], v[194:197], v[42:45]
	v_mfma_f32_16x16x32_bf16 v[28:31], v[140:143], v[208:211], v[28:31]
	v_mfma_f32_16x16x32_bf16 v[24:27], v[162:165], v[208:211], v[24:27]
	v_mfma_f32_16x16x32_bf16 v[12:15], v[140:143], v[220:223], v[12:15]
	v_mfma_f32_16x16x32_bf16 v[8:11], v[162:165], v[220:223], v[8:11]
	v_mfma_f32_16x16x32_bf16 v[62:65], v[148:151], v[190:193], v[62:65]
	v_mfma_f32_16x16x32_bf16 v[58:61], v[166:169], v[190:193], v[58:61]
	v_mfma_f32_16x16x32_bf16 v[46:49], v[148:151], v[198:201], v[46:49]
	v_mfma_f32_16x16x32_bf16 v[42:45], v[166:169], v[198:201], v[42:45]
	v_mfma_f32_16x16x32_bf16 v[28:31], v[148:151], v[216:219], v[28:31]
	v_mfma_f32_16x16x32_bf16 v[24:27], v[166:169], v[216:219], v[24:27]
	v_mfma_f32_16x16x32_bf16 v[12:15], v[148:151], v[224:227], v[12:15]
	v_mfma_f32_16x16x32_bf16 v[8:11], v[166:169], v[224:227], v[8:11]
	v_mfma_f32_16x16x32_bf16 v[54:57], v[170:173], v[186:189], v[54:57]
	v_mfma_f32_16x16x32_bf16 v[50:53], v[178:181], v[186:189], v[50:53]
	v_mfma_f32_16x16x32_bf16 v[38:41], v[170:173], v[194:197], v[38:41]
	v_mfma_f32_16x16x32_bf16 v[34:37], v[178:181], v[194:197], v[34:37]
	v_mfma_f32_16x16x32_bf16 v[20:23], v[170:173], v[208:211], v[20:23]
	v_mfma_f32_16x16x32_bf16 v[16:19], v[178:181], v[208:211], v[16:19]
	v_mfma_f32_16x16x32_bf16 v[4:7], v[170:173], v[220:223], v[4:7]
	v_mfma_f32_16x16x32_bf16 v[0:3], v[178:181], v[220:223], v[0:3]
	v_mfma_f32_16x16x32_bf16 v[54:57], v[174:177], v[190:193], v[54:57]
	v_mfma_f32_16x16x32_bf16 v[50:53], v[182:185], v[190:193], v[50:53]
	v_mfma_f32_16x16x32_bf16 v[38:41], v[174:177], v[198:201], v[38:41]
	v_mfma_f32_16x16x32_bf16 v[34:37], v[182:185], v[198:201], v[34:37]
	v_mfma_f32_16x16x32_bf16 v[20:23], v[174:177], v[216:219], v[20:23]
	v_mfma_f32_16x16x32_bf16 v[16:19], v[182:185], v[216:219], v[16:19]
	v_mfma_f32_16x16x32_bf16 v[4:7], v[174:177], v[224:227], v[4:7]
	v_mfma_f32_16x16x32_bf16 v[0:3], v[182:185], v[224:227], v[0:3]
	s_setprio 0
	s_barrier
	s_cbranch_scc0 .Lrot_2032
	s_and_b64 vcc, exec, s[14:15]
	s_cbranch_vccz .LBB0_2035
	s_barrier

; #define PG8_STAGE(bufoff, gbase, voff) do { _Pragma("unroll") for (int _i = 0; _i < 2; ++_i) \
;         __builtin_amdgcn_global_load_lds((const unsigned*)((const char*)(gbase) + (voff)[_i]), (PG8_LAS unsigned*)(lds + (bufoff) + ldsw + _i * 8192), 16, 0, 0); } while (0)
; #define PG8_LDA(dst, b, h) do { _Pragma("unroll") for (int m = 0; m < 4; ++m) _Pragma("unroll") for (int k = 0; k < 2; ++k) dst[m][k] = *(const PG8_LAS bf16x8*)(lds + PG8_SA(b, h) + aoff + m * 2048 + k * 1024); } while (0)
; #define PG8_LDB(dst, b, h) do { _Pragma("unroll") for (int n = 0; n < 2; ++n) _Pragma("unroll") for (int k = 0; k < 2; ++k) dst[n][k] = *(const PG8_LAS bf16x8*)(lds + PG8_SB(b, h) + boff + n * 2048 + k * 1024); } while (0)
; #define PG8_WAIT_V(n) asm volatile("s_waitcnt vmcnt(" #n ")" ::: "memory")
; #define PG8_WAIT_L(n) asm volatile("s_waitcnt lgkmcnt(" #n ")" ::: "memory")
; #define PG8_BAR __builtin_amdgcn_s_barrier()
; #define PG8_SCHED __builtin_amdgcn_sched_barrier(0)
; template <class Epi, bool ALIGN_EPI = true>
; __device__ __forceinline__ void gemm_phase(PG8_LAS unsigned char* lds, const Gemm g, const StaticOrder& S, const Epi& E) {
;     ...
;         const char* nA = has_next ? (const char*)g.A + (size_t)nxt.pm * tstepA + (size_t)nxt.ks * ksA : cA; const char* nB = has_next ? (const char*)g.Bt + (size_t)nxt.pn * tstepB + (size_t)nxt.ks * ksA : cB;
;         for (int t = 0; t < nt; t += 2) {
;             const bool last = (t == nt - 2);
;             const char* a1 = cA + (size_t)(t + 1) * kstep;
;             const char* a2 = last ? nA : cA + (size_t)(t + 2) * kstep; const char* b2 = last ? nB : cB + (size_t)(t + 2) * kstep;
;             const char* a3 = a2 + kstep; const char* b3 = b2 + kstep;
;             PG8_LDB(B0, 0, 0); PG8_LDB(B1, 0, 1); PG8_SCHED; PG8_LDA(At, 0, 0); PG8_STAGE(PG8_SA(1, 1), a1 + hstepA, voffA);
;             PG8_WAIT_V(8); PG8_WAIT_L(0); PG8_BAR; PG8_MMA(0, 0, At, B0); PG8_MMA(0, 1, At, B1); PG8_BAR; PG8_SCHED;
;             PG8_LDA(At, 0, 1); PG8_STAGE(PG8_SB(0, 0), b2, voffB); PG8_STAGE(PG8_SB(0, 1), b2 + hstepB, voffB); PG8_STAGE(PG8_SA(0, 0), a2, voffA);
;             PG8_WAIT_V(8); PG8_WAIT_L(0); PG8_BAR; PG8_MMA(1, 0, At, B0); PG8_MMA(1, 1, At, B1); PG8_BAR; PG8_SCHED;
.LBB0_2118:
	s_ashr_i32 s35, s34, 31
	s_lshl_b64 s[38:39], s[34:35], 21
	s_add_u32 s7, s51, s38
	s_addc_u32 s35, s52, s39
	s_ashr_i32 s31, s30, 31
	s_lshl_b64 s[40:41], s[30:31], 9
	s_add_u32 s38, s7, s40
	s_addc_u32 s39, s35, s41
	s_and_b64 s[42:43], s[2:3], exec
	s_cselect_b32 s47, s39, s45
	s_cselect_b32 s46, s38, s44
	s_ashr_i32 s37, s36, 31
	s_lshl_b64 s[42:43], s[36:37], 21
	s_add_u32 s7, s53, s42
	s_addc_u32 s31, s66, s43
	s_add_u32 s40, s7, s40
	s_addc_u32 s41, s31, s41
	s_and_b64 s[42:43], s[2:3], exec
	s_cselect_b32 s43, s41, s49
	s_cselect_b32 s42, s40, s48
	s_add_i32 s77, 0, 0x10000
	s_add_i32 s35, 0, 0x14000
	v_add_u32_e32 v154, s77, v139
	v_add_u32_e32 v155, s35, v139
	ds_read_b128 v[0:3], v154
	ds_read_b128 v[4:7], v154 offset:1024
	ds_read_b128 v[8:11], v154 offset:2048
	ds_read_b128 v[12:15], v154 offset:3072
	ds_read_b128 v[16:19], v155
	ds_read_b128 v[20:23], v155 offset:1024
	ds_read_b128 v[24:27], v155 offset:2048
	ds_read_b128 v[28:31], v155 offset:3072
	s_add_u32 s86, s44, 0x100080
	s_addc_u32 s87, s45, 0
	s_add_i32 s83, s9, 0xc000
	v_lshl_add_u64 v[66:67], s[86:87], 0, v[136:137]
	s_mov_b32 m0, s83
	s_add_i32 s7, s9, 0xe000
	ds_read_b128 v[34:37], v143
	ds_read_b128 v[38:41], v143 offset:1024
	ds_read_b128 v[42:45], v143 offset:2048
	ds_read_b128 v[46:49], v143 offset:3072
	ds_read_b128 v[50:53], v143 offset:4096
	ds_read_b128 v[54:57], v143 offset:5120
	ds_read_b128 v[58:61], v143 offset:6144
	ds_read_b128 v[62:65], v143 offset:7168
	global_load_lds_dwordx4 v[66:67], off
	v_lshl_add_u64 v[66:67], s[86:87], 0, v[132:133]
	s_mov_b32 m0, s7
	s_nop 0
	global_load_lds_dwordx4 v[66:67], off
	s_waitcnt vmcnt(8)
	s_waitcnt lgkmcnt(0)
	s_barrier
	s_setprio 1
	v_mfma_f32_16x16x32_bf16 v[66:69], v[0:3], v[34:37], 0
	v_mfma_f32_16x16x32_bf16 v[70:73], v[8:11], v[34:37], 0
	v_mfma_f32_16x16x32_bf16 v[74:77], v[0:3], v[42:45], 0
	v_mfma_f32_16x16x32_bf16 v[78:81], v[8:11], v[42:45], 0
	v_mfma_f32_16x16x32_bf16 v[82:85], v[0:3], v[50:53], 0
	v_mfma_f32_16x16x32_bf16 v[86:89], v[8:11], v[50:53], 0
	v_mfma_f32_16x16x32_bf16 v[90:93], v[0:3], v[58:61], 0
	v_mfma_f32_16x16x32_bf16 v[94:97], v[8:11], v[58:61], 0
	v_mfma_f32_16x16x32_bf16 v[66:69], v[4:7], v[38:41], v[66:69]
	v_mfma_f32_16x16x32_bf16 v[70:73], v[12:15], v[38:41], v[70:73]
	v_mfma_f32_16x16x32_bf16 v[74:77], v[4:7], v[46:49], v[74:77]
	v_mfma_f32_16x16x32_bf16 v[78:81], v[12:15], v[46:49], v[78:81]
	v_mfma_f32_16x16x32_bf16 v[82:85], v[4:7], v[54:57], v[82:85]
	v_mfma_f32_16x16x32_bf16 v[86:89], v[12:15], v[54:57], v[86:89]
	v_mfma_f32_16x16x32_bf16 v[90:93], v[4:7], v[62:65], v[90:93]
	v_mfma_f32_16x16x32_bf16 v[94:97], v[12:15], v[62:65], v[94:97]
	v_mfma_f32_16x16x32_bf16 v[98:101], v[16:19], v[34:37], 0
	v_mfma_f32_16x16x32_bf16 v[34:37], v[24:27], v[34:37], 0
	v_mfma_f32_16x16x32_bf16 v[98:101], v[20:23], v[38:41], v[98:101]
	v_mfma_f32_16x16x32_bf16 v[34:37], v[28:31], v[38:41], v[34:37]
	v_mfma_f32_16x16x32_bf16 v[38:41], v[16:19], v[42:45], 0
	v_mfma_f32_16x16x32_bf16 v[42:45], v[24:27], v[42:45], 0
	v_mfma_f32_16x16x32_bf16 v[38:41], v[20:23], v[46:49], v[38:41]
	v_mfma_f32_16x16x32_bf16 v[42:45], v[28:31], v[46:49], v[42:45]
	v_mfma_f32_16x16x32_bf16 v[46:49], v[16:19], v[50:53], 0
	v_mfma_f32_16x16x32_bf16 v[50:53], v[24:27], v[50:53], 0
	v_mfma_f32_16x16x32_bf16 v[46:49], v[20:23], v[54:57], v[46:49]
	v_mfma_f32_16x16x32_bf16 v[50:53], v[28:31], v[54:57], v[50:53]
	v_mfma_f32_16x16x32_bf16 v[54:57], v[16:19], v[58:61], 0
	v_mfma_f32_16x16x32_bf16 v[58:61], v[24:27], v[58:61], 0
	v_mfma_f32_16x16x32_bf16 v[54:57], v[20:23], v[62:65], v[54:57]
	v_mfma_f32_16x16x32_bf16 v[58:61], v[28:31], v[62:65], v[58:61]
	s_setprio 0
	s_barrier
	v_lshl_add_u64 v[144:145], s[48:49], 0, v[134:135]
	s_add_i32 s77, s77, s67
	v_lshl_add_u64 v[146:147], v[144:145], 0, s[64:65]
	s_mov_b32 m0, s77
	s_add_i32 s31, s77, 0x2000
	ds_read_b128 v[62:65], v143 offset:16384
	ds_read_b128 v[102:105], v143 offset:17408
	ds_read_b128 v[106:109], v143 offset:18432
	ds_read_b128 v[110:113], v143 offset:19456
	ds_read_b128 v[114:117], v143 offset:20480
	ds_read_b128 v[118:121], v143 offset:21504
	ds_read_b128 v[122:125], v143 offset:22528
	ds_read_b128 v[126:129], v143 offset:23552
	global_load_lds_dwordx4 v[146:147], off
	v_lshl_add_u64 v[146:147], s[48:49], 0, v[130:131]
	s_add_u32 s86, s48, 0x100100
	v_lshl_add_u64 v[148:149], v[146:147], 0, s[64:65]
	s_mov_b32 m0, s31
	s_addc_u32 s87, s49, 0
	s_add_i32 s35, s35, s67
	global_load_lds_dwordx4 v[148:149], off
	v_lshl_add_u64 v[148:149], s[86:87], 0, v[134:135]
	s_mov_b32 m0, s35
	s_add_i32 s37, s35, 0x2000
	global_load_lds_dwordx4 v[148:149], off
	v_lshl_add_u64 v[148:149], s[86:87], 0, v[130:131]
	s_mov_b32 m0, s37
	v_lshl_add_u64 v[204:205], s[44:45], 0, v[136:137]
	global_load_lds_dwordx4 v[148:149], off
	v_lshl_add_u64 v[148:149], v[204:205], 0, s[64:65]
	s_mov_b32 m0, s9
	v_lshl_add_u64 v[206:207], s[44:45], 0, v[132:133]
	global_load_lds_dwordx4 v[148:149], off
	v_lshl_add_u64 v[148:149], v[206:207], 0, s[64:65]
	s_mov_b32 m0, s29
	s_nop 0
	global_load_lds_dwordx4 v[148:149], off
	s_waitcnt vmcnt(8)
	s_waitcnt lgkmcnt(0)
	s_barrier
; #define PG8_STAGE(bufoff, gbase, voff) do { _Pragma("unroll") for (int _i = 0; _i < 2; ++_i) \
;         __builtin_amdgcn_global_load_lds((const unsigned*)((const char*)(gbase) + (voff)[_i]), (PG8_LAS unsigned*)(lds + (bufoff) + ldsw + _i * 8192), 16, 0, 0); } while (0)
; #define PG8_LDA(dst, b, h) do { _Pragma("unroll") for (int m = 0; m < 4; ++m) _Pragma("unroll") for (int k = 0; k < 2; ++k) dst[m][k] = *(const PG8_LAS bf16x8*)(lds + PG8_SA(b, h) + aoff + m * 2048 + k * 1024); } while (0)
; #define PG8_LDB(dst, b, h) do { _Pragma("unroll") for (int n = 0; n < 2; ++n) _Pragma("unroll") for (int k = 0; k < 2; ++k) dst[n][k] = *(const PG8_LAS bf16x8*)(lds + PG8_SB(b, h) + boff + n * 2048 + k * 1024); } while (0)
; #define PG8_WAIT_V(n) asm volatile("s_waitcnt vmcnt(" #n ")" ::: "memory")
; #define PG8_WAIT_L(n) asm volatile("s_waitcnt lgkmcnt(" #n ")" ::: "memory")
; #define PG8_BAR __builtin_amdgcn_s_barrier()
; #define PG8_SCHED __builtin_amdgcn_sched_barrier(0)
; template <class Epi, bool ALIGN_EPI = true>
; __device__ __forceinline__ void gemm_phase(PG8_LAS unsigned char* lds, const Gemm g, const StaticOrder& S, const Epi& E) {
;     ...
;             PG8_WAIT_V(8); PG8_WAIT_L(0); PG8_BAR; PG8_MMA(1, 0, At, B0); PG8_MMA(1, 1, At, B1); PG8_BAR; PG8_SCHED;
;             PG8_LDB(B0, 1, 0); PG8_LDB(B1, 1, 1); PG8_SCHED; PG8_LDA(At, 1, 0); PG8_STAGE(PG8_SA(0, 1), a2 + hstepA, voffA);
;             PG8_WAIT_V(8); PG8_WAIT_L(0); PG8_BAR; PG8_MMA(0, 0, At, B0); PG8_MMA(0, 1, At, B1); PG8_BAR; PG8_SCHED;
	s_setprio 1
	v_mfma_f32_16x16x32_bf16 v[148:151], v[0:3], v[62:65], 0
	v_mfma_f32_16x16x32_bf16 v[162:165], v[0:3], v[106:109], 0
	v_mfma_f32_16x16x32_bf16 v[170:173], v[0:3], v[114:117], 0
	v_mfma_f32_16x16x32_bf16 v[0:3], v[0:3], v[122:125], 0
	v_mfma_f32_16x16x32_bf16 v[148:151], v[4:7], v[102:105], v[148:151]
	v_mfma_f32_16x16x32_bf16 v[162:165], v[4:7], v[110:113], v[162:165]
	v_mfma_f32_16x16x32_bf16 v[170:173], v[4:7], v[118:121], v[170:173]
	v_mfma_f32_16x16x32_bf16 v[0:3], v[4:7], v[126:129], v[0:3]
	v_mfma_f32_16x16x32_bf16 v[4:7], v[8:11], v[122:125], 0
	v_mfma_f32_16x16x32_bf16 v[158:161], v[8:11], v[62:65], 0
	v_mfma_f32_16x16x32_bf16 v[166:169], v[8:11], v[106:109], 0
	v_mfma_f32_16x16x32_bf16 v[174:177], v[8:11], v[114:117], 0
	v_mfma_f32_16x16x32_bf16 v[4:7], v[12:15], v[126:129], v[4:7]
	v_mfma_f32_16x16x32_bf16 v[158:161], v[12:15], v[102:105], v[158:161]
	v_mfma_f32_16x16x32_bf16 v[166:169], v[12:15], v[110:113], v[166:169]
	v_mfma_f32_16x16x32_bf16 v[174:177], v[12:15], v[118:121], v[174:177]
	v_mfma_f32_16x16x32_bf16 v[8:11], v[16:19], v[62:65], 0
	v_mfma_f32_16x16x32_bf16 v[12:15], v[24:27], v[62:65], 0
	v_mfma_f32_16x16x32_bf16 v[8:11], v[20:23], v[102:105], v[8:11]
	v_mfma_f32_16x16x32_bf16 v[12:15], v[28:31], v[102:105], v[12:15]
	v_mfma_f32_16x16x32_bf16 v[62:65], v[16:19], v[106:109], 0
	v_mfma_f32_16x16x32_bf16 v[102:105], v[24:27], v[106:109], 0
	v_mfma_f32_16x16x32_bf16 v[106:109], v[16:19], v[114:117], 0
	v_mfma_f32_16x16x32_bf16 v[16:19], v[16:19], v[122:125], 0
	v_mfma_f32_16x16x32_bf16 v[62:65], v[20:23], v[110:113], v[62:65]
	v_mfma_f32_16x16x32_bf16 v[102:105], v[28:31], v[110:113], v[102:105]
	v_mfma_f32_16x16x32_bf16 v[106:109], v[20:23], v[118:121], v[106:109]
	v_mfma_f32_16x16x32_bf16 v[110:113], v[24:27], v[114:117], 0
	v_mfma_f32_16x16x32_bf16 v[16:19], v[20:23], v[126:129], v[16:19]
	v_mfma_f32_16x16x32_bf16 v[20:23], v[24:27], v[122:125], 0
	v_mfma_f32_16x16x32_bf16 v[110:113], v[28:31], v[118:121], v[110:113]
	v_mfma_f32_16x16x32_bf16 v[20:23], v[28:31], v[126:129], v[20:23]
	s_setprio 0
	s_barrier
	s_add_i32 s85, 0, 0x18000
	s_add_i32 s88, 0, 0x1c000
	v_add_u32_e32 v240, s85, v139
	v_add_u32_e32 v244, s88, v139
	ds_read_b128 v[24:27], v240
	ds_read_b128 v[28:31], v240 offset:1024
	ds_read_b128 v[114:117], v240 offset:2048
	ds_read_b128 v[118:121], v240 offset:3072
	ds_read_b128 v[122:125], v244
	ds_read_b128 v[126:129], v244 offset:1024
	ds_read_b128 v[178:181], v244 offset:2048
	ds_read_b128 v[182:185], v244 offset:3072
	s_add_u32 s86, s44, 0x100100
	s_addc_u32 s87, s45, 0
	s_mov_b32 m0, s70
	v_lshl_add_u64 v[228:229], s[86:87], 0, v[136:137]
	ds_read_b128 v[186:189], v143 offset:32768
	ds_read_b128 v[190:193], v143 offset:33792
	ds_read_b128 v[194:197], v143 offset:34816
	ds_read_b128 v[198:201], v143 offset:35840
	ds_read_b128 v[208:211], v143 offset:36864
	ds_read_b128 v[216:219], v143 offset:37888
	ds_read_b128 v[220:223], v143 offset:38912
	ds_read_b128 v[224:227], v143 offset:39936
	global_load_lds_dwordx4 v[228:229], off
	v_lshl_add_u64 v[228:229], s[86:87], 0, v[132:133]
	s_mov_b32 m0, s71
	s_nop 0
	global_load_lds_dwordx4 v[228:229], off
	s_waitcnt vmcnt(8)
	s_waitcnt lgkmcnt(0)
	s_barrier
	s_setprio 1
	v_mfma_f32_16x16x32_bf16 v[66:69], v[24:27], v[186:189], v[66:69]
	v_mfma_f32_16x16x32_bf16 v[70:73], v[114:117], v[186:189], v[70:73]
	v_mfma_f32_16x16x32_bf16 v[74:77], v[24:27], v[194:197], v[74:77]
	v_mfma_f32_16x16x32_bf16 v[78:81], v[114:117], v[194:197], v[78:81]
	v_mfma_f32_16x16x32_bf16 v[82:85], v[24:27], v[208:211], v[82:85]
	v_mfma_f32_16x16x32_bf16 v[86:89], v[114:117], v[208:211], v[86:89]
	v_mfma_f32_16x16x32_bf16 v[90:93], v[24:27], v[220:223], v[90:93]
	v_mfma_f32_16x16x32_bf16 v[94:97], v[114:117], v[220:223], v[94:97]
	v_mfma_f32_16x16x32_bf16 v[66:69], v[28:31], v[190:193], v[66:69]
	v_mfma_f32_16x16x32_bf16 v[70:73], v[118:121], v[190:193], v[70:73]
	v_mfma_f32_16x16x32_bf16 v[74:77], v[28:31], v[198:201], v[74:77]
	v_mfma_f32_16x16x32_bf16 v[78:81], v[118:121], v[198:201], v[78:81]
	v_mfma_f32_16x16x32_bf16 v[82:85], v[28:31], v[216:219], v[82:85]
	v_mfma_f32_16x16x32_bf16 v[86:89], v[118:121], v[216:219], v[86:89]
	v_mfma_f32_16x16x32_bf16 v[90:93], v[28:31], v[224:227], v[90:93]
	v_mfma_f32_16x16x32_bf16 v[94:97], v[118:121], v[224:227], v[94:97]
	v_mfma_f32_16x16x32_bf16 v[98:101], v[122:125], v[186:189], v[98:101]
	v_mfma_f32_16x16x32_bf16 v[34:37], v[178:181], v[186:189], v[34:37]
	v_mfma_f32_16x16x32_bf16 v[38:41], v[122:125], v[194:197], v[38:41]
	v_mfma_f32_16x16x32_bf16 v[42:45], v[178:181], v[194:197], v[42:45]
	v_mfma_f32_16x16x32_bf16 v[46:49], v[122:125], v[208:211], v[46:49]
	v_mfma_f32_16x16x32_bf16 v[50:53], v[178:181], v[208:211], v[50:53]
	v_mfma_f32_16x16x32_bf16 v[54:57], v[122:125], v[220:223], v[54:57]
	v_mfma_f32_16x16x32_bf16 v[58:61], v[178:181], v[220:223], v[58:61]
	v_mfma_f32_16x16x32_bf16 v[98:101], v[126:129], v[190:193], v[98:101]
	v_mfma_f32_16x16x32_bf16 v[34:37], v[182:185], v[190:193], v[34:37]
	v_mfma_f32_16x16x32_bf16 v[38:41], v[126:129], v[198:201], v[38:41]
	v_mfma_f32_16x16x32_bf16 v[42:45], v[182:185], v[198:201], v[42:45]
	v_mfma_f32_16x16x32_bf16 v[46:49], v[126:129], v[216:219], v[46:49]
	v_mfma_f32_16x16x32_bf16 v[50:53], v[182:185], v[216:219], v[50:53]
	v_mfma_f32_16x16x32_bf16 v[54:57], v[126:129], v[224:227], v[54:57]
	v_mfma_f32_16x16x32_bf16 v[58:61], v[182:185], v[224:227], v[58:61]
	s_setprio 0
	s_barrier
; #define PG8_STAGE(bufoff, gbase, voff) do { _Pragma("unroll") for (int _i = 0; _i < 2; ++_i) \
;         __builtin_amdgcn_global_load_lds((const unsigned*)((const char*)(gbase) + (voff)[_i]), (PG8_LAS unsigned*)(lds + (bufoff) + ldsw + _i * 8192), 16, 0, 0); } while (0)
; #define PG8_LDA(dst, b, h) do { _Pragma("unroll") for (int m = 0; m < 4; ++m) _Pragma("unroll") for (int k = 0; k < 2; ++k) dst[m][k] = *(const PG8_LAS bf16x8*)(lds + PG8_SA(b, h) + aoff + m * 2048 + k * 1024); } while (0)
; #define PG8_LDB(dst, b, h) do { _Pragma("unroll") for (int n = 0; n < 2; ++n) _Pragma("unroll") for (int k = 0; k < 2; ++k) dst[n][k] = *(const PG8_LAS bf16x8*)(lds + PG8_SB(b, h) + boff + n * 2048 + k * 1024); } while (0)
; #define PG8_WAIT_V(n) asm volatile("s_waitcnt vmcnt(" #n ")" ::: "memory")
; #define PG8_WAIT_L(n) asm volatile("s_waitcnt lgkmcnt(" #n ")" ::: "memory")
; #define PG8_BAR __builtin_amdgcn_s_barrier()
; #define PG8_SCHED __builtin_amdgcn_sched_barrier(0)
; template <class Epi, bool ALIGN_EPI = true>
; __device__ __forceinline__ void gemm_phase(PG8_LAS unsigned char* lds, const Gemm g, const StaticOrder& S, const Epi& E) {
;     ...
;             PG8_LDB(B0, 0, 0); PG8_LDB(B1, 0, 1); PG8_SCHED; PG8_LDA(At, 0, 0); PG8_STAGE(PG8_SA(1, 1), a1 + hstepA, voffA);
;             PG8_WAIT_V(8); PG8_WAIT_L(0); PG8_BAR; PG8_MMA(0, 0, At, B0); PG8_MMA(0, 1, At, B1); PG8_BAR; PG8_SCHED;
;     ...
;             PG8_LDA(At, 1, 1); PG8_STAGE(PG8_SB(1, 0), b3, voffB); PG8_STAGE(PG8_SB(1, 1), b3 + hstepB, voffB); PG8_STAGE(PG8_SA(1, 0), a3, voffA);
;             PG8_WAIT_V(8); PG8_WAIT_L(0); PG8_BAR; PG8_MMA(1, 0, At, B0); PG8_MMA(1, 1, At, B1); PG8_BAR; PG8_SCHED;
	s_add_i32 s85, s85, s67
	s_add_i32 s82, s85, 0x2000
	v_lshl_add_u64 v[144:145], v[144:145], 0, s[68:69]
	s_mov_b32 m0, s85
	s_add_u32 s86, s48, 0x100180
	ds_read_b128 v[186:189], v143 offset:49152
	ds_read_b128 v[190:193], v143 offset:50176
	ds_read_b128 v[194:197], v143 offset:51200
	ds_read_b128 v[198:201], v143 offset:52224
	ds_read_b128 v[208:211], v143 offset:53248
	ds_read_b128 v[216:219], v143 offset:54272
	ds_read_b128 v[220:223], v143 offset:55296
	ds_read_b128 v[224:227], v143 offset:56320
	global_load_lds_dwordx4 v[144:145], off
	v_lshl_add_u64 v[144:145], v[146:147], 0, s[68:69]
	s_mov_b32 m0, s82
	s_addc_u32 s87, s49, 0
	s_add_i32 s48, s88, s67
	global_load_lds_dwordx4 v[144:145], off
	v_lshl_add_u64 v[144:145], s[86:87], 0, v[134:135]
	s_mov_b32 m0, s48
	s_add_i32 s49, s48, 0x2000
	global_load_lds_dwordx4 v[144:145], off
	v_lshl_add_u64 v[144:145], s[86:87], 0, v[130:131]
	s_mov_b32 m0, s49
	s_nop 0
	global_load_lds_dwordx4 v[144:145], off
	v_lshl_add_u64 v[144:145], v[204:205], 0, s[68:69]
	s_mov_b32 m0, s74
	s_nop 0
	global_load_lds_dwordx4 v[144:145], off
	v_lshl_add_u64 v[144:145], v[206:207], 0, s[68:69]
	s_mov_b32 m0, s75
	s_nop 0
	global_load_lds_dwordx4 v[144:145], off
	s_waitcnt vmcnt(8)
	s_waitcnt lgkmcnt(0)
	s_barrier
	s_setprio 1
	v_mfma_f32_16x16x32_bf16 v[0:3], v[24:27], v[220:223], v[0:3]
	v_mfma_f32_16x16x32_bf16 v[4:7], v[114:117], v[220:223], v[4:7]
	v_mfma_f32_16x16x32_bf16 v[148:151], v[24:27], v[186:189], v[148:151]
	v_mfma_f32_16x16x32_bf16 v[158:161], v[114:117], v[186:189], v[158:161]
	v_mfma_f32_16x16x32_bf16 v[162:165], v[24:27], v[194:197], v[162:165]
	v_mfma_f32_16x16x32_bf16 v[166:169], v[114:117], v[194:197], v[166:169]
	v_mfma_f32_16x16x32_bf16 v[170:173], v[24:27], v[208:211], v[170:173]
	v_mfma_f32_16x16x32_bf16 v[174:177], v[114:117], v[208:211], v[174:177]
	v_mfma_f32_16x16x32_bf16 v[0:3], v[28:31], v[224:227], v[0:3]
	v_mfma_f32_16x16x32_bf16 v[4:7], v[118:121], v[224:227], v[4:7]
	v_mfma_f32_16x16x32_bf16 v[148:151], v[28:31], v[190:193], v[148:151]
	v_mfma_f32_16x16x32_bf16 v[158:161], v[118:121], v[190:193], v[158:161]
	v_mfma_f32_16x16x32_bf16 v[162:165], v[28:31], v[198:201], v[162:165]
	v_mfma_f32_16x16x32_bf16 v[166:169], v[118:121], v[198:201], v[166:169]
	v_mfma_f32_16x16x32_bf16 v[170:173], v[28:31], v[216:219], v[170:173]
	v_mfma_f32_16x16x32_bf16 v[174:177], v[118:121], v[216:219], v[174:177]
	v_mfma_f32_16x16x32_bf16 v[8:11], v[122:125], v[186:189], v[8:11]
	v_mfma_f32_16x16x32_bf16 v[12:15], v[178:181], v[186:189], v[12:15]
	v_mfma_f32_16x16x32_bf16 v[24:27], v[122:125], v[194:197], v[62:65]
	v_mfma_f32_16x16x32_bf16 v[28:31], v[178:181], v[194:197], v[102:105]
	v_mfma_f32_16x16x32_bf16 v[62:65], v[122:125], v[208:211], v[106:109]
	v_mfma_f32_16x16x32_bf16 v[102:105], v[178:181], v[208:211], v[110:113]
	v_mfma_f32_16x16x32_bf16 v[16:19], v[122:125], v[220:223], v[16:19]
	v_mfma_f32_16x16x32_bf16 v[20:23], v[178:181], v[220:223], v[20:23]
	v_mfma_f32_16x16x32_bf16 v[8:11], v[126:129], v[190:193], v[8:11]
	v_mfma_f32_16x16x32_bf16 v[12:15], v[182:185], v[190:193], v[12:15]
	v_mfma_f32_16x16x32_bf16 v[24:27], v[126:129], v[198:201], v[24:27]
	v_mfma_f32_16x16x32_bf16 v[28:31], v[182:185], v[198:201], v[28:31]
	v_mfma_f32_16x16x32_bf16 v[62:65], v[126:129], v[216:219], v[62:65]
	v_mfma_f32_16x16x32_bf16 v[102:105], v[182:185], v[216:219], v[102:105]
	v_mfma_f32_16x16x32_bf16 v[16:19], v[126:129], v[224:227], v[16:19]
	v_mfma_f32_16x16x32_bf16 v[20:23], v[182:185], v[224:227], v[20:23]
	s_setprio 0
	s_barrier
	ds_read_b128 v[106:109], v154
	ds_read_b128 v[110:113], v154 offset:1024
	ds_read_b128 v[114:117], v154 offset:2048
	ds_read_b128 v[118:121], v154 offset:3072
	ds_read_b128 v[122:125], v155
	ds_read_b128 v[126:129], v155 offset:1024
	ds_read_b128 v[178:181], v155 offset:2048
	ds_read_b128 v[182:185], v155 offset:3072
	s_add_u32 s44, s44, 0x100180
	s_addc_u32 s45, s45, 0
	s_mov_b32 m0, s83
	v_lshl_add_u64 v[144:145], s[44:45], 0, v[136:137]
	ds_read_b128 v[186:189], v143
	ds_read_b128 v[190:193], v143 offset:1024
	ds_read_b128 v[194:197], v143 offset:2048
	ds_read_b128 v[198:201], v143 offset:3072
	ds_read_b128 v[208:211], v143 offset:4096
	ds_read_b128 v[216:219], v143 offset:5120
	ds_read_b128 v[220:223], v143 offset:6144
	ds_read_b128 v[224:227], v143 offset:7168
	global_load_lds_dwordx4 v[144:145], off
	v_lshl_add_u64 v[144:145], s[44:45], 0, v[132:133]
	s_mov_b32 m0, s7
	s_nop 0
	global_load_lds_dwordx4 v[144:145], off
	s_waitcnt vmcnt(8)
	s_waitcnt lgkmcnt(0)
	s_barrier
; #define PG8_STAGE(bufoff, gbase, voff) do { _Pragma("unroll") for (int _i = 0; _i < 2; ++_i) \
;         __builtin_amdgcn_global_load_lds((const unsigned*)((const char*)(gbase) + (voff)[_i]), (PG8_LAS unsigned*)(lds + (bufoff) + ldsw + _i * 8192), 16, 0, 0); } while (0)
; #define PG8_LDA(dst, b, h) do { _Pragma("unroll") for (int m = 0; m < 4; ++m) _Pragma("unroll") for (int k = 0; k < 2; ++k) dst[m][k] = *(const PG8_LAS bf16x8*)(lds + PG8_SA(b, h) + aoff + m * 2048 + k * 1024); } while (0)
; #define PG8_WAIT_V(n) asm volatile("s_waitcnt vmcnt(" #n ")" ::: "memory")
; #define PG8_WAIT_L(n) asm volatile("s_waitcnt lgkmcnt(" #n ")" ::: "memory")
; #define PG8_BAR __builtin_amdgcn_s_barrier()
; #define PG8_SCHED __builtin_amdgcn_sched_barrier(0)
; template <class Epi, bool ALIGN_EPI = true>
; __device__ __forceinline__ void gemm_phase(PG8_LAS unsigned char* lds, const Gemm g, const StaticOrder& S, const Epi& E) {
;     ...
;             PG8_WAIT_V(8); PG8_WAIT_L(0); PG8_BAR; PG8_MMA(0, 0, At, B0); PG8_MMA(0, 1, At, B1); PG8_BAR; PG8_SCHED;
;             PG8_LDA(At, 0, 1); PG8_STAGE(PG8_SB(0, 0), b2, voffB); PG8_STAGE(PG8_SB(0, 1), b2 + hstepB, voffB); PG8_STAGE(PG8_SA(0, 0), a2, voffA);
;             PG8_WAIT_V(8); PG8_WAIT_L(0); PG8_BAR; PG8_MMA(1, 0, At, B0); PG8_MMA(1, 1, At, B1); PG8_BAR; PG8_SCHED;
	s_setprio 1
	v_mfma_f32_16x16x32_bf16 v[66:69], v[106:109], v[186:189], v[66:69]
	v_mfma_f32_16x16x32_bf16 v[70:73], v[114:117], v[186:189], v[70:73]
	v_mfma_f32_16x16x32_bf16 v[74:77], v[106:109], v[194:197], v[74:77]
	v_mfma_f32_16x16x32_bf16 v[78:81], v[114:117], v[194:197], v[78:81]
	v_mfma_f32_16x16x32_bf16 v[82:85], v[106:109], v[208:211], v[82:85]
	v_mfma_f32_16x16x32_bf16 v[86:89], v[114:117], v[208:211], v[86:89]
	v_mfma_f32_16x16x32_bf16 v[90:93], v[106:109], v[220:223], v[90:93]
	v_mfma_f32_16x16x32_bf16 v[94:97], v[114:117], v[220:223], v[94:97]
	v_mfma_f32_16x16x32_bf16 v[66:69], v[110:113], v[190:193], v[66:69]
	v_mfma_f32_16x16x32_bf16 v[70:73], v[118:121], v[190:193], v[70:73]
	v_mfma_f32_16x16x32_bf16 v[74:77], v[110:113], v[198:201], v[74:77]
	v_mfma_f32_16x16x32_bf16 v[78:81], v[118:121], v[198:201], v[78:81]
	v_mfma_f32_16x16x32_bf16 v[82:85], v[110:113], v[216:219], v[82:85]
	v_mfma_f32_16x16x32_bf16 v[86:89], v[118:121], v[216:219], v[86:89]
	v_mfma_f32_16x16x32_bf16 v[90:93], v[110:113], v[224:227], v[90:93]
	v_mfma_f32_16x16x32_bf16 v[94:97], v[118:121], v[224:227], v[94:97]
	v_mfma_f32_16x16x32_bf16 v[50:53], v[178:181], v[208:211], v[50:53]
	v_mfma_f32_16x16x32_bf16 v[98:101], v[122:125], v[186:189], v[98:101]
	v_mfma_f32_16x16x32_bf16 v[34:37], v[178:181], v[186:189], v[34:37]
	v_mfma_f32_16x16x32_bf16 v[186:189], v[182:185], v[216:219], v[50:53]
	v_mfma_f32_16x16x32_bf16 v[50:53], v[122:125], v[220:223], v[54:57]
	v_mfma_f32_16x16x32_bf16 v[98:101], v[126:129], v[190:193], v[98:101]
	v_mfma_f32_16x16x32_bf16 v[34:37], v[182:185], v[190:193], v[34:37]
	v_mfma_f32_16x16x32_bf16 v[38:41], v[122:125], v[194:197], v[38:41]
	v_mfma_f32_16x16x32_bf16 v[42:45], v[178:181], v[194:197], v[42:45]
	v_mfma_f32_16x16x32_bf16 v[46:49], v[122:125], v[208:211], v[46:49]
	v_mfma_f32_16x16x32_bf16 v[190:193], v[126:129], v[224:227], v[50:53]
	v_mfma_f32_16x16x32_bf16 v[50:53], v[178:181], v[220:223], v[58:61]
	v_mfma_f32_16x16x32_bf16 v[38:41], v[126:129], v[198:201], v[38:41]
	v_mfma_f32_16x16x32_bf16 v[42:45], v[182:185], v[198:201], v[42:45]
	v_mfma_f32_16x16x32_bf16 v[46:49], v[126:129], v[216:219], v[46:49]
	v_mfma_f32_16x16x32_bf16 v[58:61], v[182:185], v[224:227], v[50:53]
	s_setprio 0
	s_barrier
	s_mov_b32 m0, s77
	v_lshl_add_u64 v[214:215], s[42:43], 0, v[134:135]
	s_add_u32 s44, s42, 0x100000
	ds_read_b128 v[50:53], v143 offset:16384
	ds_read_b128 v[54:57], v143 offset:17408
	ds_read_b128 v[194:197], v143 offset:18432
	ds_read_b128 v[198:201], v143 offset:19456
	ds_read_b128 v[208:211], v143 offset:20480
	ds_read_b128 v[216:219], v143 offset:21504
	ds_read_b128 v[220:223], v143 offset:22528
	ds_read_b128 v[224:227], v143 offset:23552
	global_load_lds_dwordx4 v[214:215], off
	v_lshl_add_u64 v[252:253], s[42:43], 0, v[130:131]
	s_mov_b32 m0, s31
	s_addc_u32 s45, s43, 0
	global_load_lds_dwordx4 v[252:253], off
	v_lshl_add_u64 v[144:145], s[44:45], 0, v[134:135]
	s_mov_b32 m0, s35
	v_lshl_add_u64 v[154:155], s[46:47], 0, v[136:137]
	global_load_lds_dwordx4 v[144:145], off
	v_lshl_add_u64 v[144:145], s[44:45], 0, v[130:131]
	s_mov_b32 m0, s37
	v_lshl_add_u64 v[156:157], s[46:47], 0, v[132:133]
	global_load_lds_dwordx4 v[144:145], off
	s_mov_b32 m0, s9
	s_nop 0
	global_load_lds_dwordx4 v[154:155], off
	s_mov_b32 m0, s29
	s_nop 0
	global_load_lds_dwordx4 v[156:157], off
	s_waitcnt vmcnt(8)
	s_waitcnt lgkmcnt(0)
	s_barrier
	s_setprio 1
	v_mfma_f32_16x16x32_bf16 v[0:3], v[106:109], v[220:223], v[0:3]
	v_mfma_f32_16x16x32_bf16 v[228:231], v[110:113], v[224:227], v[0:3]
	v_mfma_f32_16x16x32_bf16 v[0:3], v[114:117], v[220:223], v[4:7]
	v_mfma_f32_16x16x32_bf16 v[148:151], v[106:109], v[50:53], v[148:151]
	v_mfma_f32_16x16x32_bf16 v[158:161], v[114:117], v[50:53], v[158:161]
	v_mfma_f32_16x16x32_bf16 v[162:165], v[106:109], v[194:197], v[162:165]
	v_mfma_f32_16x16x32_bf16 v[166:169], v[114:117], v[194:197], v[166:169]
	v_mfma_f32_16x16x32_bf16 v[170:173], v[106:109], v[208:211], v[170:173]
	v_mfma_f32_16x16x32_bf16 v[174:177], v[114:117], v[208:211], v[174:177]
	v_mfma_f32_16x16x32_bf16 v[114:117], v[118:121], v[224:227], v[0:3]
	v_mfma_f32_16x16x32_bf16 v[148:151], v[110:113], v[54:57], v[148:151]
	v_mfma_f32_16x16x32_bf16 v[158:161], v[118:121], v[54:57], v[158:161]
	v_mfma_f32_16x16x32_bf16 v[162:165], v[110:113], v[198:201], v[162:165]
	v_mfma_f32_16x16x32_bf16 v[166:169], v[118:121], v[198:201], v[166:169]
	v_mfma_f32_16x16x32_bf16 v[170:173], v[110:113], v[216:219], v[170:173]
	v_mfma_f32_16x16x32_bf16 v[174:177], v[118:121], v[216:219], v[174:177]
	v_mfma_f32_16x16x32_bf16 v[0:3], v[122:125], v[50:53], v[8:11]
	v_mfma_f32_16x16x32_bf16 v[118:121], v[126:129], v[54:57], v[0:3]
	v_mfma_f32_16x16x32_bf16 v[0:3], v[178:181], v[50:53], v[12:15]
	v_mfma_f32_16x16x32_bf16 v[232:235], v[182:185], v[54:57], v[0:3]
	v_mfma_f32_16x16x32_bf16 v[0:3], v[122:125], v[194:197], v[24:27]
	v_mfma_f32_16x16x32_bf16 v[236:239], v[126:129], v[198:201], v[0:3]
	v_mfma_f32_16x16x32_bf16 v[0:3], v[178:181], v[194:197], v[28:31]
	v_mfma_f32_16x16x32_bf16 v[194:197], v[182:185], v[198:201], v[0:3]
	v_mfma_f32_16x16x32_bf16 v[0:3], v[122:125], v[208:211], v[62:65]
	v_mfma_f32_16x16x32_bf16 v[198:201], v[126:129], v[216:219], v[0:3]
	v_mfma_f32_16x16x32_bf16 v[0:3], v[178:181], v[208:211], v[102:105]
	v_mfma_f32_16x16x32_bf16 v[102:105], v[182:185], v[216:219], v[0:3]
	v_mfma_f32_16x16x32_bf16 v[0:3], v[122:125], v[220:223], v[16:19]
	v_mfma_f32_16x16x32_bf16 v[208:211], v[126:129], v[224:227], v[0:3]
	v_mfma_f32_16x16x32_bf16 v[0:3], v[178:181], v[220:223], v[20:23]
	v_mfma_f32_16x16x32_bf16 v[178:181], v[182:185], v[224:227], v[0:3]
	s_setprio 0
	s_barrier
; #define PG8_STAGE(bufoff, gbase, voff) do { _Pragma("unroll") for (int _i = 0; _i < 2; ++_i) \
;         __builtin_amdgcn_global_load_lds((const unsigned*)((const char*)(gbase) + (voff)[_i]), (PG8_LAS unsigned*)(lds + (bufoff) + ldsw + _i * 8192), 16, 0, 0); } while (0)
; #define PG8_LDA(dst, b, h) do { _Pragma("unroll") for (int m = 0; m < 4; ++m) _Pragma("unroll") for (int k = 0; k < 2; ++k) dst[m][k] = *(const PG8_LAS bf16x8*)(lds + PG8_SA(b, h) + aoff + m * 2048 + k * 1024); } while (0)
; #define PG8_LDB(dst, b, h) do { _Pragma("unroll") for (int n = 0; n < 2; ++n) _Pragma("unroll") for (int k = 0; k < 2; ++k) dst[n][k] = *(const PG8_LAS bf16x8*)(lds + PG8_SB(b, h) + boff + n * 2048 + k * 1024); } while (0)
; #define PG8_WAIT_V(n) asm volatile("s_waitcnt vmcnt(" #n ")" ::: "memory")
; #define PG8_WAIT_L(n) asm volatile("s_waitcnt lgkmcnt(" #n ")" ::: "memory")
; #define PG8_BAR __builtin_amdgcn_s_barrier()
; #define PG8_SCHED __builtin_amdgcn_sched_barrier(0)
; template <class Epi, bool ALIGN_EPI = true>
; __device__ __forceinline__ void gemm_phase(PG8_LAS unsigned char* lds, const Gemm g, const StaticOrder& S, const Epi& E) {
;     ...
;             PG8_LDB(B0, 1, 0); PG8_LDB(B1, 1, 1); PG8_SCHED; PG8_LDA(At, 1, 0); PG8_STAGE(PG8_SA(0, 1), a2 + hstepA, voffA);
;             PG8_WAIT_V(8); PG8_WAIT_L(0); PG8_BAR; PG8_MMA(0, 0, At, B0); PG8_MMA(0, 1, At, B1); PG8_BAR; PG8_SCHED;
;             PG8_LDA(At, 1, 1); PG8_STAGE(PG8_SB(1, 0), b3, voffB); PG8_STAGE(PG8_SB(1, 1), b3 + hstepB, voffB); PG8_STAGE(PG8_SA(1, 0), a3, voffA);
;             PG8_WAIT_V(8); PG8_WAIT_L(0); PG8_BAR; PG8_MMA(1, 0, At, B0); PG8_MMA(1, 1, At, B1); PG8_BAR; PG8_SCHED;
;         }
;         if constexpr (ALIGN_EPI) { if (wr == 0) PG8_BAR; }
	ds_read_b128 v[122:125], v240
	ds_read_b128 v[126:129], v240 offset:1024
	ds_read_b128 v[182:185], v240 offset:2048
	ds_read_b128 v[216:219], v240 offset:3072
	ds_read_b128 v[220:223], v244
	ds_read_b128 v[224:227], v244 offset:1024
	ds_read_b128 v[240:243], v244 offset:2048
	ds_read_b128 v[244:247], v244 offset:3072
	s_add_u32 s44, s46, 0x100000
	s_addc_u32 s45, s47, 0
	s_mov_b32 m0, s70
	v_lshl_add_u64 v[0:1], s[44:45], 0, v[136:137]
	ds_read_b128 v[16:19], v143 offset:32768
	ds_read_b128 v[20:23], v143 offset:33792
	ds_read_b128 v[62:65], v143 offset:34816
	ds_read_b128 v[106:109], v143 offset:35840
	ds_read_b128 v[110:113], v143 offset:36864
	ds_read_b128 v[248:251], v143 offset:37888
	ds_read_b128 v[144:147], v143 offset:38912
	ds_read_b128 v[204:207], v143 offset:39936
	global_load_lds_dwordx4 v[0:1], off
	v_lshl_add_u64 v[0:1], s[44:45], 0, v[132:133]
	s_mov_b32 m0, s71
	s_nop 0
	global_load_lds_dwordx4 v[0:1], off
	s_waitcnt vmcnt(8)
	s_waitcnt lgkmcnt(0)
	s_barrier
	s_setprio 1
	v_mfma_f32_16x16x32_bf16 v[0:3], v[122:125], v[16:19], v[66:69]
	v_mfma_f32_16x16x32_bf16 v[50:53], v[126:129], v[20:23], v[0:3]
	v_mfma_f32_16x16x32_bf16 v[0:3], v[182:185], v[16:19], v[70:73]
	v_mfma_f32_16x16x32_bf16 v[54:57], v[216:219], v[20:23], v[0:3]
	v_mfma_f32_16x16x32_bf16 v[0:3], v[122:125], v[62:65], v[74:77]
	v_mfma_f32_16x16x32_bf16 v[24:27], v[126:129], v[106:109], v[0:3]
	v_mfma_f32_16x16x32_bf16 v[0:3], v[182:185], v[62:65], v[78:81]
	v_mfma_f32_16x16x32_bf16 v[28:31], v[216:219], v[106:109], v[0:3]
	v_mfma_f32_16x16x32_bf16 v[0:3], v[122:125], v[110:113], v[82:85]
	v_mfma_f32_16x16x32_bf16 v[8:11], v[126:129], v[248:251], v[0:3]
	v_mfma_f32_16x16x32_bf16 v[0:3], v[182:185], v[110:113], v[86:89]
	v_mfma_f32_16x16x32_bf16 v[12:15], v[216:219], v[248:251], v[0:3]
	v_mfma_f32_16x16x32_bf16 v[0:3], v[122:125], v[144:147], v[90:93]
	v_mfma_f32_16x16x32_bf16 v[4:7], v[182:185], v[144:147], v[94:97]
	v_mfma_f32_16x16x32_bf16 v[0:3], v[126:129], v[204:207], v[0:3]
	v_mfma_f32_16x16x32_bf16 v[4:7], v[216:219], v[204:207], v[4:7]
	v_mfma_f32_16x16x32_bf16 v[66:69], v[220:223], v[16:19], v[98:101]
	v_mfma_f32_16x16x32_bf16 v[16:19], v[240:243], v[16:19], v[34:37]
	v_mfma_f32_16x16x32_bf16 v[94:97], v[244:247], v[20:23], v[16:19]
	v_mfma_f32_16x16x32_bf16 v[16:19], v[220:223], v[62:65], v[38:41]
	v_mfma_f32_16x16x32_bf16 v[90:93], v[224:227], v[20:23], v[66:69]
	v_mfma_f32_16x16x32_bf16 v[66:69], v[224:227], v[106:109], v[16:19]
	v_mfma_f32_16x16x32_bf16 v[16:19], v[240:243], v[62:65], v[42:45]
	v_mfma_f32_16x16x32_bf16 v[70:73], v[244:247], v[106:109], v[16:19]
	v_mfma_f32_16x16x32_bf16 v[16:19], v[220:223], v[110:113], v[46:49]
	v_mfma_f32_16x16x32_bf16 v[42:45], v[224:227], v[248:251], v[16:19]
	v_mfma_f32_16x16x32_bf16 v[16:19], v[240:243], v[110:113], v[186:189]
	v_mfma_f32_16x16x32_bf16 v[46:49], v[244:247], v[248:251], v[16:19]
	v_mfma_f32_16x16x32_bf16 v[16:19], v[220:223], v[144:147], v[190:193]
	v_mfma_f32_16x16x32_bf16 v[20:23], v[240:243], v[144:147], v[58:61]
	v_mfma_f32_16x16x32_bf16 v[16:19], v[224:227], v[204:207], v[16:19]
	v_mfma_f32_16x16x32_bf16 v[20:23], v[244:247], v[204:207], v[20:23]
	s_setprio 0
	s_barrier
	s_mov_b32 m0, s85
	v_lshl_add_u64 v[34:35], v[214:215], 0, s[60:61]
	s_add_u32 s42, s42, 0x100080
	ds_read_b128 v[74:77], v143 offset:49152
	ds_read_b128 v[78:81], v143 offset:50176
	ds_read_b128 v[98:101], v143 offset:51200
	ds_read_b128 v[144:147], v143 offset:52224
	ds_read_b128 v[186:189], v143 offset:53248
	ds_read_b128 v[190:193], v143 offset:54272
	ds_read_b128 v[204:207], v143 offset:55296
	ds_read_b128 v[248:251], v143 offset:56320
	global_load_lds_dwordx4 v[34:35], off
	v_lshl_add_u64 v[34:35], v[252:253], 0, s[60:61]
	s_mov_b32 m0, s82
	s_addc_u32 s43, s43, 0
	global_load_lds_dwordx4 v[34:35], off
	v_lshl_add_u64 v[34:35], s[42:43], 0, v[134:135]
	s_mov_b32 m0, s48
	s_nop 0
	global_load_lds_dwordx4 v[34:35], off
	v_lshl_add_u64 v[34:35], s[42:43], 0, v[130:131]
	s_mov_b32 m0, s49
	s_nop 0
	global_load_lds_dwordx4 v[34:35], off
	v_lshl_add_u64 v[34:35], v[154:155], 0, s[60:61]
	s_mov_b32 m0, s74
	s_nop 0
	global_load_lds_dwordx4 v[34:35], off
	v_lshl_add_u64 v[34:35], v[156:157], 0, s[60:61]
	s_mov_b32 m0, s75
	s_nop 0
	global_load_lds_dwordx4 v[34:35], off
	s_waitcnt vmcnt(8)
	s_waitcnt lgkmcnt(0)
	s_barrier
	s_setprio 1
	v_mfma_f32_16x16x32_bf16 v[34:37], v[122:125], v[74:77], v[148:151]
	v_mfma_f32_16x16x32_bf16 v[106:109], v[126:129], v[78:81], v[34:37]
	v_mfma_f32_16x16x32_bf16 v[34:37], v[182:185], v[74:77], v[158:161]
	v_mfma_f32_16x16x32_bf16 v[110:113], v[216:219], v[78:81], v[34:37]
	v_mfma_f32_16x16x32_bf16 v[34:37], v[122:125], v[98:101], v[162:165]
	v_mfma_f32_16x16x32_bf16 v[82:85], v[126:129], v[144:147], v[34:37]
	v_mfma_f32_16x16x32_bf16 v[34:37], v[182:185], v[98:101], v[166:169]
	v_mfma_f32_16x16x32_bf16 v[86:89], v[216:219], v[144:147], v[34:37]
	v_mfma_f32_16x16x32_bf16 v[34:37], v[122:125], v[186:189], v[170:173]
	v_mfma_f32_16x16x32_bf16 v[58:61], v[126:129], v[190:193], v[34:37]
	v_mfma_f32_16x16x32_bf16 v[34:37], v[182:185], v[186:189], v[174:177]
	v_mfma_f32_16x16x32_bf16 v[62:65], v[216:219], v[190:193], v[34:37]
	v_mfma_f32_16x16x32_bf16 v[34:37], v[122:125], v[204:207], v[228:231]
	v_mfma_f32_16x16x32_bf16 v[38:41], v[182:185], v[204:207], v[114:117]
	v_mfma_f32_16x16x32_bf16 v[34:37], v[126:129], v[248:251], v[34:37]
	v_mfma_f32_16x16x32_bf16 v[38:41], v[216:219], v[248:251], v[38:41]
	v_mfma_f32_16x16x32_bf16 v[114:117], v[220:223], v[74:77], v[118:121]
	v_mfma_f32_16x16x32_bf16 v[74:77], v[240:243], v[74:77], v[232:235]
	v_mfma_f32_16x16x32_bf16 v[126:129], v[244:247], v[78:81], v[74:77]
	v_mfma_f32_16x16x32_bf16 v[74:77], v[220:223], v[98:101], v[236:239]
	v_mfma_f32_16x16x32_bf16 v[122:125], v[224:227], v[78:81], v[114:117]
	v_mfma_f32_16x16x32_bf16 v[114:117], v[224:227], v[144:147], v[74:77]
	v_mfma_f32_16x16x32_bf16 v[74:77], v[240:243], v[98:101], v[194:197]
	v_mfma_f32_16x16x32_bf16 v[118:121], v[244:247], v[144:147], v[74:77]
	v_mfma_f32_16x16x32_bf16 v[74:77], v[220:223], v[186:189], v[198:201]
	v_mfma_f32_16x16x32_bf16 v[98:101], v[224:227], v[190:193], v[74:77]
	v_mfma_f32_16x16x32_bf16 v[74:77], v[240:243], v[186:189], v[102:105]
	v_mfma_f32_16x16x32_bf16 v[102:105], v[244:247], v[190:193], v[74:77]
	v_mfma_f32_16x16x32_bf16 v[74:77], v[220:223], v[204:207], v[208:211]
	v_mfma_f32_16x16x32_bf16 v[78:81], v[240:243], v[204:207], v[178:181]
	v_mfma_f32_16x16x32_bf16 v[74:77], v[224:227], v[248:251], v[74:77]
	v_mfma_f32_16x16x32_bf16 v[78:81], v[244:247], v[248:251], v[78:81]
	s_setprio 0
	s_barrier
	s_andn2_b64 vcc, exec, s[12:13]
	s_cbranch_vccnz .LBB0_2120
	s_barrier

; #define PG8_STAGE(bufoff, gbase, voff) do { _Pragma("unroll") for (int _i = 0; _i < 2; ++_i) \
;         __builtin_amdgcn_global_load_lds((const unsigned*)((const char*)(gbase) + (voff)[_i]), (PG8_LAS unsigned*)(lds + (bufoff) + ldsw + _i * 8192), 16, 0, 0); } while (0)
; #define PG8_LDA(dst, b, h) do { _Pragma("unroll") for (int m = 0; m < 4; ++m) _Pragma("unroll") for (int k = 0; k < 2; ++k) dst[m][k] = *(const PG8_LAS bf16x8*)(lds + PG8_SA(b, h) + aoff + m * 2048 + k * 1024); } while (0)
; #define PG8_LDB(dst, b, h) do { _Pragma("unroll") for (int n = 0; n < 2; ++n) _Pragma("unroll") for (int k = 0; k < 2; ++k) dst[n][k] = *(const PG8_LAS bf16x8*)(lds + PG8_SB(b, h) + boff + n * 2048 + k * 1024); } while (0)
; #define PG8_WAIT_V(n) asm volatile("s_waitcnt vmcnt(" #n ")" ::: "memory")
; #define PG8_WAIT_L(n) asm volatile("s_waitcnt lgkmcnt(" #n ")" ::: "memory")
; #define PG8_BAR __builtin_amdgcn_s_barrier()
; #define PG8_SCHED __builtin_amdgcn_sched_barrier(0)
; template <class Epi, bool ALIGN_EPI = true>
; __device__ __forceinline__ void gemm_phase(PG8_LAS unsigned char* lds, const Gemm g, const StaticOrder& S, const Epi& E) {
;     ...
;             PG8_LDB(B0, 0, 0); PG8_LDB(B1, 0, 1); PG8_SCHED; PG8_LDA(At, 0, 0); PG8_STAGE(PG8_SA(1, 1), a1 + hstepA, voffA);
;             PG8_WAIT_V(8); PG8_WAIT_L(0); PG8_BAR; PG8_MMA(0, 0, At, B0); PG8_MMA(0, 1, At, B1); PG8_BAR; PG8_SCHED;
;             PG8_LDA(At, 0, 1); PG8_STAGE(PG8_SB(0, 0), b2, voffB); PG8_STAGE(PG8_SB(0, 1), b2 + hstepB, voffB); PG8_STAGE(PG8_SA(0, 0), a2, voffA);
;             PG8_WAIT_V(8); PG8_WAIT_L(0); PG8_BAR; PG8_MMA(1, 0, At, B0); PG8_MMA(1, 1, At, B1); PG8_BAR; PG8_SCHED;
.LBB0_2132:
	s_add_u32 s43, s48, 0xfff00080
	s_addc_u32 s50, s49, -1
	s_add_i32 s93, 0, 0x10000
	s_cmp_eq_u32 s41, 60
	s_cselect_b32 s53, s45, s50
	s_cselect_b32 s52, s44, s43
	v_add_u32_e32 v32, s93, v165
	s_cselect_b32 s51, s47, s9
	s_cselect_b32 s50, s46, s7
	s_add_i32 s43, 0, 0x14000
	ds_read_b128 v[142:145], v32
	ds_read_b128 v[148:151], v32 offset:1024
	ds_read_b128 v[158:161], v32 offset:2048
	ds_read_b128 v[168:171], v32 offset:3072
	v_add_u32_e32 v32, s43, v165
	ds_read_b128 v[172:175], v32
	ds_read_b128 v[176:179], v32 offset:1024
	ds_read_b128 v[180:183], v32 offset:2048
	ds_read_b128 v[184:187], v32 offset:3072
	v_lshl_add_u64 v[146:147], s[48:49], 0, v[138:139]
	s_add_i32 m0, s75, 0xc000
	ds_read_b128 v[188:191], v167
	ds_read_b128 v[192:195], v167 offset:1024
	ds_read_b128 v[196:199], v167 offset:2048
	ds_read_b128 v[208:211], v167 offset:3072
	ds_read_b128 v[216:219], v167 offset:4096
	ds_read_b128 v[220:223], v167 offset:5120
	ds_read_b128 v[224:227], v167 offset:6144
	ds_read_b128 v[228:231], v167 offset:7168
	global_load_lds_dwordx4 v[146:147], off
	v_lshl_add_u64 v[146:147], s[48:49], 0, v[140:141]
	s_add_i32 m0, s75, 0xe000
	s_nop 0
	global_load_lds_dwordx4 v[146:147], off
	s_waitcnt vmcnt(8)
	s_waitcnt lgkmcnt(0)
	s_barrier
	s_setprio 1
	v_mfma_f32_16x16x32_bf16 v[126:129], v[142:145], v[188:191], 0
	v_mfma_f32_16x16x32_bf16 v[122:125], v[158:161], v[188:191], 0
	v_mfma_f32_16x16x32_bf16 v[110:113], v[142:145], v[196:199], 0
	v_mfma_f32_16x16x32_bf16 v[106:109], v[158:161], v[196:199], 0
	v_mfma_f32_16x16x32_bf16 v[94:97], v[142:145], v[216:219], 0
	v_mfma_f32_16x16x32_bf16 v[90:93], v[158:161], v[216:219], 0
	v_mfma_f32_16x16x32_bf16 v[78:81], v[142:145], v[224:227], 0
	v_mfma_f32_16x16x32_bf16 v[74:77], v[158:161], v[224:227], 0
	v_mfma_f32_16x16x32_bf16 v[126:129], v[148:151], v[192:195], v[126:129]
	v_mfma_f32_16x16x32_bf16 v[122:125], v[168:171], v[192:195], v[122:125]
	v_mfma_f32_16x16x32_bf16 v[110:113], v[148:151], v[208:211], v[110:113]
	v_mfma_f32_16x16x32_bf16 v[106:109], v[168:171], v[208:211], v[106:109]
	v_mfma_f32_16x16x32_bf16 v[94:97], v[148:151], v[220:223], v[94:97]
	v_mfma_f32_16x16x32_bf16 v[90:93], v[168:171], v[220:223], v[90:93]
	v_mfma_f32_16x16x32_bf16 v[78:81], v[148:151], v[228:231], v[78:81]
	v_mfma_f32_16x16x32_bf16 v[74:77], v[168:171], v[228:231], v[74:77]
	v_mfma_f32_16x16x32_bf16 v[118:121], v[172:175], v[188:191], 0
	v_mfma_f32_16x16x32_bf16 v[114:117], v[180:183], v[188:191], 0
	v_mfma_f32_16x16x32_bf16 v[102:105], v[172:175], v[196:199], 0
	v_mfma_f32_16x16x32_bf16 v[98:101], v[180:183], v[196:199], 0
	v_mfma_f32_16x16x32_bf16 v[86:89], v[172:175], v[216:219], 0
	v_mfma_f32_16x16x32_bf16 v[82:85], v[180:183], v[216:219], 0
	v_mfma_f32_16x16x32_bf16 v[70:73], v[172:175], v[224:227], 0
	v_mfma_f32_16x16x32_bf16 v[66:69], v[180:183], v[224:227], 0
	v_mfma_f32_16x16x32_bf16 v[118:121], v[176:179], v[192:195], v[118:121]
	v_mfma_f32_16x16x32_bf16 v[114:117], v[184:187], v[192:195], v[114:117]
	v_mfma_f32_16x16x32_bf16 v[102:105], v[176:179], v[208:211], v[102:105]
	v_mfma_f32_16x16x32_bf16 v[98:101], v[184:187], v[208:211], v[98:101]
	v_mfma_f32_16x16x32_bf16 v[86:89], v[176:179], v[220:223], v[86:89]
	v_mfma_f32_16x16x32_bf16 v[82:85], v[184:187], v[220:223], v[82:85]
	v_mfma_f32_16x16x32_bf16 v[70:73], v[176:179], v[228:231], v[70:73]
	v_mfma_f32_16x16x32_bf16 v[66:69], v[184:187], v[228:231], v[66:69]
	s_setprio 0
	s_barrier
	s_add_i32 s93, s93, s74
	v_lshl_add_u64 v[146:147], s[50:51], 0, v[132:133]
	s_mov_b32 m0, s93
	ds_read_b128 v[188:191], v167 offset:16384
	ds_read_b128 v[192:195], v167 offset:17408
	ds_read_b128 v[196:199], v167 offset:18432
	ds_read_b128 v[208:211], v167 offset:19456
	ds_read_b128 v[216:219], v167 offset:20480
	ds_read_b128 v[220:223], v167 offset:21504
	ds_read_b128 v[224:227], v167 offset:22528
	ds_read_b128 v[228:231], v167 offset:23552
	global_load_lds_dwordx4 v[146:147], off
	s_add_i32 m0, s93, 0x2000
	s_add_u32 s94, s50, 0x100000
	v_lshl_add_u64 v[162:163], s[50:51], 0, v[136:137]
	s_addc_u32 s95, s51, 0
	s_add_i32 s43, s43, s74
	global_load_lds_dwordx4 v[162:163], off
	v_lshl_add_u64 v[200:201], s[94:95], 0, v[132:133]
	s_mov_b32 m0, s43
	v_lshl_add_u64 v[204:205], s[52:53], 0, v[134:135]
	global_load_lds_dwordx4 v[200:201], off
	v_lshl_add_u64 v[200:201], s[94:95], 0, v[136:137]
	s_add_i32 m0, s43, 0x2000
	s_nop 0
	global_load_lds_dwordx4 v[200:201], off
	v_lshl_add_u64 v[200:201], s[52:53], 0, v[130:131]
	s_mov_b32 m0, s75
	s_nop 0
	global_load_lds_dwordx4 v[200:201], off
	s_mov_b32 m0, s76
	s_nop 0
	global_load_lds_dwordx4 v[204:205], off
	s_waitcnt vmcnt(8)
	s_waitcnt lgkmcnt(0)
	s_barrier
	s_setprio 1
	v_mfma_f32_16x16x32_bf16 v[62:65], v[142:145], v[188:191], 0
	v_mfma_f32_16x16x32_bf16 v[58:61], v[158:161], v[188:191], 0
	v_mfma_f32_16x16x32_bf16 v[46:49], v[142:145], v[196:199], 0
	v_mfma_f32_16x16x32_bf16 v[42:45], v[158:161], v[196:199], 0
	v_mfma_f32_16x16x32_bf16 v[28:31], v[142:145], v[216:219], 0
	v_mfma_f32_16x16x32_bf16 v[24:27], v[158:161], v[216:219], 0
	v_mfma_f32_16x16x32_bf16 v[12:15], v[142:145], v[224:227], 0
	v_mfma_f32_16x16x32_bf16 v[8:11], v[158:161], v[224:227], 0
	v_mfma_f32_16x16x32_bf16 v[62:65], v[148:151], v[192:195], v[62:65]
	v_mfma_f32_16x16x32_bf16 v[58:61], v[168:171], v[192:195], v[58:61]
	v_mfma_f32_16x16x32_bf16 v[46:49], v[148:151], v[208:211], v[46:49]
	v_mfma_f32_16x16x32_bf16 v[42:45], v[168:171], v[208:211], v[42:45]
	v_mfma_f32_16x16x32_bf16 v[28:31], v[148:151], v[220:223], v[28:31]
	v_mfma_f32_16x16x32_bf16 v[24:27], v[168:171], v[220:223], v[24:27]
	v_mfma_f32_16x16x32_bf16 v[12:15], v[148:151], v[228:231], v[12:15]
	v_mfma_f32_16x16x32_bf16 v[8:11], v[168:171], v[228:231], v[8:11]
	v_mfma_f32_16x16x32_bf16 v[54:57], v[172:175], v[188:191], 0
	v_mfma_f32_16x16x32_bf16 v[50:53], v[180:183], v[188:191], 0
	v_mfma_f32_16x16x32_bf16 v[38:41], v[172:175], v[196:199], 0
	v_mfma_f32_16x16x32_bf16 v[34:37], v[180:183], v[196:199], 0
	v_mfma_f32_16x16x32_bf16 v[20:23], v[172:175], v[216:219], 0
	v_mfma_f32_16x16x32_bf16 v[16:19], v[180:183], v[216:219], 0
	v_mfma_f32_16x16x32_bf16 v[4:7], v[172:175], v[224:227], 0
	v_mfma_f32_16x16x32_bf16 v[0:3], v[180:183], v[224:227], 0
	v_mfma_f32_16x16x32_bf16 v[54:57], v[176:179], v[192:195], v[54:57]
	v_mfma_f32_16x16x32_bf16 v[50:53], v[184:187], v[192:195], v[50:53]
	v_mfma_f32_16x16x32_bf16 v[38:41], v[176:179], v[208:211], v[38:41]
	v_mfma_f32_16x16x32_bf16 v[34:37], v[184:187], v[208:211], v[34:37]
	v_mfma_f32_16x16x32_bf16 v[20:23], v[176:179], v[220:223], v[20:23]
	v_mfma_f32_16x16x32_bf16 v[16:19], v[184:187], v[220:223], v[16:19]
	v_mfma_f32_16x16x32_bf16 v[4:7], v[176:179], v[228:231], v[4:7]
	v_mfma_f32_16x16x32_bf16 v[0:3], v[184:187], v[228:231], v[0:3]
	s_setprio 0
	s_barrier
	s_branch .Lp3_2132
; #define PG8_STAGE(bufoff, gbase, voff) do { _Pragma("unroll") for (int _i = 0; _i < 2; ++_i) \
;         __builtin_amdgcn_global_load_lds((const unsigned*)((const char*)(gbase) + (voff)[_i]), (PG8_LAS unsigned*)(lds + (bufoff) + ldsw + _i * 8192), 16, 0, 0); } while (0)
; #define PG8_LDA(dst, b, h) do { _Pragma("unroll") for (int m = 0; m < 4; ++m) _Pragma("unroll") for (int k = 0; k < 2; ++k) dst[m][k] = *(const PG8_LAS bf16x8*)(lds + PG8_SA(b, h) + aoff + m * 2048 + k * 1024); } while (0)
; #define PG8_LDB(dst, b, h) do { _Pragma("unroll") for (int n = 0; n < 2; ++n) _Pragma("unroll") for (int k = 0; k < 2; ++k) dst[n][k] = *(const PG8_LAS bf16x8*)(lds + PG8_SB(b, h) + boff + n * 2048 + k * 1024); } while (0)
; #define PG8_WAIT_V(n) asm volatile("s_waitcnt vmcnt(" #n ")" ::: "memory")
; #define PG8_WAIT_L(n) asm volatile("s_waitcnt lgkmcnt(" #n ")" ::: "memory")
; #define PG8_BAR __builtin_amdgcn_s_barrier()
; #define PG8_SCHED __builtin_amdgcn_sched_barrier(0)
; template <class Epi, bool ALIGN_EPI = true>
; __device__ __forceinline__ void gemm_phase(PG8_LAS unsigned char* lds, const Gemm g, const StaticOrder& S, const Epi& E) {
;     ...
;             PG8_LDB(B0, 0, 0); PG8_LDB(B1, 0, 1); PG8_SCHED; PG8_LDA(At, 0, 0); PG8_STAGE(PG8_SA(1, 1), a1 + hstepA, voffA);
;             PG8_WAIT_V(8); PG8_WAIT_L(0); PG8_BAR; PG8_MMA(0, 0, At, B0); PG8_MMA(0, 1, At, B1); PG8_BAR; PG8_SCHED;
;             PG8_LDA(At, 0, 1); PG8_STAGE(PG8_SB(0, 0), b2, voffB); PG8_STAGE(PG8_SB(0, 1), b2 + hstepB, voffB); PG8_STAGE(PG8_SA(0, 0), a2, voffA);
;             PG8_WAIT_V(8); PG8_WAIT_L(0); PG8_BAR; PG8_MMA(1, 0, At, B0); PG8_MMA(1, 1, At, B1); PG8_BAR; PG8_SCHED;
.Lrot_2132:
	ds_read_b128 v[142:145], v32
	ds_read_b128 v[148:151], v32 offset:1024
	ds_read_b128 v[158:161], v32 offset:2048
	ds_read_b128 v[168:171], v32 offset:3072
	v_add_u32_e32 v32, s43, v165
	ds_read_b128 v[172:175], v32
	ds_read_b128 v[176:179], v32 offset:1024
	ds_read_b128 v[180:183], v32 offset:2048
	ds_read_b128 v[184:187], v32 offset:3072
	v_lshl_add_u64 v[146:147], s[48:49], 0, v[138:139]
	s_add_i32 m0, s75, 0xc000
	ds_read_b128 v[188:191], v167
	ds_read_b128 v[192:195], v167 offset:1024
	ds_read_b128 v[196:199], v167 offset:2048
	ds_read_b128 v[208:211], v167 offset:3072
	ds_read_b128 v[216:219], v167 offset:4096
	ds_read_b128 v[220:223], v167 offset:5120
	ds_read_b128 v[224:227], v167 offset:6144
	ds_read_b128 v[228:231], v167 offset:7168
	global_load_lds_dwordx4 v[146:147], off
	v_lshl_add_u64 v[146:147], s[48:49], 0, v[140:141]
	s_add_i32 m0, s75, 0xe000
	s_nop 0
	global_load_lds_dwordx4 v[146:147], off
	s_waitcnt vmcnt(8)
	s_waitcnt lgkmcnt(0)
	s_barrier
	s_setprio 1
	v_mfma_f32_16x16x32_bf16 v[126:129], v[142:145], v[188:191], v[126:129]
	v_mfma_f32_16x16x32_bf16 v[122:125], v[158:161], v[188:191], v[122:125]
	v_mfma_f32_16x16x32_bf16 v[110:113], v[142:145], v[196:199], v[110:113]
	v_mfma_f32_16x16x32_bf16 v[106:109], v[158:161], v[196:199], v[106:109]
	v_mfma_f32_16x16x32_bf16 v[94:97], v[142:145], v[216:219], v[94:97]
	v_mfma_f32_16x16x32_bf16 v[90:93], v[158:161], v[216:219], v[90:93]
	v_mfma_f32_16x16x32_bf16 v[78:81], v[142:145], v[224:227], v[78:81]
	v_mfma_f32_16x16x32_bf16 v[74:77], v[158:161], v[224:227], v[74:77]
	v_mfma_f32_16x16x32_bf16 v[126:129], v[148:151], v[192:195], v[126:129]
	v_mfma_f32_16x16x32_bf16 v[122:125], v[168:171], v[192:195], v[122:125]
	v_mfma_f32_16x16x32_bf16 v[110:113], v[148:151], v[208:211], v[110:113]
	v_mfma_f32_16x16x32_bf16 v[106:109], v[168:171], v[208:211], v[106:109]
	v_mfma_f32_16x16x32_bf16 v[94:97], v[148:151], v[220:223], v[94:97]
	v_mfma_f32_16x16x32_bf16 v[90:93], v[168:171], v[220:223], v[90:93]
	v_mfma_f32_16x16x32_bf16 v[78:81], v[148:151], v[228:231], v[78:81]
	v_mfma_f32_16x16x32_bf16 v[74:77], v[168:171], v[228:231], v[74:77]
	v_mfma_f32_16x16x32_bf16 v[118:121], v[172:175], v[188:191], v[118:121]
	v_mfma_f32_16x16x32_bf16 v[114:117], v[180:183], v[188:191], v[114:117]
	v_mfma_f32_16x16x32_bf16 v[102:105], v[172:175], v[196:199], v[102:105]
	v_mfma_f32_16x16x32_bf16 v[98:101], v[180:183], v[196:199], v[98:101]
	v_mfma_f32_16x16x32_bf16 v[86:89], v[172:175], v[216:219], v[86:89]
	v_mfma_f32_16x16x32_bf16 v[82:85], v[180:183], v[216:219], v[82:85]
	v_mfma_f32_16x16x32_bf16 v[70:73], v[172:175], v[224:227], v[70:73]
	v_mfma_f32_16x16x32_bf16 v[66:69], v[180:183], v[224:227], v[66:69]
	v_mfma_f32_16x16x32_bf16 v[118:121], v[176:179], v[192:195], v[118:121]
	v_mfma_f32_16x16x32_bf16 v[114:117], v[184:187], v[192:195], v[114:117]
	v_mfma_f32_16x16x32_bf16 v[102:105], v[176:179], v[208:211], v[102:105]
	v_mfma_f32_16x16x32_bf16 v[98:101], v[184:187], v[208:211], v[98:101]
	v_mfma_f32_16x16x32_bf16 v[86:89], v[176:179], v[220:223], v[86:89]
	v_mfma_f32_16x16x32_bf16 v[82:85], v[184:187], v[220:223], v[82:85]
	v_mfma_f32_16x16x32_bf16 v[70:73], v[176:179], v[228:231], v[70:73]
	v_mfma_f32_16x16x32_bf16 v[66:69], v[184:187], v[228:231], v[66:69]
	s_setprio 0
	s_barrier
	s_add_i32 s93, s93, s74
	v_lshl_add_u64 v[146:147], s[50:51], 0, v[132:133]
	s_mov_b32 m0, s93
	ds_read_b128 v[188:191], v167 offset:16384
	ds_read_b128 v[192:195], v167 offset:17408
	ds_read_b128 v[196:199], v167 offset:18432
	ds_read_b128 v[208:211], v167 offset:19456
	ds_read_b128 v[216:219], v167 offset:20480
	ds_read_b128 v[220:223], v167 offset:21504
	ds_read_b128 v[224:227], v167 offset:22528
	ds_read_b128 v[228:231], v167 offset:23552
	global_load_lds_dwordx4 v[146:147], off
	s_add_i32 m0, s93, 0x2000
	s_add_u32 s94, s50, 0x100000
	v_lshl_add_u64 v[162:163], s[50:51], 0, v[136:137]
	s_addc_u32 s95, s51, 0
	s_add_i32 s43, s43, s74
	global_load_lds_dwordx4 v[162:163], off
	v_lshl_add_u64 v[200:201], s[94:95], 0, v[132:133]
	s_mov_b32 m0, s43
	v_lshl_add_u64 v[204:205], s[52:53], 0, v[134:135]
	global_load_lds_dwordx4 v[200:201], off
	v_lshl_add_u64 v[200:201], s[94:95], 0, v[136:137]
	s_add_i32 m0, s43, 0x2000
	s_nop 0
	global_load_lds_dwordx4 v[200:201], off
	v_lshl_add_u64 v[200:201], s[52:53], 0, v[130:131]
	s_mov_b32 m0, s75
	s_nop 0
	global_load_lds_dwordx4 v[200:201], off
	s_mov_b32 m0, s76
	s_nop 0
	global_load_lds_dwordx4 v[204:205], off
	s_waitcnt vmcnt(8)
	s_waitcnt lgkmcnt(0)
	s_barrier
	s_setprio 1
	v_mfma_f32_16x16x32_bf16 v[62:65], v[142:145], v[188:191], v[62:65]
	v_mfma_f32_16x16x32_bf16 v[58:61], v[158:161], v[188:191], v[58:61]
	v_mfma_f32_16x16x32_bf16 v[46:49], v[142:145], v[196:199], v[46:49]
	v_mfma_f32_16x16x32_bf16 v[42:45], v[158:161], v[196:199], v[42:45]
	v_mfma_f32_16x16x32_bf16 v[28:31], v[142:145], v[216:219], v[28:31]
	v_mfma_f32_16x16x32_bf16 v[24:27], v[158:161], v[216:219], v[24:27]
	v_mfma_f32_16x16x32_bf16 v[12:15], v[142:145], v[224:227], v[12:15]
	v_mfma_f32_16x16x32_bf16 v[8:11], v[158:161], v[224:227], v[8:11]
	v_mfma_f32_16x16x32_bf16 v[62:65], v[148:151], v[192:195], v[62:65]
	v_mfma_f32_16x16x32_bf16 v[58:61], v[168:171], v[192:195], v[58:61]
	v_mfma_f32_16x16x32_bf16 v[46:49], v[148:151], v[208:211], v[46:49]
	v_mfma_f32_16x16x32_bf16 v[42:45], v[168:171], v[208:211], v[42:45]
	v_mfma_f32_16x16x32_bf16 v[28:31], v[148:151], v[220:223], v[28:31]
	v_mfma_f32_16x16x32_bf16 v[24:27], v[168:171], v[220:223], v[24:27]
	v_mfma_f32_16x16x32_bf16 v[12:15], v[148:151], v[228:231], v[12:15]
	v_mfma_f32_16x16x32_bf16 v[8:11], v[168:171], v[228:231], v[8:11]
	v_mfma_f32_16x16x32_bf16 v[54:57], v[172:175], v[188:191], v[54:57]
	v_mfma_f32_16x16x32_bf16 v[50:53], v[180:183], v[188:191], v[50:53]
	v_mfma_f32_16x16x32_bf16 v[38:41], v[172:175], v[196:199], v[38:41]
	v_mfma_f32_16x16x32_bf16 v[34:37], v[180:183], v[196:199], v[34:37]
	v_mfma_f32_16x16x32_bf16 v[20:23], v[172:175], v[216:219], v[20:23]
	v_mfma_f32_16x16x32_bf16 v[16:19], v[180:183], v[216:219], v[16:19]
	v_mfma_f32_16x16x32_bf16 v[4:7], v[172:175], v[224:227], v[4:7]
	v_mfma_f32_16x16x32_bf16 v[0:3], v[180:183], v[224:227], v[0:3]
	v_mfma_f32_16x16x32_bf16 v[54:57], v[176:179], v[192:195], v[54:57]
	v_mfma_f32_16x16x32_bf16 v[50:53], v[184:187], v[192:195], v[50:53]
	v_mfma_f32_16x16x32_bf16 v[38:41], v[176:179], v[208:211], v[38:41]
	v_mfma_f32_16x16x32_bf16 v[34:37], v[184:187], v[208:211], v[34:37]
	v_mfma_f32_16x16x32_bf16 v[20:23], v[176:179], v[220:223], v[20:23]
	v_mfma_f32_16x16x32_bf16 v[16:19], v[184:187], v[220:223], v[16:19]
	v_mfma_f32_16x16x32_bf16 v[4:7], v[176:179], v[228:231], v[4:7]
	v_mfma_f32_16x16x32_bf16 v[0:3], v[184:187], v[228:231], v[0:3]
	s_setprio 0
	s_barrier
; #define PG8_STAGE(bufoff, gbase, voff) do { _Pragma("unroll") for (int _i = 0; _i < 2; ++_i) \
;         __builtin_amdgcn_global_load_lds((const unsigned*)((const char*)(gbase) + (voff)[_i]), (PG8_LAS unsigned*)(lds + (bufoff) + ldsw + _i * 8192), 16, 0, 0); } while (0)
; #define PG8_LDA(dst, b, h) do { _Pragma("unroll") for (int m = 0; m < 4; ++m) _Pragma("unroll") for (int k = 0; k < 2; ++k) dst[m][k] = *(const PG8_LAS bf16x8*)(lds + PG8_SA(b, h) + aoff + m * 2048 + k * 1024); } while (0)
; #define PG8_LDB(dst, b, h) do { _Pragma("unroll") for (int n = 0; n < 2; ++n) _Pragma("unroll") for (int k = 0; k < 2; ++k) dst[n][k] = *(const PG8_LAS bf16x8*)(lds + PG8_SB(b, h) + boff + n * 2048 + k * 1024); } while (0)
; #define PG8_WAIT_V(n) asm volatile("s_waitcnt vmcnt(" #n ")" ::: "memory")
; #define PG8_WAIT_L(n) asm volatile("s_waitcnt lgkmcnt(" #n ")" ::: "memory")
; #define PG8_BAR __builtin_amdgcn_s_barrier()
; #define PG8_SCHED __builtin_amdgcn_sched_barrier(0)
; template <class Epi, bool ALIGN_EPI = true>
; __device__ __forceinline__ void gemm_phase(PG8_LAS unsigned char* lds, const Gemm g, const StaticOrder& S, const Epi& E) {
;     ...
;             PG8_LDB(B0, 1, 0); PG8_LDB(B1, 1, 1); PG8_SCHED; PG8_LDA(At, 1, 0); PG8_STAGE(PG8_SA(0, 1), a2 + hstepA, voffA);
;             PG8_WAIT_V(8); PG8_WAIT_L(0); PG8_BAR; PG8_MMA(0, 0, At, B0); PG8_MMA(0, 1, At, B1); PG8_BAR; PG8_SCHED;
.Lp3_2132:
	s_add_i32 s43, 0, 0x18000
	v_add_u32_e32 v32, s43, v165
	s_add_i32 s93, 0, 0x1c000
	ds_read_b128 v[142:145], v32
	ds_read_b128 v[148:151], v32 offset:1024
	ds_read_b128 v[158:161], v32 offset:2048
	ds_read_b128 v[168:171], v32 offset:3072
	v_add_u32_e32 v32, s93, v165
	ds_read_b128 v[172:175], v32
	ds_read_b128 v[176:179], v32 offset:1024
	ds_read_b128 v[180:183], v32 offset:2048
	ds_read_b128 v[184:187], v32 offset:3072
	s_add_u32 s52, s52, 0x100000
	s_addc_u32 s53, s53, 0
	s_mov_b32 m0, s77
	v_lshl_add_u64 v[206:207], s[52:53], 0, v[130:131]
	ds_read_b128 v[188:191], v167 offset:32768
	ds_read_b128 v[192:195], v167 offset:33792
	ds_read_b128 v[196:199], v167 offset:34816
	ds_read_b128 v[208:211], v167 offset:35840
	ds_read_b128 v[216:219], v167 offset:36864
	ds_read_b128 v[220:223], v167 offset:37888
	ds_read_b128 v[224:227], v167 offset:38912
	ds_read_b128 v[228:231], v167 offset:39936
	global_load_lds_dwordx4 v[206:207], off
	v_lshl_add_u64 v[206:207], s[52:53], 0, v[134:135]
	s_mov_b32 m0, s82
	s_nop 0
	global_load_lds_dwordx4 v[206:207], off
	s_waitcnt vmcnt(8)
	s_waitcnt lgkmcnt(0)
	s_barrier
	s_setprio 1
	v_mfma_f32_16x16x32_bf16 v[126:129], v[142:145], v[188:191], v[126:129]
	v_mfma_f32_16x16x32_bf16 v[122:125], v[158:161], v[188:191], v[122:125]
	v_mfma_f32_16x16x32_bf16 v[110:113], v[142:145], v[196:199], v[110:113]
	v_mfma_f32_16x16x32_bf16 v[106:109], v[158:161], v[196:199], v[106:109]
	v_mfma_f32_16x16x32_bf16 v[94:97], v[142:145], v[216:219], v[94:97]
	v_mfma_f32_16x16x32_bf16 v[90:93], v[158:161], v[216:219], v[90:93]
	v_mfma_f32_16x16x32_bf16 v[78:81], v[142:145], v[224:227], v[78:81]
	v_mfma_f32_16x16x32_bf16 v[74:77], v[158:161], v[224:227], v[74:77]
	v_mfma_f32_16x16x32_bf16 v[126:129], v[148:151], v[192:195], v[126:129]
	v_mfma_f32_16x16x32_bf16 v[122:125], v[168:171], v[192:195], v[122:125]
	v_mfma_f32_16x16x32_bf16 v[110:113], v[148:151], v[208:211], v[110:113]
	v_mfma_f32_16x16x32_bf16 v[106:109], v[168:171], v[208:211], v[106:109]
	v_mfma_f32_16x16x32_bf16 v[94:97], v[148:151], v[220:223], v[94:97]
	v_mfma_f32_16x16x32_bf16 v[90:93], v[168:171], v[220:223], v[90:93]
	v_mfma_f32_16x16x32_bf16 v[78:81], v[148:151], v[228:231], v[78:81]
	v_mfma_f32_16x16x32_bf16 v[74:77], v[168:171], v[228:231], v[74:77]
	v_mfma_f32_16x16x32_bf16 v[118:121], v[172:175], v[188:191], v[118:121]
	v_mfma_f32_16x16x32_bf16 v[114:117], v[180:183], v[188:191], v[114:117]
	v_mfma_f32_16x16x32_bf16 v[102:105], v[172:175], v[196:199], v[102:105]
	v_mfma_f32_16x16x32_bf16 v[98:101], v[180:183], v[196:199], v[98:101]
	v_mfma_f32_16x16x32_bf16 v[86:89], v[172:175], v[216:219], v[86:89]
	v_mfma_f32_16x16x32_bf16 v[82:85], v[180:183], v[216:219], v[82:85]
	v_mfma_f32_16x16x32_bf16 v[70:73], v[172:175], v[224:227], v[70:73]
	v_mfma_f32_16x16x32_bf16 v[66:69], v[180:183], v[224:227], v[66:69]
	v_mfma_f32_16x16x32_bf16 v[118:121], v[176:179], v[192:195], v[118:121]
	v_mfma_f32_16x16x32_bf16 v[114:117], v[184:187], v[192:195], v[114:117]
	v_mfma_f32_16x16x32_bf16 v[102:105], v[176:179], v[208:211], v[102:105]
	v_mfma_f32_16x16x32_bf16 v[98:101], v[184:187], v[208:211], v[98:101]
	v_mfma_f32_16x16x32_bf16 v[86:89], v[176:179], v[220:223], v[86:89]
	v_mfma_f32_16x16x32_bf16 v[82:85], v[184:187], v[220:223], v[82:85]
	v_mfma_f32_16x16x32_bf16 v[70:73], v[176:179], v[228:231], v[70:73]
	v_mfma_f32_16x16x32_bf16 v[66:69], v[184:187], v[228:231], v[66:69]
	s_setprio 0
	s_barrier
; #define PG8_STAGE(bufoff, gbase, voff) do { _Pragma("unroll") for (int _i = 0; _i < 2; ++_i) \
;         __builtin_amdgcn_global_load_lds((const unsigned*)((const char*)(gbase) + (voff)[_i]), (PG8_LAS unsigned*)(lds + (bufoff) + ldsw + _i * 8192), 16, 0, 0); } while (0)
; #define PG8_LDA(dst, b, h) do { _Pragma("unroll") for (int m = 0; m < 4; ++m) _Pragma("unroll") for (int k = 0; k < 2; ++k) dst[m][k] = *(const PG8_LAS bf16x8*)(lds + PG8_SA(b, h) + aoff + m * 2048 + k * 1024); } while (0)
; #define PG8_WAIT_V(n) asm volatile("s_waitcnt vmcnt(" #n ")" ::: "memory")
; #define PG8_WAIT_L(n) asm volatile("s_waitcnt lgkmcnt(" #n ")" ::: "memory")
; #define PG8_BAR __builtin_amdgcn_s_barrier()
; #define PG8_SCHED __builtin_amdgcn_sched_barrier(0)
; template <class Epi, bool ALIGN_EPI = true>
; __device__ __forceinline__ void gemm_phase(PG8_LAS unsigned char* lds, const Gemm g, const StaticOrder& S, const Epi& E) {
;     ...
;         for (int t = 0; t < nt; t += 2) {
;             const bool last = (t == nt - 2);
;             const char* a1 = cA + (size_t)(t + 1) * kstep;
;             const char* a2 = last ? nA : cA + (size_t)(t + 2) * kstep; const char* b2 = last ? nB : cB + (size_t)(t + 2) * kstep;
;             const char* a3 = a2 + kstep; const char* b3 = b2 + kstep;
;     ...
;             PG8_LDA(At, 1, 1); PG8_STAGE(PG8_SB(1, 0), b3, voffB); PG8_STAGE(PG8_SB(1, 1), b3 + hstepB, voffB); PG8_STAGE(PG8_SA(1, 0), a3, voffA);
;             PG8_WAIT_V(8); PG8_WAIT_L(0); PG8_BAR; PG8_MMA(1, 0, At, B0); PG8_MMA(1, 1, At, B1); PG8_BAR; PG8_SCHED;
	s_add_i32 s43, s43, s74
	v_lshl_add_u64 v[146:147], v[146:147], 0, s[60:61]
	s_mov_b32 m0, s43
	ds_read_b128 v[188:191], v167 offset:49152
	ds_read_b128 v[192:195], v167 offset:50176
	ds_read_b128 v[196:199], v167 offset:51200
	ds_read_b128 v[208:211], v167 offset:52224
	ds_read_b128 v[216:219], v167 offset:53248
	ds_read_b128 v[220:223], v167 offset:54272
	ds_read_b128 v[224:227], v167 offset:55296
	ds_read_b128 v[228:231], v167 offset:56320
	global_load_lds_dwordx4 v[146:147], off
	s_add_i32 m0, s43, 0x2000
	s_add_u32 s50, s50, 0x100080
	v_lshl_add_u64 v[146:147], v[162:163], 0, s[60:61]
	s_addc_u32 s51, s51, 0
	s_add_i32 s43, s93, s74
	global_load_lds_dwordx4 v[146:147], off
	v_lshl_add_u64 v[146:147], s[50:51], 0, v[132:133]
	s_mov_b32 m0, s43
	s_nop 0
	global_load_lds_dwordx4 v[146:147], off
	v_lshl_add_u64 v[146:147], s[50:51], 0, v[136:137]
	s_add_i32 m0, s43, 0x2000
	s_nop 0
	global_load_lds_dwordx4 v[146:147], off
	v_lshl_add_u64 v[146:147], v[200:201], 0, s[60:61]
	s_mov_b32 m0, s83
	s_nop 0
	global_load_lds_dwordx4 v[146:147], off
	v_lshl_add_u64 v[146:147], v[204:205], 0, s[60:61]
	s_mov_b32 m0, s85
	s_nop 0
	global_load_lds_dwordx4 v[146:147], off
	s_add_i32 s41, s41, 2
	s_add_u32 s48, s48, 0x100
	s_addc_u32 s49, s49, 0
	s_add_u32 s7, s7, 0x100
	s_addc_u32 s9, s9, 0
	s_add_u32 s43, s48, 0xfff00080
	s_addc_u32 s50, s49, -1
	s_add_i32 s93, 0, 0x10000
	s_cmp_eq_u32 s41, 60
	s_cselect_b32 s53, s45, s50
	s_cselect_b32 s52, s44, s43
	v_add_u32_e32 v32, s93, v165
	s_cselect_b32 s51, s47, s9
	s_cselect_b32 s50, s46, s7
	s_add_i32 s43, 0, 0x14000
	s_cmp_gt_u32 s41, 61
	s_waitcnt vmcnt(8)
	s_waitcnt lgkmcnt(0)
	s_barrier
	s_setprio 1
	v_mfma_f32_16x16x32_bf16 v[62:65], v[142:145], v[188:191], v[62:65]
	v_mfma_f32_16x16x32_bf16 v[58:61], v[158:161], v[188:191], v[58:61]
	v_mfma_f32_16x16x32_bf16 v[46:49], v[142:145], v[196:199], v[46:49]
	v_mfma_f32_16x16x32_bf16 v[42:45], v[158:161], v[196:199], v[42:45]
	v_mfma_f32_16x16x32_bf16 v[28:31], v[142:145], v[216:219], v[28:31]
	v_mfma_f32_16x16x32_bf16 v[24:27], v[158:161], v[216:219], v[24:27]
	v_mfma_f32_16x16x32_bf16 v[12:15], v[142:145], v[224:227], v[12:15]
	v_mfma_f32_16x16x32_bf16 v[8:11], v[158:161], v[224:227], v[8:11]
	v_mfma_f32_16x16x32_bf16 v[62:65], v[148:151], v[192:195], v[62:65]
	v_mfma_f32_16x16x32_bf16 v[58:61], v[168:171], v[192:195], v[58:61]
	v_mfma_f32_16x16x32_bf16 v[46:49], v[148:151], v[208:211], v[46:49]
	v_mfma_f32_16x16x32_bf16 v[42:45], v[168:171], v[208:211], v[42:45]
	v_mfma_f32_16x16x32_bf16 v[28:31], v[148:151], v[220:223], v[28:31]
	v_mfma_f32_16x16x32_bf16 v[24:27], v[168:171], v[220:223], v[24:27]
	v_mfma_f32_16x16x32_bf16 v[12:15], v[148:151], v[228:231], v[12:15]
	v_mfma_f32_16x16x32_bf16 v[8:11], v[168:171], v[228:231], v[8:11]
	v_mfma_f32_16x16x32_bf16 v[54:57], v[172:175], v[188:191], v[54:57]
	v_mfma_f32_16x16x32_bf16 v[50:53], v[180:183], v[188:191], v[50:53]
	v_mfma_f32_16x16x32_bf16 v[38:41], v[172:175], v[196:199], v[38:41]
	v_mfma_f32_16x16x32_bf16 v[34:37], v[180:183], v[196:199], v[34:37]
	v_mfma_f32_16x16x32_bf16 v[20:23], v[172:175], v[216:219], v[20:23]
	v_mfma_f32_16x16x32_bf16 v[16:19], v[180:183], v[216:219], v[16:19]
	v_mfma_f32_16x16x32_bf16 v[4:7], v[172:175], v[224:227], v[4:7]
	v_mfma_f32_16x16x32_bf16 v[0:3], v[180:183], v[224:227], v[0:3]
	v_mfma_f32_16x16x32_bf16 v[54:57], v[176:179], v[192:195], v[54:57]
	v_mfma_f32_16x16x32_bf16 v[50:53], v[184:187], v[192:195], v[50:53]
	v_mfma_f32_16x16x32_bf16 v[38:41], v[176:179], v[208:211], v[38:41]
	v_mfma_f32_16x16x32_bf16 v[34:37], v[184:187], v[208:211], v[34:37]
	v_mfma_f32_16x16x32_bf16 v[20:23], v[176:179], v[220:223], v[20:23]
	v_mfma_f32_16x16x32_bf16 v[16:19], v[184:187], v[220:223], v[16:19]
	v_mfma_f32_16x16x32_bf16 v[4:7], v[176:179], v[228:231], v[4:7]
	v_mfma_f32_16x16x32_bf16 v[0:3], v[184:187], v[228:231], v[0:3]
	s_setprio 0
	s_barrier
	s_cbranch_scc0 .Lrot_2132
	s_and_b64 vcc, exec, s[38:39]
	s_cbranch_vccz .LBB0_2135
	s_barrier
